# scan: double-buffered decay vector (D) with 2KB extra static LDS; glaprep: raw Q/K tiles staged in LDS by 16B loads, per-element u16 global loads replaced by ds_read_u16
# speedup vs baseline: 1.0120x; 1.0029x over previous
; DI bf16_t f2bf(float f) { unsigned u = __builtin_bit_cast(unsigned, f); return (bf16_t)((u + 0x7fffu + ((u >> 16) & 1u)) >> 16); }
; DI float logsigmoidf_(float x) { return fminf(x, 0.f) - __logf(1.0f + __expf(-fabsf(x))); }
; __device__ void phase_glaprep(const Params& p, unsigned char* shm) {
;     ...
;         const int dir = unit & 1, h = (unit >> 1) & 3, gch = unit >> 3, r0 = gch * 64;
; #pragma unroll
;         for (int it = 0; it < 2; ++it) { const int x = tid + 512 * it; gls[x] = GL[(size_t)(r0 + (x >> 4)) * 32 + dir * 16 + (x & 15)]; }
;         float w[16];
; #pragma unroll
;         for (int r = 0; r < 16; ++r) w[r] = Wg2[(size_t)(dir * 16 + r) * KD + h * 256 + d];
;         const float bias = bg[dir * KD + h * 256 + d];
;         __syncthreads();
;         float g[32]; float tot = 0.f;
; #pragma unroll
;         for (int ii = 0; ii < 32; ++ii) { const f32x4* gr = (const f32x4*)(gls + (half * 32 + ii) * 16); float x = bias;
; #pragma unroll
;             for (int r4 = 0; r4 < 4; ++r4) { const f32x4 gv = gr[r4]; x += gv[0] * w[4 * r4] + gv[1] * w[4 * r4 + 1] + gv[2] * w[4 * r4 + 2] + gv[3] * w[4 * r4 + 3]; }
;             g[ii] = logsigmoidf_(x) * 0.0625f; tot += g[ii]; }
;         if (half == 0) { tots[d] = tot; tots[512 + d] = g[31]; } else { tots[256 + d] = tot; tots[768 + d] = g[0]; }
;         __syncthreads();
;         const float tot0 = tots[d], tot1 = tots[256 + d];
;         float Gmid, Glast = tot0 + tot1;
;         if (dir == 0) { Gmid = tot0 + tots[768 + d]; float a = half ? tot0 : 0.f;
; #pragma unroll
;             for (int ii = 0; ii < 32; ++ii) { a += g[ii]; g[ii] = a; } }
;         else { Gmid = tots[512 + d] + tot1; float a = half ? 0.f : tot1;
; #pragma unroll
;     ...
;         unsigned kt[16];
;         const float e1d = __expf(Gmid), e2d = __expf(Glast - Gmid);
; #pragma unroll
;         for (int ii = 0; ii < 32; ii += 2) {
;             float kh[2];
; #pragma unroll
;             for (int e = 0; e < 2; ++e) { const int i = half * 32 + ii + e; const float E = __expf(g[ii + e] - Gmid), Ei = __builtin_amdgcn_rcpf(E);
;                 const size_t gi = (size_t)(r0 + i) * KD + h * 256 + d;
;                 const float qv = bf2f(Q[gi]) * E, kv = bf2f(Kx[gi]) * Ei; kh[e] = kv * e2d;
;                 Qs[i * 264 + d] = f2bf(qv); Ks[i * 264 + d] = f2bf(kv); Qh[i * 264 + d] = f2bf(qv * e1d); }
.LBB0_575:
	s_ashr_i32 s81, s56, 3
	s_and_b32 s58, s56, 1
	s_lshl_b32 s57, s81, 6
	s_lshl_b32 s54, s58, 6
	v_or_b32_e32 v2, s57, v49
	v_add_u32_e32 v4, s57, v57
	v_lshl_add_u64 v[0:1], v[14:15], 0, s[54:55]
	v_ashrrev_i32_e32 v3, 31, v2
	v_ashrrev_i32_e32 v5, 31, v4
	s_bfe_u32 s54, s56, 0x20001
	v_lshlrev_b64 v[2:3], 7, v[2:3]
	v_lshlrev_b64 v[4:5], 7, v[4:5]
	s_lshl_b32 s0, s58, 14
	s_lshl_b32 s60, s54, 8
	v_lshl_add_u64 v[2:3], v[0:1], 0, v[2:3]
	v_lshl_add_u64 v[0:1], v[0:1], 0, v[4:5]
	s_or_b32 s0, s60, s0
	global_load_dword v172, v[2:3], off
	global_load_dword v173, v[0:1], off
	v_or_b32_e32 v0, s0, v48
	v_lshlrev_b32_e32 v12, 2, v0
	v_lshl_add_u64 v[168:169], s[38:39], 0, v[12:13]
	v_add_co_u32_e32 v0, vcc, s66, v168
	s_lshl_b32 s0, s58, 10
	s_nop 0
	v_addc_co_u32_e32 v1, vcc, 0, v169, vcc
	v_add_co_u32_e32 v2, vcc, s65, v168
	s_or_b32 s0, s60, s0
	s_nop 0
	v_addc_co_u32_e32 v3, vcc, 0, v169, vcc
	v_add_co_u32_e32 v4, vcc, s67, v168
	s_nop 1
	v_addc_co_u32_e32 v5, vcc, 0, v169, vcc
	v_add_co_u32_e32 v38, vcc, s68, v168
	s_nop 1
	v_addc_co_u32_e32 v39, vcc, 0, v169, vcc
	v_add_co_u32_e32 v40, vcc, s69, v168
	global_load_dword v7, v12, s[38:39]
	global_load_dword v11, v[0:1], off offset:-4096
	global_load_dword v8, v[0:1], off
	global_load_dword v9, v[2:3], off offset:-4096
	global_load_dword v6, v[2:3], off
	global_load_dword v10, v[4:5], off offset:-4096
	s_nop 0
	global_load_dword v3, v[4:5], off
	s_nop 0
	global_load_dword v5, v[38:39], off offset:-4096
	v_addc_co_u32_e32 v41, vcc, 0, v169, vcc
	global_load_dword v0, v[38:39], off
	global_load_dword v2, v[40:41], off offset:-4096
	global_load_dword v1, v[40:41], off
	v_add_co_u32_e32 v38, vcc, s70, v168
	v_or_b32_e32 v4, s0, v48
	s_nop 0
	v_addc_co_u32_e32 v39, vcc, 0, v169, vcc
	v_add_co_u32_e32 v170, vcc, s71, v168
	v_lshlrev_b32_e32 v4, 2, v4
	s_nop 0
	v_addc_co_u32_e32 v171, vcc, 0, v169, vcc
	global_load_dword v167, v4, s[40:41]
	global_load_dword v40, v[38:39], off offset:-4096
	global_load_dword v12, v[38:39], off
	global_load_dword v41, v[170:171], off offset:-4096
	s_nop 0
	global_load_dword v38, v[170:171], off
	v_lshrrev_b32_e32 v232, 5, v136
	v_and_b32_e32 v233, 31, v136
	v_lshlrev_b32_e32 v233, 4, v233
	v_add_u32_e32 v234, s57, v232
	v_lshlrev_b32_e32 v234, 11, v234
	s_lshl_b32 s98, s60, 1
	v_add3_u32 v234, v234, v233, s98
	v_mov_b32_e32 v235, 0
	v_lshl_add_u64 v[236:237], s[44:45], 0, v[234:235]
	v_lshl_add_u64 v[238:239], s[52:53], 0, v[234:235]
	s_mov_b32 s100, 0x8000
	s_mov_b32 s101, 0
	s_movk_i32 s99, 0x210
	v_mad_u32_u24 v240, v232, s99, v233
	v_add_u32_e32 v241, 0x8400, v240
	global_load_dwordx4 v[200:203], v[236:237], off
	global_load_dwordx4 v[216:219], v[238:239], off
	v_lshl_add_u64 v[236:237], v[236:237], 0, s[100:101]
	v_lshl_add_u64 v[238:239], v[238:239], 0, s[100:101]
	global_load_dwordx4 v[204:207], v[236:237], off
	global_load_dwordx4 v[220:223], v[238:239], off
	v_lshl_add_u64 v[236:237], v[236:237], 0, s[100:101]
	v_lshl_add_u64 v[238:239], v[238:239], 0, s[100:101]
	global_load_dwordx4 v[208:211], v[236:237], off
	global_load_dwordx4 v[224:227], v[238:239], off
	v_lshl_add_u64 v[236:237], v[236:237], 0, s[100:101]
	v_lshl_add_u64 v[238:239], v[238:239], 0, s[100:101]
	global_load_dwordx4 v[212:215], v[236:237], off
	global_load_dwordx4 v[228:231], v[238:239], off
	v_add_co_u32_e32 v168, vcc, s72, v168
	s_waitcnt vmcnt(0)
	ds_write2st64_b32 v53, v172, v173 offset1:8
	ds_write_b128 v240, v[200:203] offset:8192
	ds_write_b128 v241, v[216:219] offset:8192
	ds_write_b128 v240, v[204:207] offset:16640
	ds_write_b128 v241, v[220:223] offset:16640
	ds_write_b128 v240, v[208:211] offset:25088
	ds_write_b128 v241, v[224:227] offset:25088
	ds_write_b128 v240, v[212:215] offset:33536
	ds_write_b128 v241, v[228:231] offset:33536
	v_addc_co_u32_e32 v169, vcc, 0, v169, vcc
	global_load_dword v39, v[168:169], off
	s_waitcnt lgkmcnt(0)
	s_barrier
	ds_read_b128 v[168:171], v50
	ds_read_b128 v[172:175], v50 offset:16
	ds_read_b128 v[176:179], v50 offset:32
	ds_read_b128 v[180:183], v50 offset:48
	s_waitcnt lgkmcnt(3)
	v_mul_f32_e32 v4, v11, v169
	v_fmac_f32_e32 v4, v7, v168
	v_fmac_f32_e32 v4, v8, v170
	v_fmac_f32_e32 v4, v9, v171
	s_waitcnt lgkmcnt(2)
	v_mul_f32_e32 v169, v10, v173
	v_fmac_f32_e32 v169, v6, v172
	v_fmac_f32_e32 v169, v3, v174
	v_fmac_f32_e32 v169, v5, v175
	s_waitcnt lgkmcnt(1)
	v_mul_f32_e32 v173, v2, v177
	v_fmac_f32_e32 v173, v0, v176
	v_fmac_f32_e32 v173, v1, v178
	v_add_f32_e32 v4, v167, v4
	v_fmac_f32_e32 v173, v40, v179
	v_add_f32_e32 v4, v4, v169
	s_waitcnt lgkmcnt(0)
	v_mul_f32_e32 v168, v41, v181
	v_fmac_f32_e32 v168, v12, v180
	v_fmac_f32_e32 v168, v38, v182
	v_add_f32_e32 v4, v4, v173
	s_waitcnt vmcnt(0)
	v_fmac_f32_e32 v168, v39, v183
	v_add_f32_e32 v4, v4, v168
	v_mul_f32_e64 v168, |v4|, s73
	v_exp_f32_e32 v168, v168
	v_min_f32_e32 v4, 0, v4
	v_add_f32_e32 v168, 1.0, v168
	v_cmp_gt_f32_e32 vcc, s74, v168
	s_nop 1
	v_cndmask_b32_e64 v169, 0, 32, vcc
	v_ldexp_f32 v168, v168, v169
	v_log_f32_e32 v172, v168
	s_nop 0
	v_mul_f32_e32 v168, 0x3f317217, v172
	v_fma_f32 v173, v172, s75, -v168
	ds_read_b128 v[168:171], v50 offset:64
	v_fmac_f32_e32 v173, 0x3377d1cf, v172
	v_fmac_f32_e32 v173, 0x3f317217, v172
	v_cmp_lt_f32_e64 s[24:25], |v172|, s76
	s_nop 1
	v_cndmask_b32_e64 v176, v172, v173, s[24:25]
	ds_read_b128 v[172:175], v50 offset:80
	s_waitcnt lgkmcnt(1)
	v_mul_f32_e32 v169, v11, v169
	v_fmac_f32_e32 v169, v7, v168
	v_fmac_f32_e32 v169, v8, v170
	v_fmac_f32_e32 v169, v9, v171
	v_add_f32_e32 v177, v167, v169
	s_waitcnt lgkmcnt(0)
; DI float logsigmoidf_(float x) { return fminf(x, 0.f) - __logf(1.0f + __expf(-fabsf(x))); }
; __device__ void phase_glaprep(const Params& p, unsigned char* shm) {
;     ...
;         for (int ii = 0; ii < 32; ++ii) { const f32x4* gr = (const f32x4*)(gls + (half * 32 + ii) * 16); float x = bias;
; #pragma unroll
;             for (int r4 = 0; r4 < 4; ++r4) { const f32x4 gv = gr[r4]; x += gv[0] * w[4 * r4] + gv[1] * w[4 * r4 + 1] + gv[2] * w[4 * r4 + 2] + gv[3] * w[4 * r4 + 3]; }
;             g[ii] = logsigmoidf_(x) * 0.0625f; tot += g[ii]; }
	v_mul_f32_e32 v173, v10, v173
	ds_read_b128 v[168:171], v50 offset:96
	v_fmac_f32_e32 v173, v6, v172
	v_fmac_f32_e32 v173, v3, v174
	v_fmac_f32_e32 v173, v5, v175
	v_add_f32_e32 v177, v177, v173
	ds_read_b128 v[172:175], v50 offset:112
	s_waitcnt lgkmcnt(1)
	v_mul_f32_e32 v169, v2, v169
	v_fmac_f32_e32 v169, v0, v168
	v_fmac_f32_e32 v169, v1, v170
	v_fmac_f32_e32 v169, v40, v171
	v_add_f32_e32 v168, v177, v169
	s_waitcnt lgkmcnt(0)
	v_mul_f32_e32 v169, v41, v173
	v_fmac_f32_e32 v169, v12, v172
	v_fmac_f32_e32 v169, v38, v174
	v_fmac_f32_e32 v169, v39, v175
	v_add_f32_e32 v169, v168, v169
	v_mul_f32_e64 v168, |v169|, s73
	v_exp_f32_e32 v168, v168
	v_cndmask_b32_e32 v170, 0, v166, vcc
	v_sub_f32_e32 v170, v176, v170
	v_sub_f32_e32 v170, v4, v170
	v_add_f32_e32 v4, 1.0, v168
	v_cmp_gt_f32_e32 vcc, s74, v4
	v_min_f32_e32 v169, 0, v169
	s_nop 0
	v_cndmask_b32_e64 v168, 0, 32, vcc
	v_ldexp_f32 v4, v4, v168
	v_log_f32_e32 v178, v4
	v_mul_f32_e32 v4, 0x3d800000, v170
	v_fma_f32 v168, v170, s77, 0
	ds_read_b128 v[170:173], v50 offset:128
	v_mul_f32_e32 v174, 0x3f317217, v178
	v_fma_f32 v179, v178, s75, -v174
	ds_read_b128 v[174:177], v50 offset:144
	v_fmac_f32_e32 v179, 0x3377d1cf, v178
	s_waitcnt lgkmcnt(1)
	v_mul_f32_e32 v171, v11, v171
	v_fmac_f32_e32 v171, v7, v170
	v_fmac_f32_e32 v171, v8, v172
	v_fmac_f32_e32 v171, v9, v173
	v_add_f32_e32 v180, v167, v171
	s_waitcnt lgkmcnt(0)
	v_mul_f32_e32 v175, v10, v175
	ds_read_b128 v[170:173], v50 offset:160
	v_fmac_f32_e32 v175, v6, v174
	v_fmac_f32_e32 v175, v3, v176
	v_fmac_f32_e32 v175, v5, v177
	v_add_f32_e32 v180, v180, v175
	ds_read_b128 v[174:177], v50 offset:176
	s_waitcnt lgkmcnt(1)
	v_mul_f32_e32 v171, v2, v171
	v_fmac_f32_e32 v171, v0, v170
	v_fmac_f32_e32 v171, v1, v172
	v_fmac_f32_e32 v171, v40, v173
	v_add_f32_e32 v170, v180, v171
	s_waitcnt lgkmcnt(0)
	v_mul_f32_e32 v171, v41, v175
	v_fmac_f32_e32 v171, v12, v174
	v_fmac_f32_e32 v171, v38, v176
	v_fmac_f32_e32 v171, v39, v177
	v_add_f32_e32 v170, v170, v171
	v_mul_f32_e64 v171, |v170|, s73
	v_exp_f32_e32 v171, v171
	v_fmac_f32_e32 v179, 0x3f317217, v178
	v_cmp_lt_f32_e64 s[24:25], |v178|, s76
	v_cndmask_b32_e32 v173, 0, v166, vcc
	v_add_f32_e32 v171, 1.0, v171
	v_cndmask_b32_e64 v172, v178, v179, s[24:25]
	v_cmp_gt_f32_e32 vcc, s74, v171
	v_sub_f32_e32 v172, v172, v173
	v_sub_f32_e32 v169, v169, v172
	v_cndmask_b32_e64 v173, 0, 32, vcc
	v_ldexp_f32 v171, v171, v173
	v_log_f32_e32 v178, v171
	v_min_f32_e32 v179, 0, v170
	ds_read_b128 v[170:173], v50 offset:192
	v_fmac_f32_e32 v168, 0x3d800000, v169
	v_mul_f32_e32 v174, 0x3f317217, v178
	v_fma_f32 v180, v178, s75, -v174
	ds_read_b128 v[174:177], v50 offset:208
	s_waitcnt lgkmcnt(1)
	v_mul_f32_e32 v171, v11, v171
	v_fmac_f32_e32 v171, v7, v170
	v_fmac_f32_e32 v171, v8, v172
	v_fmac_f32_e32 v171, v9, v173
	v_add_f32_e32 v181, v167, v171
	s_waitcnt lgkmcnt(0)
	v_mul_f32_e32 v175, v10, v175
	ds_read_b128 v[170:173], v50 offset:224
	v_fmac_f32_e32 v175, v6, v174
	v_fmac_f32_e32 v175, v3, v176
	v_fmac_f32_e32 v175, v5, v177
	v_add_f32_e32 v181, v181, v175
	ds_read_b128 v[174:177], v50 offset:240
	s_waitcnt lgkmcnt(1)
	v_mul_f32_e32 v171, v2, v171
	v_fmac_f32_e32 v171, v0, v170
	v_fmac_f32_e32 v171, v1, v172
	v_fmac_f32_e32 v171, v40, v173
	v_add_f32_e32 v170, v181, v171
	s_waitcnt lgkmcnt(0)
	v_mul_f32_e32 v171, v41, v175
	v_fmac_f32_e32 v171, v12, v174
	v_fmac_f32_e32 v171, v38, v176
	v_fmac_f32_e32 v171, v39, v177
	v_add_f32_e32 v171, v170, v171
	v_mul_f32_e64 v170, |v171|, s73
	v_exp_f32_e32 v170, v170
	v_fmac_f32_e32 v180, 0x3377d1cf, v178
	v_fmac_f32_e32 v180, 0x3f317217, v178
	v_cmp_lt_f32_e64 s[24:25], |v178|, s76
	v_add_f32_e32 v170, 1.0, v170
	v_cndmask_b32_e32 v173, 0, v166, vcc
	v_cndmask_b32_e64 v172, v178, v180, s[24:25]
	v_cmp_gt_f32_e32 vcc, s74, v170
	v_sub_f32_e32 v172, v172, v173
	v_min_f32_e32 v171, 0, v171
	v_cndmask_b32_e64 v173, 0, 32, vcc
	v_ldexp_f32 v170, v170, v173
	v_log_f32_e32 v180, v170
	v_sub_f32_e32 v170, v179, v172
	ds_read_b128 v[172:175], v50 offset:256
	v_fmac_f32_e32 v168, 0x3d800000, v170
	v_mul_f32_e32 v176, 0x3f317217, v180
	v_fma_f32 v181, v180, s75, -v176
	ds_read_b128 v[176:179], v50 offset:272
	s_waitcnt lgkmcnt(1)
	v_mul_f32_e32 v173, v11, v173
	v_fmac_f32_e32 v173, v7, v172
	v_fmac_f32_e32 v173, v8, v174
	v_fmac_f32_e32 v173, v9, v175
	v_add_f32_e32 v182, v167, v173
	s_waitcnt lgkmcnt(0)
	v_mul_f32_e32 v177, v10, v177
	ds_read_b128 v[172:175], v50 offset:288
	v_fmac_f32_e32 v177, v6, v176
	v_fmac_f32_e32 v177, v3, v178
	v_fmac_f32_e32 v177, v5, v179
	v_add_f32_e32 v182, v182, v177
	ds_read_b128 v[176:179], v50 offset:304
	s_waitcnt lgkmcnt(1)
	v_mul_f32_e32 v173, v2, v173
	v_fmac_f32_e32 v173, v0, v172
	v_fmac_f32_e32 v173, v1, v174
	v_fmac_f32_e32 v173, v40, v175
	v_add_f32_e32 v172, v182, v173
	s_waitcnt lgkmcnt(0)
	v_mul_f32_e32 v173, v41, v177
	v_fmac_f32_e32 v173, v12, v176
	v_fmac_f32_e32 v173, v38, v178
	v_fmac_f32_e32 v173, v39, v179
	v_add_f32_e32 v172, v172, v173
	v_mul_f32_e64 v173, |v172|, s73
	v_exp_f32_e32 v173, v173
	v_fmac_f32_e32 v181, 0x3377d1cf, v180
	v_fmac_f32_e32 v181, 0x3f317217, v180
	v_cmp_lt_f32_e64 s[24:25], |v180|, s76
	v_add_f32_e32 v173, 1.0, v173
	v_cndmask_b32_e32 v175, 0, v166, vcc
	v_cndmask_b32_e64 v174, v180, v181, s[24:25]
	v_cmp_gt_f32_e32 vcc, s74, v173
	v_sub_f32_e32 v174, v174, v175
	v_sub_f32_e32 v171, v171, v174
	v_cndmask_b32_e64 v175, 0, 32, vcc
	v_ldexp_f32 v173, v173, v175
	v_log_f32_e32 v180, v173
	v_min_f32_e32 v181, 0, v172
	ds_read_b128 v[172:175], v50 offset:320
	v_fmac_f32_e32 v168, 0x3d800000, v171
	v_mul_f32_e32 v176, 0x3f317217, v180
	v_fma_f32 v182, v180, s75, -v176
	ds_read_b128 v[176:179], v50 offset:336
	s_waitcnt lgkmcnt(1)
; DI float logsigmoidf_(float x) { return fminf(x, 0.f) - __logf(1.0f + __expf(-fabsf(x))); }
; __device__ void phase_glaprep(const Params& p, unsigned char* shm) {
;     ...
;         for (int ii = 0; ii < 32; ++ii) { const f32x4* gr = (const f32x4*)(gls + (half * 32 + ii) * 16); float x = bias;
; #pragma unroll
;             for (int r4 = 0; r4 < 4; ++r4) { const f32x4 gv = gr[r4]; x += gv[0] * w[4 * r4] + gv[1] * w[4 * r4 + 1] + gv[2] * w[4 * r4 + 2] + gv[3] * w[4 * r4 + 3]; }
;             g[ii] = logsigmoidf_(x) * 0.0625f; tot += g[ii]; }
	v_mul_f32_e32 v173, v11, v173
	v_fmac_f32_e32 v173, v7, v172
	v_fmac_f32_e32 v173, v8, v174
	v_fmac_f32_e32 v173, v9, v175
	v_add_f32_e32 v183, v167, v173
	s_waitcnt lgkmcnt(0)
	v_mul_f32_e32 v177, v10, v177
	ds_read_b128 v[172:175], v50 offset:352
	v_fmac_f32_e32 v177, v6, v176
	v_fmac_f32_e32 v177, v3, v178
	v_fmac_f32_e32 v177, v5, v179
	v_add_f32_e32 v183, v183, v177
	ds_read_b128 v[176:179], v50 offset:368
	s_waitcnt lgkmcnt(1)
	v_mul_f32_e32 v173, v2, v173
	v_fmac_f32_e32 v173, v0, v172
	v_fmac_f32_e32 v173, v1, v174
	v_fmac_f32_e32 v173, v40, v175
	v_add_f32_e32 v172, v183, v173
	s_waitcnt lgkmcnt(0)
	v_mul_f32_e32 v173, v41, v177
	v_fmac_f32_e32 v173, v12, v176
	v_fmac_f32_e32 v173, v38, v178
	v_fmac_f32_e32 v173, v39, v179
	v_add_f32_e32 v173, v172, v173
	v_mul_f32_e64 v172, |v173|, s73
	v_exp_f32_e32 v172, v172
	v_fmac_f32_e32 v182, 0x3377d1cf, v180
	v_fmac_f32_e32 v182, 0x3f317217, v180
	v_cmp_lt_f32_e64 s[24:25], |v180|, s76
	v_add_f32_e32 v172, 1.0, v172
	v_cndmask_b32_e32 v175, 0, v166, vcc
	v_cndmask_b32_e64 v174, v180, v182, s[24:25]
	v_cmp_gt_f32_e32 vcc, s74, v172
	v_sub_f32_e32 v174, v174, v175
	v_min_f32_e32 v173, 0, v173
	v_cndmask_b32_e64 v175, 0, 32, vcc
	v_ldexp_f32 v172, v172, v175
	v_log_f32_e32 v182, v172
	v_sub_f32_e32 v172, v181, v174
	ds_read_b128 v[174:177], v50 offset:384
	v_fmac_f32_e32 v168, 0x3d800000, v172
	v_mul_f32_e32 v178, 0x3f317217, v182
	v_fma_f32 v183, v182, s75, -v178
	ds_read_b128 v[178:181], v50 offset:400
	s_waitcnt lgkmcnt(1)
	v_mul_f32_e32 v175, v11, v175
	v_fmac_f32_e32 v175, v7, v174
	v_fmac_f32_e32 v175, v8, v176
	v_fmac_f32_e32 v175, v9, v177
	v_add_f32_e32 v184, v167, v175
	s_waitcnt lgkmcnt(0)
	v_mul_f32_e32 v179, v10, v179
	ds_read_b128 v[174:177], v50 offset:416
	v_fmac_f32_e32 v179, v6, v178
	v_fmac_f32_e32 v179, v3, v180
	v_fmac_f32_e32 v179, v5, v181
	v_add_f32_e32 v184, v184, v179
	ds_read_b128 v[178:181], v50 offset:432
	s_waitcnt lgkmcnt(1)
	v_mul_f32_e32 v175, v2, v175
	v_fmac_f32_e32 v175, v0, v174
	v_fmac_f32_e32 v175, v1, v176
	v_fmac_f32_e32 v175, v40, v177
	v_add_f32_e32 v174, v184, v175
	s_waitcnt lgkmcnt(0)
	v_mul_f32_e32 v175, v41, v179
	v_fmac_f32_e32 v175, v12, v178
	v_fmac_f32_e32 v175, v38, v180
	v_fmac_f32_e32 v175, v39, v181
	v_add_f32_e32 v174, v174, v175
	v_mul_f32_e64 v175, |v174|, s73
	v_exp_f32_e32 v175, v175
	v_fmac_f32_e32 v183, 0x3377d1cf, v182
	v_fmac_f32_e32 v183, 0x3f317217, v182
	v_cmp_lt_f32_e64 s[24:25], |v182|, s76
	v_add_f32_e32 v175, 1.0, v175
	v_cndmask_b32_e32 v177, 0, v166, vcc
	v_cndmask_b32_e64 v176, v182, v183, s[24:25]
	v_cmp_gt_f32_e32 vcc, s74, v175
	v_sub_f32_e32 v176, v176, v177
	v_sub_f32_e32 v173, v173, v176
	v_cndmask_b32_e64 v177, 0, 32, vcc
	v_ldexp_f32 v175, v175, v177
	v_log_f32_e32 v182, v175
	v_min_f32_e32 v183, 0, v174
	ds_read_b128 v[174:177], v50 offset:448
	v_fmac_f32_e32 v168, 0x3d800000, v173
	v_mul_f32_e32 v178, 0x3f317217, v182
	v_fma_f32 v184, v182, s75, -v178
	ds_read_b128 v[178:181], v50 offset:464
	s_waitcnt lgkmcnt(1)
	v_mul_f32_e32 v175, v11, v175
	v_fmac_f32_e32 v175, v7, v174
	v_fmac_f32_e32 v175, v8, v176
	v_fmac_f32_e32 v175, v9, v177
	v_add_f32_e32 v185, v167, v175
	s_waitcnt lgkmcnt(0)
	v_mul_f32_e32 v179, v10, v179
	ds_read_b128 v[174:177], v50 offset:480
	v_fmac_f32_e32 v179, v6, v178
	v_fmac_f32_e32 v179, v3, v180
	v_fmac_f32_e32 v179, v5, v181
	v_add_f32_e32 v185, v185, v179
	ds_read_b128 v[178:181], v50 offset:496
	s_waitcnt lgkmcnt(1)
	v_mul_f32_e32 v175, v2, v175
	v_fmac_f32_e32 v175, v0, v174
	v_fmac_f32_e32 v175, v1, v176
	v_fmac_f32_e32 v175, v40, v177
	v_add_f32_e32 v174, v185, v175
	s_waitcnt lgkmcnt(0)
	v_mul_f32_e32 v175, v41, v179
	v_fmac_f32_e32 v175, v12, v178
	v_fmac_f32_e32 v175, v38, v180
	v_fmac_f32_e32 v175, v39, v181
	v_add_f32_e32 v175, v174, v175
	v_mul_f32_e64 v174, |v175|, s73
	v_exp_f32_e32 v174, v174
	v_fmac_f32_e32 v184, 0x3377d1cf, v182
	v_fmac_f32_e32 v184, 0x3f317217, v182
	v_cmp_lt_f32_e64 s[24:25], |v182|, s76
	v_add_f32_e32 v174, 1.0, v174
	v_cndmask_b32_e32 v177, 0, v166, vcc
	v_cndmask_b32_e64 v176, v182, v184, s[24:25]
	v_cmp_gt_f32_e32 vcc, s74, v174
	v_sub_f32_e32 v176, v176, v177
	v_min_f32_e32 v175, 0, v175
	v_cndmask_b32_e64 v177, 0, 32, vcc
	v_ldexp_f32 v174, v174, v177
	v_log_f32_e32 v184, v174
	v_sub_f32_e32 v174, v183, v176
	ds_read_b128 v[176:179], v50 offset:512
	v_fmac_f32_e32 v168, 0x3d800000, v174
	v_mul_f32_e32 v180, 0x3f317217, v184
	v_fma_f32 v185, v184, s75, -v180
	ds_read_b128 v[180:183], v50 offset:528
	s_waitcnt lgkmcnt(1)
	v_mul_f32_e32 v177, v11, v177
	v_fmac_f32_e32 v177, v7, v176
	v_fmac_f32_e32 v177, v8, v178
	v_fmac_f32_e32 v177, v9, v179
	v_add_f32_e32 v186, v167, v177
	s_waitcnt lgkmcnt(0)
	v_mul_f32_e32 v181, v10, v181
	ds_read_b128 v[176:179], v50 offset:544
	v_fmac_f32_e32 v181, v6, v180
	v_fmac_f32_e32 v181, v3, v182
	v_fmac_f32_e32 v181, v5, v183
	v_add_f32_e32 v186, v186, v181
	ds_read_b128 v[180:183], v50 offset:560
	s_waitcnt lgkmcnt(1)
	v_mul_f32_e32 v177, v2, v177
	v_fmac_f32_e32 v177, v0, v176
	v_fmac_f32_e32 v177, v1, v178
	v_fmac_f32_e32 v177, v40, v179
	v_add_f32_e32 v176, v186, v177
	s_waitcnt lgkmcnt(0)
	v_mul_f32_e32 v177, v41, v181
	v_fmac_f32_e32 v177, v12, v180
	v_fmac_f32_e32 v177, v38, v182
	v_fmac_f32_e32 v177, v39, v183
	v_add_f32_e32 v176, v176, v177
	v_mul_f32_e64 v177, |v176|, s73
	v_exp_f32_e32 v177, v177
	v_fmac_f32_e32 v185, 0x3377d1cf, v184
	v_fmac_f32_e32 v185, 0x3f317217, v184
	v_cmp_lt_f32_e64 s[24:25], |v184|, s76
	v_add_f32_e32 v177, 1.0, v177
	v_cndmask_b32_e32 v179, 0, v166, vcc
	v_cndmask_b32_e64 v178, v184, v185, s[24:25]
	v_cmp_gt_f32_e32 vcc, s74, v177
	v_sub_f32_e32 v178, v178, v179
	v_sub_f32_e32 v175, v175, v178
	v_cndmask_b32_e64 v179, 0, 32, vcc
	v_ldexp_f32 v177, v177, v179
	v_log_f32_e32 v184, v177
	v_min_f32_e32 v185, 0, v176
	ds_read_b128 v[176:179], v50 offset:576
	v_fmac_f32_e32 v168, 0x3d800000, v175
	v_mul_f32_e32 v180, 0x3f317217, v184
	v_fma_f32 v186, v184, s75, -v180
	ds_read_b128 v[180:183], v50 offset:592
	s_waitcnt lgkmcnt(1)
; DI float logsigmoidf_(float x) { return fminf(x, 0.f) - __logf(1.0f + __expf(-fabsf(x))); }
; __device__ void phase_glaprep(const Params& p, unsigned char* shm) {
;     ...
;         for (int ii = 0; ii < 32; ++ii) { const f32x4* gr = (const f32x4*)(gls + (half * 32 + ii) * 16); float x = bias;
; #pragma unroll
;             for (int r4 = 0; r4 < 4; ++r4) { const f32x4 gv = gr[r4]; x += gv[0] * w[4 * r4] + gv[1] * w[4 * r4 + 1] + gv[2] * w[4 * r4 + 2] + gv[3] * w[4 * r4 + 3]; }
;             g[ii] = logsigmoidf_(x) * 0.0625f; tot += g[ii]; }
	v_mul_f32_e32 v177, v11, v177
	v_fmac_f32_e32 v177, v7, v176
	v_fmac_f32_e32 v177, v8, v178
	v_fmac_f32_e32 v177, v9, v179
	v_add_f32_e32 v187, v167, v177
	s_waitcnt lgkmcnt(0)
	v_mul_f32_e32 v181, v10, v181
	ds_read_b128 v[176:179], v50 offset:608
	v_fmac_f32_e32 v181, v6, v180
	v_fmac_f32_e32 v181, v3, v182
	v_fmac_f32_e32 v181, v5, v183
	v_add_f32_e32 v187, v187, v181
	ds_read_b128 v[180:183], v50 offset:624
	s_waitcnt lgkmcnt(1)
	v_mul_f32_e32 v177, v2, v177
	v_fmac_f32_e32 v177, v0, v176
	v_fmac_f32_e32 v177, v1, v178
	v_fmac_f32_e32 v177, v40, v179
	v_add_f32_e32 v176, v187, v177
	s_waitcnt lgkmcnt(0)
	v_mul_f32_e32 v177, v41, v181
	v_fmac_f32_e32 v177, v12, v180
	v_fmac_f32_e32 v177, v38, v182
	v_fmac_f32_e32 v177, v39, v183
	v_add_f32_e32 v177, v176, v177
	v_mul_f32_e64 v176, |v177|, s73
	v_exp_f32_e32 v176, v176
	v_fmac_f32_e32 v186, 0x3377d1cf, v184
	v_fmac_f32_e32 v186, 0x3f317217, v184
	v_cmp_lt_f32_e64 s[24:25], |v184|, s76
	v_add_f32_e32 v176, 1.0, v176
	v_cndmask_b32_e32 v179, 0, v166, vcc
	v_cndmask_b32_e64 v178, v184, v186, s[24:25]
	v_cmp_gt_f32_e32 vcc, s74, v176
	v_sub_f32_e32 v178, v178, v179
	v_min_f32_e32 v177, 0, v177
	v_cndmask_b32_e64 v179, 0, 32, vcc
	v_ldexp_f32 v176, v176, v179
	v_log_f32_e32 v186, v176
	v_sub_f32_e32 v176, v185, v178
	ds_read_b128 v[178:181], v50 offset:640
	v_fmac_f32_e32 v168, 0x3d800000, v176
	v_mul_f32_e32 v182, 0x3f317217, v186
	v_fma_f32 v187, v186, s75, -v182
	ds_read_b128 v[182:185], v50 offset:656
	s_waitcnt lgkmcnt(1)
	v_mul_f32_e32 v179, v11, v179
	v_fmac_f32_e32 v179, v7, v178
	v_fmac_f32_e32 v179, v8, v180
	v_fmac_f32_e32 v179, v9, v181
	v_add_f32_e32 v188, v167, v179
	s_waitcnt lgkmcnt(0)
	v_mul_f32_e32 v183, v10, v183
	ds_read_b128 v[178:181], v50 offset:672
	v_fmac_f32_e32 v183, v6, v182
	v_fmac_f32_e32 v183, v3, v184
	v_fmac_f32_e32 v183, v5, v185
	v_add_f32_e32 v188, v188, v183
	ds_read_b128 v[182:185], v50 offset:688
	s_waitcnt lgkmcnt(1)
	v_mul_f32_e32 v179, v2, v179
	v_fmac_f32_e32 v179, v0, v178
	v_fmac_f32_e32 v179, v1, v180
	v_fmac_f32_e32 v179, v40, v181
	v_add_f32_e32 v178, v188, v179
	s_waitcnt lgkmcnt(0)
	v_mul_f32_e32 v179, v41, v183
	v_fmac_f32_e32 v179, v12, v182
	v_fmac_f32_e32 v179, v38, v184
	v_fmac_f32_e32 v179, v39, v185
	v_add_f32_e32 v178, v178, v179
	v_mul_f32_e64 v179, |v178|, s73
	v_exp_f32_e32 v179, v179
	v_fmac_f32_e32 v187, 0x3377d1cf, v186
	v_fmac_f32_e32 v187, 0x3f317217, v186
	v_cmp_lt_f32_e64 s[24:25], |v186|, s76
	v_add_f32_e32 v179, 1.0, v179
	v_cndmask_b32_e32 v181, 0, v166, vcc
	v_cndmask_b32_e64 v180, v186, v187, s[24:25]
	v_cmp_gt_f32_e32 vcc, s74, v179
	v_sub_f32_e32 v180, v180, v181
	v_sub_f32_e32 v177, v177, v180
	v_cndmask_b32_e64 v181, 0, 32, vcc
	v_ldexp_f32 v179, v179, v181
	v_log_f32_e32 v186, v179
	v_min_f32_e32 v187, 0, v178
	ds_read_b128 v[178:181], v50 offset:704
	v_fmac_f32_e32 v168, 0x3d800000, v177
	v_mul_f32_e32 v182, 0x3f317217, v186
	v_fma_f32 v188, v186, s75, -v182
	ds_read_b128 v[182:185], v50 offset:720
	s_waitcnt lgkmcnt(1)
	v_mul_f32_e32 v179, v11, v179
	v_fmac_f32_e32 v179, v7, v178
	v_fmac_f32_e32 v179, v8, v180
	v_fmac_f32_e32 v179, v9, v181
	v_add_f32_e32 v189, v167, v179
	s_waitcnt lgkmcnt(0)
	v_mul_f32_e32 v183, v10, v183
	ds_read_b128 v[178:181], v50 offset:736
	v_fmac_f32_e32 v183, v6, v182
	v_fmac_f32_e32 v183, v3, v184
	v_fmac_f32_e32 v183, v5, v185
	v_add_f32_e32 v189, v189, v183
	ds_read_b128 v[182:185], v50 offset:752
	s_waitcnt lgkmcnt(1)
	v_mul_f32_e32 v179, v2, v179
	v_fmac_f32_e32 v179, v0, v178
	v_fmac_f32_e32 v179, v1, v180
	v_fmac_f32_e32 v179, v40, v181
	v_add_f32_e32 v178, v189, v179
	s_waitcnt lgkmcnt(0)
	v_mul_f32_e32 v179, v41, v183
	v_fmac_f32_e32 v179, v12, v182
	v_fmac_f32_e32 v179, v38, v184
	v_fmac_f32_e32 v179, v39, v185
	v_add_f32_e32 v179, v178, v179
	v_mul_f32_e64 v178, |v179|, s73
	v_exp_f32_e32 v178, v178
	v_fmac_f32_e32 v188, 0x3377d1cf, v186
	v_fmac_f32_e32 v188, 0x3f317217, v186
	v_cmp_lt_f32_e64 s[24:25], |v186|, s76
	v_add_f32_e32 v178, 1.0, v178
	v_cndmask_b32_e32 v181, 0, v166, vcc
	v_cndmask_b32_e64 v180, v186, v188, s[24:25]
	v_cmp_gt_f32_e32 vcc, s74, v178
	v_sub_f32_e32 v180, v180, v181
	v_min_f32_e32 v179, 0, v179
	v_cndmask_b32_e64 v181, 0, 32, vcc
	v_ldexp_f32 v178, v178, v181
	v_log_f32_e32 v188, v178
	v_sub_f32_e32 v178, v187, v180
	ds_read_b128 v[180:183], v50 offset:768
	v_fmac_f32_e32 v168, 0x3d800000, v178
	v_mul_f32_e32 v184, 0x3f317217, v188
	v_fma_f32 v189, v188, s75, -v184
	ds_read_b128 v[184:187], v50 offset:784
	s_waitcnt lgkmcnt(1)
	v_mul_f32_e32 v181, v11, v181
	v_fmac_f32_e32 v181, v7, v180
	v_fmac_f32_e32 v181, v8, v182
	v_fmac_f32_e32 v181, v9, v183
	v_add_f32_e32 v190, v167, v181
	s_waitcnt lgkmcnt(0)
	v_mul_f32_e32 v185, v10, v185
	ds_read_b128 v[180:183], v50 offset:800
	v_fmac_f32_e32 v185, v6, v184
	v_fmac_f32_e32 v185, v3, v186
	v_fmac_f32_e32 v185, v5, v187
	v_add_f32_e32 v190, v190, v185
	ds_read_b128 v[184:187], v50 offset:816
	s_waitcnt lgkmcnt(1)
	v_mul_f32_e32 v181, v2, v181
	v_fmac_f32_e32 v181, v0, v180
	v_fmac_f32_e32 v181, v1, v182
	v_fmac_f32_e32 v181, v40, v183
	v_add_f32_e32 v180, v190, v181
	s_waitcnt lgkmcnt(0)
	v_mul_f32_e32 v181, v41, v185
	v_fmac_f32_e32 v181, v12, v184
	v_fmac_f32_e32 v181, v38, v186
	v_fmac_f32_e32 v181, v39, v187
	v_add_f32_e32 v180, v180, v181
	v_mul_f32_e64 v181, |v180|, s73
	v_exp_f32_e32 v181, v181
	v_fmac_f32_e32 v189, 0x3377d1cf, v188
	v_fmac_f32_e32 v189, 0x3f317217, v188
	v_cmp_lt_f32_e64 s[24:25], |v188|, s76
	v_add_f32_e32 v181, 1.0, v181
	v_cndmask_b32_e32 v183, 0, v166, vcc
	v_cndmask_b32_e64 v182, v188, v189, s[24:25]
	v_cmp_gt_f32_e32 vcc, s74, v181
	v_sub_f32_e32 v182, v182, v183
	v_sub_f32_e32 v179, v179, v182
	v_cndmask_b32_e64 v183, 0, 32, vcc
	v_ldexp_f32 v181, v181, v183
	v_log_f32_e32 v188, v181
	v_min_f32_e32 v189, 0, v180
	ds_read_b128 v[180:183], v50 offset:832
	v_fmac_f32_e32 v168, 0x3d800000, v179
	v_mul_f32_e32 v184, 0x3f317217, v188
	v_fma_f32 v190, v188, s75, -v184
	ds_read_b128 v[184:187], v50 offset:848
	s_waitcnt lgkmcnt(1)
; DI float logsigmoidf_(float x) { return fminf(x, 0.f) - __logf(1.0f + __expf(-fabsf(x))); }
; __device__ void phase_glaprep(const Params& p, unsigned char* shm) {
;     ...
;         for (int ii = 0; ii < 32; ++ii) { const f32x4* gr = (const f32x4*)(gls + (half * 32 + ii) * 16); float x = bias;
; #pragma unroll
;             for (int r4 = 0; r4 < 4; ++r4) { const f32x4 gv = gr[r4]; x += gv[0] * w[4 * r4] + gv[1] * w[4 * r4 + 1] + gv[2] * w[4 * r4 + 2] + gv[3] * w[4 * r4 + 3]; }
;             g[ii] = logsigmoidf_(x) * 0.0625f; tot += g[ii]; }
	v_mul_f32_e32 v181, v11, v181
	v_fmac_f32_e32 v181, v7, v180
	v_fmac_f32_e32 v181, v8, v182
	v_fmac_f32_e32 v181, v9, v183
	v_add_f32_e32 v191, v167, v181
	s_waitcnt lgkmcnt(0)
	v_mul_f32_e32 v185, v10, v185
	ds_read_b128 v[180:183], v50 offset:864
	v_fmac_f32_e32 v185, v6, v184
	v_fmac_f32_e32 v185, v3, v186
	v_fmac_f32_e32 v185, v5, v187
	v_add_f32_e32 v191, v191, v185
	ds_read_b128 v[184:187], v50 offset:880
	s_waitcnt lgkmcnt(1)
	v_mul_f32_e32 v181, v2, v181
	v_fmac_f32_e32 v181, v0, v180
	v_fmac_f32_e32 v181, v1, v182
	v_fmac_f32_e32 v181, v40, v183
	v_add_f32_e32 v180, v191, v181
	s_waitcnt lgkmcnt(0)
	v_mul_f32_e32 v181, v41, v185
	v_fmac_f32_e32 v181, v12, v184
	v_fmac_f32_e32 v181, v38, v186
	v_fmac_f32_e32 v181, v39, v187
	v_add_f32_e32 v181, v180, v181
	v_mul_f32_e64 v180, |v181|, s73
	v_exp_f32_e32 v180, v180
	v_fmac_f32_e32 v190, 0x3377d1cf, v188
	v_fmac_f32_e32 v190, 0x3f317217, v188
	v_cmp_lt_f32_e64 s[24:25], |v188|, s76
	v_add_f32_e32 v180, 1.0, v180
	v_cndmask_b32_e32 v183, 0, v166, vcc
	v_cndmask_b32_e64 v182, v188, v190, s[24:25]
	v_cmp_gt_f32_e32 vcc, s74, v180
	v_sub_f32_e32 v182, v182, v183
	v_min_f32_e32 v181, 0, v181
	v_cndmask_b32_e64 v183, 0, 32, vcc
	v_ldexp_f32 v180, v180, v183
	v_log_f32_e32 v190, v180
	v_sub_f32_e32 v180, v189, v182
	ds_read_b128 v[182:185], v50 offset:896
	v_fmac_f32_e32 v168, 0x3d800000, v180
	v_mul_f32_e32 v186, 0x3f317217, v190
	v_fma_f32 v191, v190, s75, -v186
	ds_read_b128 v[186:189], v50 offset:912
	s_waitcnt lgkmcnt(1)
	v_mul_f32_e32 v183, v11, v183
	v_fmac_f32_e32 v183, v7, v182
	v_fmac_f32_e32 v183, v8, v184
	v_fmac_f32_e32 v183, v9, v185
	v_add_f32_e32 v192, v167, v183
	s_waitcnt lgkmcnt(0)
	v_mul_f32_e32 v187, v10, v187
	ds_read_b128 v[182:185], v50 offset:928
	v_fmac_f32_e32 v187, v6, v186
	v_fmac_f32_e32 v187, v3, v188
	v_fmac_f32_e32 v187, v5, v189
	v_add_f32_e32 v192, v192, v187
	ds_read_b128 v[186:189], v50 offset:944
	s_waitcnt lgkmcnt(1)
	v_mul_f32_e32 v183, v2, v183
	v_fmac_f32_e32 v183, v0, v182
	v_fmac_f32_e32 v183, v1, v184
	v_fmac_f32_e32 v183, v40, v185
	v_add_f32_e32 v182, v192, v183
	s_waitcnt lgkmcnt(0)
	v_mul_f32_e32 v183, v41, v187
	v_fmac_f32_e32 v183, v12, v186
	v_fmac_f32_e32 v183, v38, v188
	v_fmac_f32_e32 v183, v39, v189
	v_add_f32_e32 v182, v182, v183
	v_mul_f32_e64 v183, |v182|, s73
	v_exp_f32_e32 v183, v183
	v_fmac_f32_e32 v191, 0x3377d1cf, v190
	v_fmac_f32_e32 v191, 0x3f317217, v190
	v_cmp_lt_f32_e64 s[24:25], |v190|, s76
	v_add_f32_e32 v183, 1.0, v183
	v_cndmask_b32_e32 v185, 0, v166, vcc
	v_cndmask_b32_e64 v184, v190, v191, s[24:25]
	v_cmp_gt_f32_e32 vcc, s74, v183
	v_sub_f32_e32 v184, v184, v185
	v_sub_f32_e32 v181, v181, v184
	v_cndmask_b32_e64 v185, 0, 32, vcc
	v_ldexp_f32 v183, v183, v185
	v_log_f32_e32 v190, v183
	v_min_f32_e32 v191, 0, v182
	ds_read_b128 v[182:185], v50 offset:960
	v_fmac_f32_e32 v168, 0x3d800000, v181
	v_mul_f32_e32 v186, 0x3f317217, v190
	v_fma_f32 v192, v190, s75, -v186
	ds_read_b128 v[186:189], v50 offset:976
	s_waitcnt lgkmcnt(1)
	v_mul_f32_e32 v183, v11, v183
	v_fmac_f32_e32 v183, v7, v182
	v_fmac_f32_e32 v183, v8, v184
	v_fmac_f32_e32 v183, v9, v185
	v_add_f32_e32 v193, v167, v183
	s_waitcnt lgkmcnt(0)
	v_mul_f32_e32 v187, v10, v187
	ds_read_b128 v[182:185], v50 offset:992
	v_fmac_f32_e32 v187, v6, v186
	v_fmac_f32_e32 v187, v3, v188
	v_fmac_f32_e32 v187, v5, v189
	v_add_f32_e32 v193, v193, v187
	ds_read_b128 v[186:189], v50 offset:1008
	s_waitcnt lgkmcnt(1)
	v_mul_f32_e32 v183, v2, v183
	v_fmac_f32_e32 v183, v0, v182
	v_fmac_f32_e32 v183, v1, v184
	v_fmac_f32_e32 v183, v40, v185
	v_add_f32_e32 v182, v193, v183
	s_waitcnt lgkmcnt(0)
	v_mul_f32_e32 v183, v41, v187
	v_fmac_f32_e32 v183, v12, v186
	v_fmac_f32_e32 v183, v38, v188
	v_fmac_f32_e32 v183, v39, v189
	v_add_f32_e32 v183, v182, v183
	v_mul_f32_e64 v182, |v183|, s73
	v_exp_f32_e32 v182, v182
	v_fmac_f32_e32 v192, 0x3377d1cf, v190
	v_fmac_f32_e32 v192, 0x3f317217, v190
	v_cmp_lt_f32_e64 s[24:25], |v190|, s76
	v_add_f32_e32 v182, 1.0, v182
	v_cndmask_b32_e32 v185, 0, v166, vcc
	v_cndmask_b32_e64 v184, v190, v192, s[24:25]
	v_cmp_gt_f32_e32 vcc, s74, v182
	v_sub_f32_e32 v184, v184, v185
	v_min_f32_e32 v183, 0, v183
	v_cndmask_b32_e64 v185, 0, 32, vcc
	v_ldexp_f32 v182, v182, v185
	v_log_f32_e32 v192, v182
	v_sub_f32_e32 v182, v191, v184
	ds_read_b128 v[184:187], v50 offset:1024
	v_fmac_f32_e32 v168, 0x3d800000, v182
	v_mul_f32_e32 v188, 0x3f317217, v192
	v_fma_f32 v193, v192, s75, -v188
	ds_read_b128 v[188:191], v50 offset:1040
	s_waitcnt lgkmcnt(1)
	v_mul_f32_e32 v185, v11, v185
	v_fmac_f32_e32 v185, v7, v184
	v_fmac_f32_e32 v185, v8, v186
	v_fmac_f32_e32 v185, v9, v187
	v_add_f32_e32 v194, v167, v185
	s_waitcnt lgkmcnt(0)
	v_mul_f32_e32 v189, v10, v189
	ds_read_b128 v[184:187], v50 offset:1056
	v_fmac_f32_e32 v189, v6, v188
	v_fmac_f32_e32 v189, v3, v190
	v_fmac_f32_e32 v189, v5, v191
	v_add_f32_e32 v194, v194, v189
	ds_read_b128 v[188:191], v50 offset:1072
	s_waitcnt lgkmcnt(1)
	v_mul_f32_e32 v185, v2, v185
	v_fmac_f32_e32 v185, v0, v184
	v_fmac_f32_e32 v185, v1, v186
	v_fmac_f32_e32 v185, v40, v187
	v_add_f32_e32 v184, v194, v185
	s_waitcnt lgkmcnt(0)
	v_mul_f32_e32 v185, v41, v189
	v_fmac_f32_e32 v185, v12, v188
	v_fmac_f32_e32 v185, v38, v190
	v_fmac_f32_e32 v185, v39, v191
	v_add_f32_e32 v184, v184, v185
	v_mul_f32_e64 v185, |v184|, s73
	v_exp_f32_e32 v185, v185
	v_fmac_f32_e32 v193, 0x3377d1cf, v192
	v_fmac_f32_e32 v193, 0x3f317217, v192
	v_cmp_lt_f32_e64 s[24:25], |v192|, s76
	v_add_f32_e32 v185, 1.0, v185
	v_cndmask_b32_e32 v187, 0, v166, vcc
	v_cndmask_b32_e64 v186, v192, v193, s[24:25]
	v_cmp_gt_f32_e32 vcc, s74, v185
	v_sub_f32_e32 v186, v186, v187
	v_sub_f32_e32 v183, v183, v186
	v_cndmask_b32_e64 v187, 0, 32, vcc
	v_ldexp_f32 v185, v185, v187
	v_log_f32_e32 v192, v185
	v_min_f32_e32 v193, 0, v184
	ds_read_b128 v[184:187], v50 offset:1088
	v_fmac_f32_e32 v168, 0x3d800000, v183
	v_mul_f32_e32 v188, 0x3f317217, v192
	v_fma_f32 v194, v192, s75, -v188
	ds_read_b128 v[188:191], v50 offset:1104
	s_waitcnt lgkmcnt(1)
; DI float logsigmoidf_(float x) { return fminf(x, 0.f) - __logf(1.0f + __expf(-fabsf(x))); }
; __device__ void phase_glaprep(const Params& p, unsigned char* shm) {
;     ...
;         for (int ii = 0; ii < 32; ++ii) { const f32x4* gr = (const f32x4*)(gls + (half * 32 + ii) * 16); float x = bias;
; #pragma unroll
;             for (int r4 = 0; r4 < 4; ++r4) { const f32x4 gv = gr[r4]; x += gv[0] * w[4 * r4] + gv[1] * w[4 * r4 + 1] + gv[2] * w[4 * r4 + 2] + gv[3] * w[4 * r4 + 3]; }
;             g[ii] = logsigmoidf_(x) * 0.0625f; tot += g[ii]; }
	v_mul_f32_e32 v185, v11, v185
	v_fmac_f32_e32 v185, v7, v184
	v_fmac_f32_e32 v185, v8, v186
	v_fmac_f32_e32 v185, v9, v187
	v_add_f32_e32 v195, v167, v185
	s_waitcnt lgkmcnt(0)
	v_mul_f32_e32 v189, v10, v189
	ds_read_b128 v[184:187], v50 offset:1120
	v_fmac_f32_e32 v189, v6, v188
	v_fmac_f32_e32 v189, v3, v190
	v_fmac_f32_e32 v189, v5, v191
	v_add_f32_e32 v195, v195, v189
	ds_read_b128 v[188:191], v50 offset:1136
	s_waitcnt lgkmcnt(1)
	v_mul_f32_e32 v185, v2, v185
	v_fmac_f32_e32 v185, v0, v184
	v_fmac_f32_e32 v185, v1, v186
	v_fmac_f32_e32 v185, v40, v187
	v_add_f32_e32 v184, v195, v185
	s_waitcnt lgkmcnt(0)
	v_mul_f32_e32 v185, v41, v189
	v_fmac_f32_e32 v185, v12, v188
	v_fmac_f32_e32 v185, v38, v190
	v_fmac_f32_e32 v185, v39, v191
	v_add_f32_e32 v185, v184, v185
	v_mul_f32_e64 v184, |v185|, s73
	v_exp_f32_e32 v184, v184
	v_fmac_f32_e32 v194, 0x3377d1cf, v192
	v_fmac_f32_e32 v194, 0x3f317217, v192
	v_cmp_lt_f32_e64 s[24:25], |v192|, s76
	v_add_f32_e32 v184, 1.0, v184
	v_cndmask_b32_e32 v187, 0, v166, vcc
	v_cndmask_b32_e64 v186, v192, v194, s[24:25]
	v_cmp_gt_f32_e32 vcc, s74, v184
	v_sub_f32_e32 v186, v186, v187
	v_min_f32_e32 v185, 0, v185
	v_cndmask_b32_e64 v187, 0, 32, vcc
	v_ldexp_f32 v184, v184, v187
	v_log_f32_e32 v194, v184
	v_sub_f32_e32 v184, v193, v186
	ds_read_b128 v[186:189], v50 offset:1152
	v_fmac_f32_e32 v168, 0x3d800000, v184
	v_mul_f32_e32 v190, 0x3f317217, v194
	v_fma_f32 v195, v194, s75, -v190
	ds_read_b128 v[190:193], v50 offset:1168
	s_waitcnt lgkmcnt(1)
	v_mul_f32_e32 v187, v11, v187
	v_fmac_f32_e32 v187, v7, v186
	v_fmac_f32_e32 v187, v8, v188
	v_fmac_f32_e32 v187, v9, v189
	v_add_f32_e32 v196, v167, v187
	s_waitcnt lgkmcnt(0)
	v_mul_f32_e32 v191, v10, v191
	ds_read_b128 v[186:189], v50 offset:1184
	v_fmac_f32_e32 v191, v6, v190
	v_fmac_f32_e32 v191, v3, v192
	v_fmac_f32_e32 v191, v5, v193
	v_add_f32_e32 v196, v196, v191
	ds_read_b128 v[190:193], v50 offset:1200
	s_waitcnt lgkmcnt(1)
	v_mul_f32_e32 v187, v2, v187
	v_fmac_f32_e32 v187, v0, v186
	v_fmac_f32_e32 v187, v1, v188
	v_fmac_f32_e32 v187, v40, v189
	v_add_f32_e32 v186, v196, v187
	s_waitcnt lgkmcnt(0)
	v_mul_f32_e32 v187, v41, v191
	v_fmac_f32_e32 v187, v12, v190
	v_fmac_f32_e32 v187, v38, v192
	v_fmac_f32_e32 v187, v39, v193
	v_add_f32_e32 v186, v186, v187
	v_mul_f32_e64 v187, |v186|, s73
	v_exp_f32_e32 v187, v187
	v_fmac_f32_e32 v195, 0x3377d1cf, v194
	v_fmac_f32_e32 v195, 0x3f317217, v194
	v_cmp_lt_f32_e64 s[24:25], |v194|, s76
	v_add_f32_e32 v187, 1.0, v187
	v_cndmask_b32_e32 v189, 0, v166, vcc
	v_cndmask_b32_e64 v188, v194, v195, s[24:25]
	v_cmp_gt_f32_e32 vcc, s74, v187
	v_sub_f32_e32 v188, v188, v189
	v_sub_f32_e32 v185, v185, v188
	v_cndmask_b32_e64 v189, 0, 32, vcc
	v_ldexp_f32 v187, v187, v189
	v_log_f32_e32 v194, v187
	v_min_f32_e32 v195, 0, v186
	ds_read_b128 v[186:189], v50 offset:1216
	v_fmac_f32_e32 v168, 0x3d800000, v185
	v_mul_f32_e32 v190, 0x3f317217, v194
	v_fma_f32 v196, v194, s75, -v190
	ds_read_b128 v[190:193], v50 offset:1232
	s_waitcnt lgkmcnt(1)
	v_mul_f32_e32 v187, v11, v187
	v_fmac_f32_e32 v187, v7, v186
	v_fmac_f32_e32 v187, v8, v188
	v_fmac_f32_e32 v187, v9, v189
	v_add_f32_e32 v197, v167, v187
	s_waitcnt lgkmcnt(0)
	v_mul_f32_e32 v191, v10, v191
	ds_read_b128 v[186:189], v50 offset:1248
	v_fmac_f32_e32 v191, v6, v190
	v_fmac_f32_e32 v191, v3, v192
	v_fmac_f32_e32 v191, v5, v193
	v_add_f32_e32 v197, v197, v191
	ds_read_b128 v[190:193], v50 offset:1264
	s_waitcnt lgkmcnt(1)
	v_mul_f32_e32 v187, v2, v187
	v_fmac_f32_e32 v187, v0, v186
	v_fmac_f32_e32 v187, v1, v188
	v_fmac_f32_e32 v187, v40, v189
	v_add_f32_e32 v186, v197, v187
	s_waitcnt lgkmcnt(0)
	v_mul_f32_e32 v187, v41, v191
	v_fmac_f32_e32 v187, v12, v190
	v_fmac_f32_e32 v187, v38, v192
	v_fmac_f32_e32 v187, v39, v193
	v_add_f32_e32 v187, v186, v187
	v_mul_f32_e64 v186, |v187|, s73
	v_exp_f32_e32 v186, v186
	v_fmac_f32_e32 v196, 0x3377d1cf, v194
	v_fmac_f32_e32 v196, 0x3f317217, v194
	v_cmp_lt_f32_e64 s[24:25], |v194|, s76
	v_add_f32_e32 v186, 1.0, v186
	v_cndmask_b32_e32 v189, 0, v166, vcc
	v_cndmask_b32_e64 v188, v194, v196, s[24:25]
	v_cmp_gt_f32_e32 vcc, s74, v186
	v_sub_f32_e32 v188, v188, v189
	v_min_f32_e32 v187, 0, v187
	v_cndmask_b32_e64 v189, 0, 32, vcc
	v_ldexp_f32 v186, v186, v189
	v_log_f32_e32 v196, v186
	v_sub_f32_e32 v186, v195, v188
	ds_read_b128 v[188:191], v50 offset:1280
	v_fmac_f32_e32 v168, 0x3d800000, v186
	v_mul_f32_e32 v192, 0x3f317217, v196
	v_fma_f32 v197, v196, s75, -v192
	ds_read_b128 v[192:195], v50 offset:1296
	s_waitcnt lgkmcnt(1)
	v_mul_f32_e32 v189, v11, v189
	v_fmac_f32_e32 v189, v7, v188
	v_fmac_f32_e32 v189, v8, v190
	v_fmac_f32_e32 v189, v9, v191
	v_add_f32_e32 v198, v167, v189
	s_waitcnt lgkmcnt(0)
	v_mul_f32_e32 v193, v10, v193
	ds_read_b128 v[188:191], v50 offset:1312
	v_fmac_f32_e32 v193, v6, v192
	v_fmac_f32_e32 v193, v3, v194
	v_fmac_f32_e32 v193, v5, v195
	v_add_f32_e32 v198, v198, v193
	ds_read_b128 v[192:195], v50 offset:1328
	s_waitcnt lgkmcnt(1)
	v_mul_f32_e32 v189, v2, v189
	v_fmac_f32_e32 v189, v0, v188
	v_fmac_f32_e32 v189, v1, v190
	v_fmac_f32_e32 v189, v40, v191
	v_add_f32_e32 v188, v198, v189
	s_waitcnt lgkmcnt(0)
	v_mul_f32_e32 v189, v41, v193
	v_fmac_f32_e32 v189, v12, v192
	v_fmac_f32_e32 v189, v38, v194
	v_fmac_f32_e32 v189, v39, v195
	v_add_f32_e32 v188, v188, v189
	v_mul_f32_e64 v189, |v188|, s73
	v_exp_f32_e32 v189, v189
	v_fmac_f32_e32 v197, 0x3377d1cf, v196
	v_fmac_f32_e32 v197, 0x3f317217, v196
	v_cmp_lt_f32_e64 s[24:25], |v196|, s76
	v_add_f32_e32 v189, 1.0, v189
	v_cndmask_b32_e32 v191, 0, v166, vcc
	v_cndmask_b32_e64 v190, v196, v197, s[24:25]
	v_cmp_gt_f32_e32 vcc, s74, v189
	v_sub_f32_e32 v190, v190, v191
	v_sub_f32_e32 v187, v187, v190
	v_cndmask_b32_e64 v191, 0, 32, vcc
	v_ldexp_f32 v189, v189, v191
	v_log_f32_e32 v196, v189
	v_min_f32_e32 v197, 0, v188
	ds_read_b128 v[188:191], v50 offset:1344
	v_fmac_f32_e32 v168, 0x3d800000, v187
	v_mul_f32_e32 v192, 0x3f317217, v196
	v_fma_f32 v198, v196, s75, -v192
	ds_read_b128 v[192:195], v50 offset:1360
	s_waitcnt lgkmcnt(1)
; DI float logsigmoidf_(float x) { return fminf(x, 0.f) - __logf(1.0f + __expf(-fabsf(x))); }
; __device__ void phase_glaprep(const Params& p, unsigned char* shm) {
;     ...
;         for (int ii = 0; ii < 32; ++ii) { const f32x4* gr = (const f32x4*)(gls + (half * 32 + ii) * 16); float x = bias;
; #pragma unroll
;             for (int r4 = 0; r4 < 4; ++r4) { const f32x4 gv = gr[r4]; x += gv[0] * w[4 * r4] + gv[1] * w[4 * r4 + 1] + gv[2] * w[4 * r4 + 2] + gv[3] * w[4 * r4 + 3]; }
;             g[ii] = logsigmoidf_(x) * 0.0625f; tot += g[ii]; }
	v_mul_f32_e32 v189, v11, v189
	v_fmac_f32_e32 v189, v7, v188
	v_fmac_f32_e32 v189, v8, v190
	v_fmac_f32_e32 v189, v9, v191
	v_add_f32_e32 v199, v167, v189
	s_waitcnt lgkmcnt(0)
	v_mul_f32_e32 v193, v10, v193
	ds_read_b128 v[188:191], v50 offset:1376
	v_fmac_f32_e32 v193, v6, v192
	v_fmac_f32_e32 v193, v3, v194
	v_fmac_f32_e32 v193, v5, v195
	v_add_f32_e32 v199, v199, v193
	ds_read_b128 v[192:195], v50 offset:1392
	s_waitcnt lgkmcnt(1)
	v_mul_f32_e32 v189, v2, v189
	v_fmac_f32_e32 v189, v0, v188
	v_fmac_f32_e32 v189, v1, v190
	v_fmac_f32_e32 v189, v40, v191
	v_add_f32_e32 v188, v199, v189
	s_waitcnt lgkmcnt(0)
	v_mul_f32_e32 v189, v41, v193
	v_fmac_f32_e32 v189, v12, v192
	v_fmac_f32_e32 v189, v38, v194
	v_fmac_f32_e32 v189, v39, v195
	v_add_f32_e32 v189, v188, v189
	v_mul_f32_e64 v188, |v189|, s73
	v_exp_f32_e32 v188, v188
	v_fmac_f32_e32 v198, 0x3377d1cf, v196
	v_fmac_f32_e32 v198, 0x3f317217, v196
	v_cmp_lt_f32_e64 s[24:25], |v196|, s76
	v_add_f32_e32 v188, 1.0, v188
	v_cndmask_b32_e32 v191, 0, v166, vcc
	v_cndmask_b32_e64 v190, v196, v198, s[24:25]
	v_cmp_gt_f32_e32 vcc, s74, v188
	v_sub_f32_e32 v190, v190, v191
	v_min_f32_e32 v189, 0, v189
	v_cndmask_b32_e64 v191, 0, 32, vcc
	v_ldexp_f32 v188, v188, v191
	v_log_f32_e32 v198, v188
	v_sub_f32_e32 v188, v197, v190
	ds_read_b128 v[190:193], v50 offset:1408
	v_fmac_f32_e32 v168, 0x3d800000, v188
	v_mul_f32_e32 v194, 0x3f317217, v198
	v_fma_f32 v199, v198, s75, -v194
	ds_read_b128 v[194:197], v50 offset:1424
	s_waitcnt lgkmcnt(1)
	v_mul_f32_e32 v191, v11, v191
	v_fmac_f32_e32 v191, v7, v190
	v_fmac_f32_e32 v191, v8, v192
	v_fmac_f32_e32 v191, v9, v193
	v_add_f32_e32 v200, v167, v191
	s_waitcnt lgkmcnt(0)
	v_mul_f32_e32 v195, v10, v195
	ds_read_b128 v[190:193], v50 offset:1440
	v_fmac_f32_e32 v195, v6, v194
	v_fmac_f32_e32 v195, v3, v196
	v_fmac_f32_e32 v195, v5, v197
	v_add_f32_e32 v200, v200, v195
	ds_read_b128 v[194:197], v50 offset:1456
	s_waitcnt lgkmcnt(1)
	v_mul_f32_e32 v191, v2, v191
	v_fmac_f32_e32 v191, v0, v190
	v_fmac_f32_e32 v191, v1, v192
	v_fmac_f32_e32 v191, v40, v193
	v_add_f32_e32 v190, v200, v191
	s_waitcnt lgkmcnt(0)
	v_mul_f32_e32 v191, v41, v195
	v_fmac_f32_e32 v191, v12, v194
	v_fmac_f32_e32 v191, v38, v196
	v_fmac_f32_e32 v191, v39, v197
	v_add_f32_e32 v190, v190, v191
	v_mul_f32_e64 v191, |v190|, s73
	v_exp_f32_e32 v191, v191
	v_fmac_f32_e32 v199, 0x3377d1cf, v198
	v_fmac_f32_e32 v199, 0x3f317217, v198
	v_cmp_lt_f32_e64 s[24:25], |v198|, s76
	v_add_f32_e32 v191, 1.0, v191
	v_cndmask_b32_e32 v193, 0, v166, vcc
	v_cndmask_b32_e64 v192, v198, v199, s[24:25]
	v_cmp_gt_f32_e32 vcc, s74, v191
	v_sub_f32_e32 v192, v192, v193
	v_sub_f32_e32 v189, v189, v192
	v_cndmask_b32_e64 v193, 0, 32, vcc
	v_ldexp_f32 v191, v191, v193
	v_log_f32_e32 v198, v191
	v_min_f32_e32 v199, 0, v190
	ds_read_b128 v[190:193], v50 offset:1472
	v_fmac_f32_e32 v168, 0x3d800000, v189
	v_mul_f32_e32 v194, 0x3f317217, v198
	v_fma_f32 v200, v198, s75, -v194
	ds_read_b128 v[194:197], v50 offset:1488
	s_waitcnt lgkmcnt(1)
	v_mul_f32_e32 v191, v11, v191
	v_fmac_f32_e32 v191, v7, v190
	v_fmac_f32_e32 v191, v8, v192
	v_fmac_f32_e32 v191, v9, v193
	v_add_f32_e32 v201, v167, v191
	s_waitcnt lgkmcnt(0)
	v_mul_f32_e32 v195, v10, v195
	ds_read_b128 v[190:193], v50 offset:1504
	v_fmac_f32_e32 v195, v6, v194
	v_fmac_f32_e32 v195, v3, v196
	v_fmac_f32_e32 v195, v5, v197
	v_add_f32_e32 v201, v201, v195
	ds_read_b128 v[194:197], v50 offset:1520
	s_waitcnt lgkmcnt(1)
	v_mul_f32_e32 v191, v2, v191
	v_fmac_f32_e32 v191, v0, v190
	v_fmac_f32_e32 v191, v1, v192
	v_fmac_f32_e32 v191, v40, v193
	v_add_f32_e32 v190, v201, v191
	s_waitcnt lgkmcnt(0)
	v_mul_f32_e32 v191, v41, v195
	v_fmac_f32_e32 v191, v12, v194
	v_fmac_f32_e32 v191, v38, v196
	v_fmac_f32_e32 v191, v39, v197
	v_add_f32_e32 v191, v190, v191
	v_mul_f32_e64 v190, |v191|, s73
	v_exp_f32_e32 v190, v190
	v_fmac_f32_e32 v200, 0x3377d1cf, v198
	v_fmac_f32_e32 v200, 0x3f317217, v198
	v_cmp_lt_f32_e64 s[24:25], |v198|, s76
	v_add_f32_e32 v190, 1.0, v190
	v_cndmask_b32_e32 v193, 0, v166, vcc
	v_cndmask_b32_e64 v192, v198, v200, s[24:25]
	v_cmp_gt_f32_e32 vcc, s74, v190
	v_sub_f32_e32 v192, v192, v193
	v_min_f32_e32 v191, 0, v191
	v_cndmask_b32_e64 v193, 0, 32, vcc
	v_ldexp_f32 v190, v190, v193
	v_log_f32_e32 v200, v190
	v_sub_f32_e32 v190, v199, v192
	ds_read_b128 v[192:195], v50 offset:1536
	v_fmac_f32_e32 v168, 0x3d800000, v190
	v_mul_f32_e32 v196, 0x3f317217, v200
	v_fma_f32 v201, v200, s75, -v196
	ds_read_b128 v[196:199], v50 offset:1552
	s_waitcnt lgkmcnt(1)
	v_mul_f32_e32 v193, v11, v193
	v_fmac_f32_e32 v193, v7, v192
	v_fmac_f32_e32 v193, v8, v194
	v_fmac_f32_e32 v193, v9, v195
	v_add_f32_e32 v202, v167, v193
	s_waitcnt lgkmcnt(0)
	v_mul_f32_e32 v197, v10, v197
	ds_read_b128 v[192:195], v50 offset:1568
	v_fmac_f32_e32 v197, v6, v196
	v_fmac_f32_e32 v197, v3, v198
	v_fmac_f32_e32 v197, v5, v199
	v_add_f32_e32 v202, v202, v197
	ds_read_b128 v[196:199], v50 offset:1584
	s_waitcnt lgkmcnt(1)
	v_mul_f32_e32 v193, v2, v193
	v_fmac_f32_e32 v193, v0, v192
	v_fmac_f32_e32 v193, v1, v194
	v_fmac_f32_e32 v193, v40, v195
	v_add_f32_e32 v192, v202, v193
	s_waitcnt lgkmcnt(0)
	v_mul_f32_e32 v193, v41, v197
	v_fmac_f32_e32 v193, v12, v196
	v_fmac_f32_e32 v193, v38, v198
	v_fmac_f32_e32 v193, v39, v199
	v_add_f32_e32 v192, v192, v193
	v_mul_f32_e64 v193, |v192|, s73
	v_exp_f32_e32 v193, v193
	v_fmac_f32_e32 v201, 0x3377d1cf, v200
	v_fmac_f32_e32 v201, 0x3f317217, v200
	v_cmp_lt_f32_e64 s[24:25], |v200|, s76
	v_add_f32_e32 v193, 1.0, v193
	v_cndmask_b32_e32 v195, 0, v166, vcc
	v_cndmask_b32_e64 v194, v200, v201, s[24:25]
	v_cmp_gt_f32_e32 vcc, s74, v193
	v_sub_f32_e32 v194, v194, v195
	v_sub_f32_e32 v191, v191, v194
	v_cndmask_b32_e64 v195, 0, 32, vcc
	v_ldexp_f32 v193, v193, v195
	v_log_f32_e32 v200, v193
	v_min_f32_e32 v201, 0, v192
	ds_read_b128 v[192:195], v50 offset:1600
	v_fmac_f32_e32 v168, 0x3d800000, v191
	v_mul_f32_e32 v196, 0x3f317217, v200
	v_fma_f32 v202, v200, s75, -v196
	ds_read_b128 v[196:199], v50 offset:1616
	s_waitcnt lgkmcnt(1)
; DI float logsigmoidf_(float x) { return fminf(x, 0.f) - __logf(1.0f + __expf(-fabsf(x))); }
; __device__ void phase_glaprep(const Params& p, unsigned char* shm) {
;     ...
;         for (int ii = 0; ii < 32; ++ii) { const f32x4* gr = (const f32x4*)(gls + (half * 32 + ii) * 16); float x = bias;
; #pragma unroll
;             for (int r4 = 0; r4 < 4; ++r4) { const f32x4 gv = gr[r4]; x += gv[0] * w[4 * r4] + gv[1] * w[4 * r4 + 1] + gv[2] * w[4 * r4 + 2] + gv[3] * w[4 * r4 + 3]; }
;             g[ii] = logsigmoidf_(x) * 0.0625f; tot += g[ii]; }
	v_mul_f32_e32 v193, v11, v193
	v_fmac_f32_e32 v193, v7, v192
	v_fmac_f32_e32 v193, v8, v194
	v_fmac_f32_e32 v193, v9, v195
	v_add_f32_e32 v203, v167, v193
	s_waitcnt lgkmcnt(0)
	v_mul_f32_e32 v197, v10, v197
	ds_read_b128 v[192:195], v50 offset:1632
	v_fmac_f32_e32 v197, v6, v196
	v_fmac_f32_e32 v197, v3, v198
	v_fmac_f32_e32 v197, v5, v199
	v_add_f32_e32 v203, v203, v197
	ds_read_b128 v[196:199], v50 offset:1648
	s_waitcnt lgkmcnt(1)
	v_mul_f32_e32 v193, v2, v193
	v_fmac_f32_e32 v193, v0, v192
	v_fmac_f32_e32 v193, v1, v194
	v_fmac_f32_e32 v193, v40, v195
	v_add_f32_e32 v192, v203, v193
	s_waitcnt lgkmcnt(0)
	v_mul_f32_e32 v193, v41, v197
	v_fmac_f32_e32 v193, v12, v196
	v_fmac_f32_e32 v193, v38, v198
	v_fmac_f32_e32 v193, v39, v199
	v_add_f32_e32 v193, v192, v193
	v_mul_f32_e64 v192, |v193|, s73
	v_exp_f32_e32 v192, v192
	v_fmac_f32_e32 v202, 0x3377d1cf, v200
	v_fmac_f32_e32 v202, 0x3f317217, v200
	v_cmp_lt_f32_e64 s[24:25], |v200|, s76
	v_add_f32_e32 v192, 1.0, v192
	v_cndmask_b32_e32 v195, 0, v166, vcc
	v_cndmask_b32_e64 v194, v200, v202, s[24:25]
	v_cmp_gt_f32_e32 vcc, s74, v192
	v_sub_f32_e32 v194, v194, v195
	v_min_f32_e32 v193, 0, v193
	v_cndmask_b32_e64 v195, 0, 32, vcc
	v_ldexp_f32 v192, v192, v195
	v_log_f32_e32 v202, v192
	v_sub_f32_e32 v192, v201, v194
	ds_read_b128 v[194:197], v50 offset:1664
	v_fmac_f32_e32 v168, 0x3d800000, v192
	v_mul_f32_e32 v198, 0x3f317217, v202
	v_fma_f32 v203, v202, s75, -v198
	ds_read_b128 v[198:201], v50 offset:1680
	s_waitcnt lgkmcnt(1)
	v_mul_f32_e32 v195, v11, v195
	v_fmac_f32_e32 v195, v7, v194
	v_fmac_f32_e32 v195, v8, v196
	v_fmac_f32_e32 v195, v9, v197
	v_add_f32_e32 v204, v167, v195
	s_waitcnt lgkmcnt(0)
	v_mul_f32_e32 v199, v10, v199
	ds_read_b128 v[194:197], v50 offset:1696
	v_fmac_f32_e32 v199, v6, v198
	v_fmac_f32_e32 v199, v3, v200
	v_fmac_f32_e32 v199, v5, v201
	v_add_f32_e32 v204, v204, v199
	ds_read_b128 v[198:201], v50 offset:1712
	s_waitcnt lgkmcnt(1)
	v_mul_f32_e32 v195, v2, v195
	v_fmac_f32_e32 v195, v0, v194
	v_fmac_f32_e32 v195, v1, v196
	v_fmac_f32_e32 v195, v40, v197
	v_add_f32_e32 v194, v204, v195
	s_waitcnt lgkmcnt(0)
	v_mul_f32_e32 v195, v41, v199
	v_fmac_f32_e32 v195, v12, v198
	v_fmac_f32_e32 v195, v38, v200
	v_fmac_f32_e32 v195, v39, v201
	v_add_f32_e32 v194, v194, v195
	v_mul_f32_e64 v195, |v194|, s73
	v_exp_f32_e32 v195, v195
	v_fmac_f32_e32 v203, 0x3377d1cf, v202
	v_fmac_f32_e32 v203, 0x3f317217, v202
	v_cmp_lt_f32_e64 s[24:25], |v202|, s76
	v_add_f32_e32 v195, 1.0, v195
	v_cndmask_b32_e32 v197, 0, v166, vcc
	v_cndmask_b32_e64 v196, v202, v203, s[24:25]
	v_cmp_gt_f32_e32 vcc, s74, v195
	v_sub_f32_e32 v196, v196, v197
	v_sub_f32_e32 v193, v193, v196
	v_cndmask_b32_e64 v197, 0, 32, vcc
	v_ldexp_f32 v195, v195, v197
	v_log_f32_e32 v202, v195
	v_min_f32_e32 v203, 0, v194
	ds_read_b128 v[194:197], v50 offset:1728
	v_fmac_f32_e32 v168, 0x3d800000, v193
	v_mul_f32_e32 v198, 0x3f317217, v202
	v_fma_f32 v204, v202, s75, -v198
	ds_read_b128 v[198:201], v50 offset:1744
	s_waitcnt lgkmcnt(1)
	v_mul_f32_e32 v195, v11, v195
	v_fmac_f32_e32 v195, v7, v194
	v_fmac_f32_e32 v195, v8, v196
	v_fmac_f32_e32 v195, v9, v197
	v_add_f32_e32 v205, v167, v195
	s_waitcnt lgkmcnt(0)
	v_mul_f32_e32 v199, v10, v199
	ds_read_b128 v[194:197], v50 offset:1760
	v_fmac_f32_e32 v199, v6, v198
	v_fmac_f32_e32 v199, v3, v200
	v_fmac_f32_e32 v199, v5, v201
	v_add_f32_e32 v205, v205, v199
	ds_read_b128 v[198:201], v50 offset:1776
	s_waitcnt lgkmcnt(1)
	v_mul_f32_e32 v195, v2, v195
	v_fmac_f32_e32 v195, v0, v194
	v_fmac_f32_e32 v195, v1, v196
	v_fmac_f32_e32 v195, v40, v197
	v_add_f32_e32 v194, v205, v195
	s_waitcnt lgkmcnt(0)
	v_mul_f32_e32 v195, v41, v199
	v_fmac_f32_e32 v195, v12, v198
	v_fmac_f32_e32 v195, v38, v200
	v_fmac_f32_e32 v195, v39, v201
	v_add_f32_e32 v195, v194, v195
	v_mul_f32_e64 v194, |v195|, s73
	v_exp_f32_e32 v194, v194
	v_fmac_f32_e32 v204, 0x3377d1cf, v202
	v_fmac_f32_e32 v204, 0x3f317217, v202
	v_cmp_lt_f32_e64 s[24:25], |v202|, s76
	v_add_f32_e32 v194, 1.0, v194
	v_cndmask_b32_e32 v197, 0, v166, vcc
	v_cndmask_b32_e64 v196, v202, v204, s[24:25]
	v_cmp_gt_f32_e32 vcc, s74, v194
	v_sub_f32_e32 v196, v196, v197
	v_min_f32_e32 v195, 0, v195
	v_cndmask_b32_e64 v197, 0, 32, vcc
	v_ldexp_f32 v194, v194, v197
	v_log_f32_e32 v204, v194
	v_sub_f32_e32 v194, v203, v196
	ds_read_b128 v[196:199], v50 offset:1792
	v_fmac_f32_e32 v168, 0x3d800000, v194
	v_mul_f32_e32 v200, 0x3f317217, v204
	v_fma_f32 v205, v204, s75, -v200
	ds_read_b128 v[200:203], v50 offset:1808
	s_waitcnt lgkmcnt(1)
	v_mul_f32_e32 v197, v11, v197
	v_fmac_f32_e32 v197, v7, v196
	v_fmac_f32_e32 v197, v8, v198
	v_fmac_f32_e32 v197, v9, v199
	v_add_f32_e32 v206, v167, v197
	s_waitcnt lgkmcnt(0)
	v_mul_f32_e32 v201, v10, v201
	ds_read_b128 v[196:199], v50 offset:1824
	v_fmac_f32_e32 v201, v6, v200
	v_fmac_f32_e32 v201, v3, v202
	v_fmac_f32_e32 v201, v5, v203
	v_add_f32_e32 v206, v206, v201
	ds_read_b128 v[200:203], v50 offset:1840
	s_waitcnt lgkmcnt(1)
	v_mul_f32_e32 v197, v2, v197
	v_fmac_f32_e32 v197, v0, v196
	v_fmac_f32_e32 v197, v1, v198
	v_fmac_f32_e32 v197, v40, v199
	v_add_f32_e32 v196, v206, v197
	s_waitcnt lgkmcnt(0)
; DI float logsigmoidf_(float x) { return fminf(x, 0.f) - __logf(1.0f + __expf(-fabsf(x))); }
; __device__ void phase_glaprep(const Params& p, unsigned char* shm) {
;     ...
;         for (int ii = 0; ii < 32; ++ii) { const f32x4* gr = (const f32x4*)(gls + (half * 32 + ii) * 16); float x = bias;
; #pragma unroll
;             for (int r4 = 0; r4 < 4; ++r4) { const f32x4 gv = gr[r4]; x += gv[0] * w[4 * r4] + gv[1] * w[4 * r4 + 1] + gv[2] * w[4 * r4 + 2] + gv[3] * w[4 * r4 + 3]; }
;             g[ii] = logsigmoidf_(x) * 0.0625f; tot += g[ii]; }
;         if (half == 0) { tots[d] = tot; tots[512 + d] = g[31]; } else { tots[256 + d] = tot; tots[768 + d] = g[0]; }
	v_mul_f32_e32 v197, v41, v201
	v_fmac_f32_e32 v197, v12, v200
	v_fmac_f32_e32 v197, v38, v202
	v_fmac_f32_e32 v197, v39, v203
	v_add_f32_e32 v196, v196, v197
	v_mul_f32_e64 v197, |v196|, s73
	v_exp_f32_e32 v197, v197
	v_fmac_f32_e32 v205, 0x3377d1cf, v204
	v_fmac_f32_e32 v205, 0x3f317217, v204
	v_cmp_lt_f32_e64 s[24:25], |v204|, s76
	v_add_f32_e32 v197, 1.0, v197
	v_cndmask_b32_e32 v199, 0, v166, vcc
	v_cndmask_b32_e64 v198, v204, v205, s[24:25]
	v_cmp_gt_f32_e32 vcc, s74, v197
	v_sub_f32_e32 v198, v198, v199
	v_sub_f32_e32 v195, v195, v198
	v_cndmask_b32_e64 v199, 0, 32, vcc
	v_ldexp_f32 v197, v197, v199
	v_log_f32_e32 v204, v197
	v_min_f32_e32 v205, 0, v196
	ds_read_b128 v[196:199], v50 offset:1856
	v_fmac_f32_e32 v168, 0x3d800000, v195
	v_mul_f32_e32 v200, 0x3f317217, v204
	v_fma_f32 v206, v204, s75, -v200
	ds_read_b128 v[200:203], v50 offset:1872
	s_waitcnt lgkmcnt(1)
	v_mul_f32_e32 v197, v11, v197
	v_fmac_f32_e32 v197, v7, v196
	v_fmac_f32_e32 v197, v8, v198
	v_fmac_f32_e32 v197, v9, v199
	v_add_f32_e32 v207, v167, v197
	s_waitcnt lgkmcnt(0)
	v_mul_f32_e32 v201, v10, v201
	ds_read_b128 v[196:199], v50 offset:1888
	v_fmac_f32_e32 v201, v6, v200
	v_fmac_f32_e32 v201, v3, v202
	v_fmac_f32_e32 v201, v5, v203
	v_add_f32_e32 v207, v207, v201
	ds_read_b128 v[200:203], v50 offset:1904
	s_waitcnt lgkmcnt(1)
	v_mul_f32_e32 v197, v2, v197
	v_fmac_f32_e32 v197, v0, v196
	v_fmac_f32_e32 v197, v1, v198
	v_fmac_f32_e32 v197, v40, v199
	v_add_f32_e32 v196, v207, v197
	s_waitcnt lgkmcnt(0)
	v_mul_f32_e32 v197, v41, v201
	v_fmac_f32_e32 v197, v12, v200
	v_fmac_f32_e32 v197, v38, v202
	v_fmac_f32_e32 v197, v39, v203
	v_add_f32_e32 v197, v196, v197
	v_mul_f32_e64 v196, |v197|, s73
	v_exp_f32_e32 v196, v196
	v_fmac_f32_e32 v206, 0x3377d1cf, v204
	v_fmac_f32_e32 v206, 0x3f317217, v204
	v_cmp_lt_f32_e64 s[24:25], |v204|, s76
	v_add_f32_e32 v196, 1.0, v196
	v_cndmask_b32_e32 v199, 0, v166, vcc
	v_cndmask_b32_e64 v198, v204, v206, s[24:25]
	v_cmp_gt_f32_e32 vcc, s74, v196
	v_sub_f32_e32 v198, v198, v199
	v_min_f32_e32 v197, 0, v197
	v_cndmask_b32_e64 v199, 0, 32, vcc
	v_ldexp_f32 v196, v196, v199
	v_log_f32_e32 v206, v196
	v_sub_f32_e32 v196, v205, v198
	ds_read_b128 v[198:201], v50 offset:1920
	v_fmac_f32_e32 v168, 0x3d800000, v196
	v_mul_f32_e32 v202, 0x3f317217, v206
	v_fma_f32 v207, v206, s75, -v202
	ds_read_b128 v[202:205], v50 offset:1936
	s_waitcnt lgkmcnt(1)
	v_mul_f32_e32 v199, v11, v199
	v_fmac_f32_e32 v199, v7, v198
	v_fmac_f32_e32 v199, v8, v200
	v_fmac_f32_e32 v199, v9, v201
	v_add_f32_e32 v208, v167, v199
	s_waitcnt lgkmcnt(0)
	v_mul_f32_e32 v203, v10, v203
	ds_read_b128 v[198:201], v50 offset:1952
	v_fmac_f32_e32 v203, v6, v202
	v_fmac_f32_e32 v203, v3, v204
	v_fmac_f32_e32 v203, v5, v205
	v_add_f32_e32 v208, v208, v203
	ds_read_b128 v[202:205], v50 offset:1968
	s_waitcnt lgkmcnt(1)
	v_mul_f32_e32 v199, v2, v199
	v_fmac_f32_e32 v199, v0, v198
	v_fmac_f32_e32 v199, v1, v200
	v_fmac_f32_e32 v199, v40, v201
	v_add_f32_e32 v198, v208, v199
	s_waitcnt lgkmcnt(0)
	v_mul_f32_e32 v199, v41, v203
	v_fmac_f32_e32 v199, v12, v202
	v_fmac_f32_e32 v199, v38, v204
	v_fmac_f32_e32 v199, v39, v205
	v_add_f32_e32 v198, v198, v199
	v_mul_f32_e64 v199, |v198|, s73
	v_exp_f32_e32 v199, v199
	v_fmac_f32_e32 v207, 0x3377d1cf, v206
	v_fmac_f32_e32 v207, 0x3f317217, v206
	v_cmp_lt_f32_e64 s[24:25], |v206|, s76
	v_add_f32_e32 v199, 1.0, v199
	v_cndmask_b32_e32 v201, 0, v166, vcc
	v_cndmask_b32_e64 v200, v206, v207, s[24:25]
	v_cmp_gt_f32_e32 vcc, s74, v199
	v_sub_f32_e32 v200, v200, v201
	v_sub_f32_e32 v217, v197, v200
	v_cndmask_b32_e64 v201, 0, 32, vcc
	v_ldexp_f32 v199, v199, v201
	v_log_f32_e32 v206, v199
	v_min_f32_e32 v197, 0, v198
	ds_read_b128 v[198:201], v50 offset:1984
	v_fmac_f32_e32 v168, 0x3d800000, v217
	v_mul_f32_e32 v202, 0x3f317217, v206
	v_fma_f32 v207, v206, s75, -v202
	ds_read_b128 v[202:205], v50 offset:2000
	s_waitcnt lgkmcnt(1)
	v_mul_f32_e32 v11, v11, v199
	v_fmac_f32_e32 v11, v7, v198
	v_fmac_f32_e32 v11, v8, v200
	v_fmac_f32_e32 v11, v9, v201
	s_waitcnt lgkmcnt(0)
	v_mul_f32_e32 v10, v10, v203
	v_fmac_f32_e32 v10, v6, v202
	ds_read_b128 v[6:9], v50 offset:2016
	ds_read_b128 v[198:201], v50 offset:2032
	v_fmac_f32_e32 v10, v3, v204
	v_add_f32_e32 v11, v167, v11
	v_fmac_f32_e32 v10, v5, v205
	s_waitcnt lgkmcnt(1)
	v_mul_f32_e32 v2, v2, v7
	v_fmac_f32_e32 v2, v0, v6
	v_fmac_f32_e32 v2, v1, v8
	s_waitcnt lgkmcnt(0)
	v_mul_f32_e32 v1, v41, v199
	v_fmac_f32_e32 v1, v12, v198
	v_add_f32_e32 v3, v11, v10
	v_fmac_f32_e32 v2, v40, v9
	v_fmac_f32_e32 v1, v38, v200
	v_add_f32_e32 v0, v3, v2
	v_fmac_f32_e32 v1, v39, v201
	v_add_f32_e32 v1, v0, v1
	v_mul_f32_e64 v0, |v1|, s73
	v_exp_f32_e32 v0, v0
	v_fmac_f32_e32 v207, 0x3377d1cf, v206
	v_fmac_f32_e32 v207, 0x3f317217, v206
	v_cmp_lt_f32_e64 s[24:25], |v206|, s76
	v_add_f32_e32 v0, 1.0, v0
	v_cndmask_b32_e32 v3, 0, v166, vcc
	v_cndmask_b32_e64 v2, v206, v207, s[24:25]
	v_cmp_gt_f32_e32 vcc, s74, v0
	v_sub_f32_e32 v2, v2, v3
	v_min_f32_e32 v1, 0, v1
	v_cndmask_b32_e64 v3, 0, 32, vcc
	v_ldexp_f32 v0, v0, v3
	v_log_f32_e32 v3, v0
	v_sub_f32_e32 v0, v197, v2
	v_fmac_f32_e32 v168, 0x3d800000, v0
	v_mul_f32_e32 v2, 0x3f317217, v3
	v_fma_f32 v2, v3, s75, -v2
	v_fmac_f32_e32 v2, 0x3377d1cf, v3
	v_fmac_f32_e32 v2, 0x3f317217, v3
	v_cmp_lt_f32_e64 s[24:25], |v3|, s76
	s_nop 1
	v_cndmask_b32_e64 v2, v3, v2, s[24:25]
	v_cndmask_b32_e32 v3, 0, v166, vcc
	v_sub_f32_e32 v2, v2, v3
	v_sub_f32_e32 v1, v1, v2
	v_fmac_f32_e32 v168, 0x3d800000, v1
	s_and_saveexec_b64 s[0:1], s[6:7]
	s_xor_b64 s[24:25], exec, s[0:1]
	s_cbranch_execz .LBB0_577
	ds_write_b32 v51, v168 offset:5120
	ds_write_b32 v52, v4 offset:4096

; DI unsigned cvt_pk_bf16(float lo, float hi) { unsigned r; asm("v_cvt_pk_bf16_f32 %0, %1, %2" : "=v"(r) : "v"(lo), "v"(hi)); return r; }
; DI bf16_t f2bf(float f) { unsigned u = __builtin_bit_cast(unsigned, f); return (bf16_t)((u + 0x7fffu + ((u >> 16) & 1u)) >> 16); }
; __device__ void phase_glaprep(const Params& p, unsigned char* shm) {
;     ...
;         for (int ii = 0; ii < 32; ii += 2) {
;             float kh[2];
; #pragma unroll
;             for (int e = 0; e < 2; ++e) { const int i = half * 32 + ii + e; const float E = __expf(g[ii + e] - Gmid), Ei = __builtin_amdgcn_rcpf(E);
;                 const size_t gi = (size_t)(r0 + i) * KD + h * 256 + d;
;                 const float qv = bf2f(Q[gi]) * E, kv = bf2f(Kx[gi]) * Ei; kh[e] = kv * e2d;
;                 Qs[i * 264 + d] = f2bf(qv); Ks[i * 264 + d] = f2bf(kv); Qh[i * 264 + d] = f2bf(qv * e1d); }
;             kt[ii >> 1] = cvt_pk_bf16(kh[0], kh[1]);
;         }
.LBB0_583:
	v_add_u32_e32 v2, s57, v54
	v_add_u32_e32 v192, s57, v60
	v_or_b32_e32 v4, s60, v48
	v_ashrrev_i32_e32 v3, 31, v2
	v_ashrrev_i32_e32 v193, 31, v192
	v_lshlrev_b64 v[2:3], 11, v[2:3]
	v_lshlrev_b32_e32 v171, 1, v4
	v_lshlrev_b64 v[192:193], 11, v[192:193]
	v_or_b32_e32 v2, v2, v171
	v_or_b32_e32 v192, v192, v171
	v_lshl_add_u64 v[190:191], s[44:45], 0, v[2:3]
	v_lshl_add_u64 v[194:195], s[44:45], 0, v[192:193]
	v_lshl_add_u64 v[2:3], s[52:53], 0, v[2:3]
	v_lshl_add_u64 v[192:193], s[52:53], 0, v[192:193]
	ds_read_u16 v4, v58 offset:8192
	ds_read_u16 v196, v58 offset:41984
	s_nop 0
	ds_read_u16 v194, v61 offset:8192
	s_nop 0
	ds_read_u16 v195, v61 offset:41984
	v_add_u32_e32 v2, s57, v63
	v_ashrrev_i32_e32 v3, 31, v2
	s_waitcnt lgkmcnt(0)
	v_add_f32_e32 v39, v0, v1
	v_add_u32_e32 v0, s57, v66
	v_lshlrev_b64 v[2:3], 11, v[2:3]
	v_ashrrev_i32_e32 v1, 31, v0
	v_or_b32_e32 v2, v2, v171
	v_lshlrev_b64 v[0:1], 11, v[0:1]
	v_lshl_add_u64 v[190:191], s[44:45], 0, v[2:3]
	v_or_b32_e32 v0, v0, v171
	ds_read_u16 v197, v64 offset:8192
	v_lshl_add_u64 v[2:3], s[52:53], 0, v[2:3]
	v_lshl_add_u64 v[192:193], s[44:45], 0, v[0:1]
	ds_read_u16 v192, v67 offset:8192
	v_lshl_add_u64 v[0:1], s[52:53], 0, v[0:1]
	ds_read_u16 v198, v64 offset:41984
	ds_read_u16 v193, v67 offset:41984
	v_mul_f32_e32 v3, 0x3fb8aa3b, v41
	v_sub_f32_e32 v189, v189, v41
	v_add_u32_e32 v2, s57, v69
	v_sub_f32_e32 v174, v174, v41
	v_sub_f32_e32 v191, v173, v41
	v_exp_f32_e32 v173, v3
	v_sub_f32_e32 v0, v39, v41
	v_mul_f32_e32 v1, 0x3fb8aa3b, v189
	v_ashrrev_i32_e32 v3, 31, v2
	v_add_u32_e32 v190, s57, v72
	v_mul_f32_e32 v174, 0x3fb8aa3b, v174
	v_mul_f32_e32 v199, 0x3fb8aa3b, v0
	v_exp_f32_e32 v200, v1
	v_lshlrev_b64 v[0:1], 11, v[2:3]
	v_mul_f32_e32 v189, 0x3fb8aa3b, v191
	v_ashrrev_i32_e32 v191, 31, v190
	v_exp_f32_e32 v201, v174
	v_or_b32_e32 v0, v0, v171
	v_lshlrev_b64 v[2:3], 11, v[190:191]
	v_lshl_add_u64 v[190:191], s[44:45], 0, v[0:1]
	v_lshl_add_u64 v[0:1], s[52:53], 0, v[0:1]
	ds_read_u16 v190, v70 offset:8192
	s_nop 0
	ds_read_u16 v191, v70 offset:41984
	v_rcp_f32_e32 v0, v200
	v_rcp_f32_e32 v1, v201
	v_exp_f32_e32 v174, v199
	v_exp_f32_e32 v189, v189
	v_or_b32_e32 v2, v2, v171
	v_sub_f32_e32 v182, v182, v41
	v_mul_f32_e32 v182, 0x3fb8aa3b, v182
	v_exp_f32_e32 v182, v182
	v_sub_f32_e32 v181, v181, v41
	v_mul_f32_e32 v181, 0x3fb8aa3b, v181
	v_exp_f32_e32 v181, v181
	v_sub_f32_e32 v180, v180, v41
	v_mul_f32_e32 v180, 0x3fb8aa3b, v180
	v_exp_f32_e32 v180, v180
	v_sub_f32_e32 v5, v5, v41
	v_mul_f32_e32 v5, 0x3fb8aa3b, v5
	v_sub_f32_e32 v179, v179, v41
	v_mul_f32_e32 v179, 0x3fb8aa3b, v179
	v_exp_f32_e32 v179, v179
	v_sub_f32_e32 v6, v6, v41
	v_mul_f32_e32 v6, 0x3fb8aa3b, v6
	v_sub_f32_e32 v178, v178, v41
	v_mul_f32_e32 v178, 0x3fb8aa3b, v178
	v_exp_f32_e32 v178, v178
	v_sub_f32_e32 v7, v7, v41
	v_mul_f32_e32 v7, 0x3fb8aa3b, v7
	v_sub_f32_e32 v177, v177, v41
	v_mul_f32_e32 v177, 0x3fb8aa3b, v177
	v_exp_f32_e32 v177, v177
	v_sub_f32_e32 v8, v8, v41
	v_mul_f32_e32 v8, 0x3fb8aa3b, v8
	v_sub_f32_e32 v176, v176, v41
	v_mul_f32_e32 v176, 0x3fb8aa3b, v176
	v_exp_f32_e32 v176, v176
	v_sub_f32_e32 v9, v9, v41
	v_mul_f32_e32 v9, 0x3fb8aa3b, v9
	v_sub_f32_e32 v175, v175, v41
	s_waitcnt lgkmcnt(9)
	v_lshlrev_b32_e32 v4, 16, v4
	s_waitcnt lgkmcnt(8)
	v_lshlrev_b32_e32 v196, 16, v196
	v_mul_f32_e32 v4, v200, v4
	s_waitcnt lgkmcnt(6)
	v_lshlrev_b32_e32 v195, 16, v195
	v_mul_f32_e32 v0, v0, v196
	v_lshlrev_b32_e32 v194, 16, v194
	v_mul_f32_e32 v1, v1, v195
	v_bfe_u32 v196, v4, 16, 1
	v_bfe_u32 v199, v0, 16, 1
	v_mul_f32_e32 v200, v173, v4
	v_mul_f32_e32 v194, v201, v194
	v_mul_f32_e32 v195, v174, v0
	v_bfe_u32 v203, v1, 16, 1
	v_add3_u32 v4, v4, v196, s78
	v_add3_u32 v0, v0, v199, s78
	v_bfe_u32 v196, v200, 16, 1
	v_mul_f32_e32 v201, v174, v1
	v_bfe_u32 v202, v194, 16, 1
	v_add3_u32 v1, v1, v203, s78
	ds_write_b16_d16_hi v58, v4 offset:8192
	ds_write_b16_d16_hi v58, v0 offset:41984
	v_add3_u32 v0, v200, v196, s78
	v_mul_f32_e32 v204, v173, v194
	v_add3_u32 v194, v194, v202, s78
	ds_write_b16_d16_hi v59, v0
	ds_write_b16_d16_hi v61, v194 offset:8192
	ds_write_b16_d16_hi v61, v1 offset:41984
	v_lshl_add_u64 v[0:1], s[44:45], 0, v[2:3]
	ds_read_u16 v194, v73 offset:8192
	v_lshl_add_u64 v[0:1], s[52:53], 0, v[2:3]
	ds_read_u16 v196, v73 offset:41984
	v_rcp_f32_e32 v1, v189
	s_waitcnt lgkmcnt(12)
	v_lshlrev_b32_e32 v2, 16, v197
	v_mul_f32_e32 v2, v189, v2
	s_waitcnt lgkmcnt(10)
	v_lshlrev_b32_e32 v3, 16, v198
	v_bfe_u32 v199, v204, 16, 1
	v_mul_f32_e32 v1, v1, v3
	v_bfe_u32 v3, v2, 16, 1
	v_add3_u32 v4, v204, v199, s78
	v_add3_u32 v3, v2, v3, s78
	ds_write_b16_d16_hi v62, v4
	ds_write_b16_d16_hi v64, v3 offset:8192
	v_bfe_u32 v3, v1, 16, 1
	v_mul_f32_e32 v4, v174, v1
	v_add3_u32 v1, v1, v3, s78
	ds_write_b16_d16_hi v64, v1 offset:41984
	v_mul_f32_e32 v1, v173, v2
	v_sub_f32_e32 v2, v188, v41
	v_mul_f32_e32 v2, 0x3fb8aa3b, v2
	v_exp_f32_e32 v2, v2
	v_bfe_u32 v3, v1, 16, 1
	v_add3_u32 v1, v1, v3, s78
	ds_write_b16_d16_hi v65, v1
	v_rcp_f32_e32 v1, v2
	v_lshlrev_b32_e32 v3, 16, v192
	v_mul_f32_e32 v192, v2, v3
	s_waitcnt lgkmcnt(13)
	v_lshlrev_b32_e32 v2, 16, v193
	v_mul_f32_e32 v1, v1, v2
	v_add_u32_e32 v2, s57, v75
	v_ashrrev_i32_e32 v3, 31, v2
	v_lshlrev_b64 v[2:3], 11, v[2:3]
	v_or_b32_e32 v2, v2, v171
	v_lshl_add_u64 v[188:189], s[44:45], 0, v[2:3]
	ds_read_u16 v197, v76 offset:8192
	v_lshl_add_u64 v[2:3], s[52:53], 0, v[2:3]
	v_cvt_pk_bf16_f32 v0, v195, v201
	v_bfe_u32 v195, v192, 16, 1
	ds_read_u16 v198, v76 offset:41984
	v_add3_u32 v2, v192, v195, s78
	ds_write_b16_d16_hi v67, v2 offset:8192
	v_bfe_u32 v2, v1, 16, 1
	v_mul_f32_e32 v193, v174, v1
	v_add3_u32 v1, v1, v2, s78
	ds_write_b16_d16_hi v67, v1 offset:41984
	v_mul_f32_e32 v1, v173, v192
	v_bfe_u32 v2, v1, 16, 1
	v_add3_u32 v1, v1, v2, s78
	v_sub_f32_e32 v2, v187, v41
	v_mul_f32_e32 v2, 0x3fb8aa3b, v2
	v_exp_f32_e32 v187, v2
	v_add_u32_e32 v2, s57, v78
	v_ashrrev_i32_e32 v3, 31, v2
	v_lshlrev_b64 v[2:3], 11, v[2:3]
	v_or_b32_e32 v2, v2, v171
	v_lshl_add_u64 v[188:189], s[44:45], 0, v[2:3]
	ds_read_u16 v188, v79 offset:8192
	v_lshl_add_u64 v[2:3], s[52:53], 0, v[2:3]
	ds_read_u16 v189, v79 offset:41984
	v_rcp_f32_e32 v2, v187
	s_waitcnt lgkmcnt(15)
; DI unsigned cvt_pk_bf16(float lo, float hi) { unsigned r; asm("v_cvt_pk_bf16_f32 %0, %1, %2" : "=v"(r) : "v"(lo), "v"(hi)); return r; }
; DI bf16_t f2bf(float f) { unsigned u = __builtin_bit_cast(unsigned, f); return (bf16_t)((u + 0x7fffu + ((u >> 16) & 1u)) >> 16); }
; __device__ void phase_glaprep(const Params& p, unsigned char* shm) {
;     ...
;         for (int ii = 0; ii < 32; ii += 2) {
;             float kh[2];
; #pragma unroll
;             for (int e = 0; e < 2; ++e) { const int i = half * 32 + ii + e; const float E = __expf(g[ii + e] - Gmid), Ei = __builtin_amdgcn_rcpf(E);
;                 const size_t gi = (size_t)(r0 + i) * KD + h * 256 + d;
;                 const float qv = bf2f(Q[gi]) * E, kv = bf2f(Kx[gi]) * Ei; kh[e] = kv * e2d;
;                 Qs[i * 264 + d] = f2bf(qv); Ks[i * 264 + d] = f2bf(kv); Qh[i * 264 + d] = f2bf(qv * e1d); }
;             kt[ii >> 1] = cvt_pk_bf16(kh[0], kh[1]);
;         }
	v_lshlrev_b32_e32 v3, 16, v190
	v_mul_f32_e32 v3, v187, v3
	ds_write_b16_d16_hi v68, v1
	v_cvt_pk_bf16_f32 v1, v4, v193
	s_waitcnt lgkmcnt(15)
	v_lshlrev_b32_e32 v4, 16, v191
	v_bfe_u32 v187, v3, 16, 1
	v_mul_f32_e32 v2, v2, v4
	v_add3_u32 v187, v3, v187, s78
	ds_write_b16_d16_hi v70, v187 offset:8192
	v_bfe_u32 v187, v2, 16, 1
	v_mul_f32_e32 v4, v174, v2
	v_add3_u32 v2, v2, v187, s78
	ds_write_b16_d16_hi v70, v2 offset:41984
	v_mul_f32_e32 v2, v173, v3
	v_sub_f32_e32 v3, v186, v41
	v_mul_f32_e32 v3, 0x3fb8aa3b, v3
	v_exp_f32_e32 v3, v3
	v_bfe_u32 v186, v2, 16, 1
	v_add3_u32 v2, v2, v186, s78
	ds_write_b16_d16_hi v71, v2
	v_rcp_f32_e32 v2, v3
	s_waitcnt lgkmcnt(15)
	v_lshlrev_b32_e32 v186, 16, v194
	v_mul_f32_e32 v190, v3, v186
	s_waitcnt lgkmcnt(14)
	v_lshlrev_b32_e32 v3, 16, v196
	v_mul_f32_e32 v191, v2, v3
	v_add_u32_e32 v2, s57, v81
	v_ashrrev_i32_e32 v3, 31, v2
	v_lshlrev_b64 v[2:3], 11, v[2:3]
	v_or_b32_e32 v2, v2, v171
	v_bfe_u32 v193, v190, 16, 1
	v_lshl_add_u64 v[186:187], s[44:45], 0, v[2:3]
	v_lshl_add_u64 v[2:3], s[52:53], 0, v[2:3]
	ds_read_u16 v194, v82 offset:8192
	ds_read_u16 v195, v82 offset:41984
	v_add3_u32 v2, v190, v193, s78
	ds_write_b16_d16_hi v73, v2 offset:8192
	v_bfe_u32 v2, v191, 16, 1
	v_add3_u32 v2, v191, v2, s78
	ds_write_b16_d16_hi v73, v2 offset:41984
	v_mul_f32_e32 v2, v173, v190
	v_bfe_u32 v3, v2, 16, 1
	v_add3_u32 v190, v2, v3, s78
	v_sub_f32_e32 v2, v185, v41
	v_mul_f32_e32 v2, 0x3fb8aa3b, v2
	v_exp_f32_e32 v185, v2
	v_add_u32_e32 v2, s57, v84
	v_ashrrev_i32_e32 v3, 31, v2
	v_lshlrev_b64 v[2:3], 11, v[2:3]
	v_or_b32_e32 v2, v2, v171
	v_lshl_add_u64 v[186:187], s[44:45], 0, v[2:3]
	v_lshl_add_u64 v[2:3], s[52:53], 0, v[2:3]
	v_mul_f32_e32 v192, v174, v191
	ds_read_u16 v191, v85 offset:8192
	ds_read_u16 v193, v85 offset:41984
	v_rcp_f32_e32 v3, v185
	v_cvt_pk_bf16_f32 v2, v4, v192
	s_waitcnt lgkmcnt(15)
	v_lshlrev_b32_e32 v4, 16, v197
	v_mul_f32_e32 v4, v185, v4
	s_waitcnt lgkmcnt(14)
	v_lshlrev_b32_e32 v185, 16, v198
	v_mul_f32_e32 v3, v3, v185
	v_bfe_u32 v185, v4, 16, 1
	v_add3_u32 v185, v4, v185, s78
	ds_write_b16_d16_hi v74, v190
	ds_write_b16_d16_hi v76, v185 offset:8192
	v_bfe_u32 v185, v3, 16, 1
	v_mul_f32_e32 v190, v174, v3
	v_add3_u32 v3, v3, v185, s78
	ds_write_b16_d16_hi v76, v3 offset:41984
	v_mul_f32_e32 v3, v173, v4
	v_sub_f32_e32 v4, v184, v41
	v_mul_f32_e32 v4, 0x3fb8aa3b, v4
	v_exp_f32_e32 v4, v4
	v_bfe_u32 v184, v3, 16, 1
	v_add3_u32 v3, v3, v184, s78
	ds_write_b16_d16_hi v77, v3
	v_rcp_f32_e32 v3, v4
	s_waitcnt lgkmcnt(15)
	v_lshlrev_b32_e32 v184, 16, v188
	v_mul_f32_e32 v4, v4, v184
	s_waitcnt lgkmcnt(14)
	v_lshlrev_b32_e32 v184, 16, v189
	v_mul_f32_e32 v3, v3, v184
	v_add_u32_e32 v184, s57, v87
	v_ashrrev_i32_e32 v185, 31, v184
	v_lshlrev_b64 v[184:185], 11, v[184:185]
	v_or_b32_e32 v184, v184, v171
	v_lshl_add_u64 v[186:187], s[44:45], 0, v[184:185]
	ds_read_u16 v192, v88 offset:8192
	v_lshl_add_u64 v[184:185], s[52:53], 0, v[184:185]
	ds_read_u16 v196, v88 offset:41984
	v_bfe_u32 v189, v4, 16, 1
	v_add3_u32 v184, v4, v189, s78
	ds_write_b16_d16_hi v79, v184 offset:8192
	v_bfe_u32 v184, v3, 16, 1
	v_mul_f32_e32 v188, v174, v3
	v_add3_u32 v3, v3, v184, s78
	v_add_u32_e32 v184, s57, v90
	v_ashrrev_i32_e32 v185, 31, v184
	v_lshlrev_b64 v[184:185], 11, v[184:185]
	v_or_b32_e32 v184, v184, v171
	v_lshl_add_u64 v[186:187], s[44:45], 0, v[184:185]
	ds_read_u16 v186, v91 offset:8192
	v_lshl_add_u64 v[184:185], s[52:53], 0, v[184:185]
	ds_read_u16 v187, v91 offset:41984
	ds_write_b16_d16_hi v79, v3 offset:41984
	v_mul_f32_e32 v3, v173, v4
	v_bfe_u32 v4, v3, 16, 1
	v_add3_u32 v3, v3, v4, s78
	v_sub_f32_e32 v4, v183, v41
	v_mul_f32_e32 v4, 0x3fb8aa3b, v4
	v_exp_f32_e32 v4, v4
	ds_write_b16_d16_hi v80, v3
	v_cvt_pk_bf16_f32 v3, v190, v188
	v_mul_f32_e32 v175, 0x3fb8aa3b, v175
	v_rcp_f32_e32 v183, v4
	s_waitcnt lgkmcnt(15)
	v_lshlrev_b32_e32 v184, 16, v194
	v_mul_f32_e32 v4, v4, v184
	s_waitcnt lgkmcnt(15)
	v_lshlrev_b32_e32 v184, 16, v195
	v_mul_f32_e32 v183, v183, v184
	v_bfe_u32 v184, v4, 16, 1
	v_add3_u32 v184, v4, v184, s78
	ds_write_b16_d16_hi v82, v184 offset:8192
	v_bfe_u32 v184, v183, 16, 1
	v_mul_f32_e32 v188, v174, v183
	v_add3_u32 v183, v183, v184, s78
	v_mul_f32_e32 v4, v173, v4
	ds_write_b16_d16_hi v82, v183 offset:41984
	v_bfe_u32 v183, v4, 16, 1
	v_add3_u32 v4, v4, v183, s78
	ds_write_b16_d16_hi v83, v4
	v_rcp_f32_e32 v4, v182
	v_exp_f32_e32 v175, v175
	v_sub_f32_e32 v10, v10, v41
	v_mul_f32_e32 v10, 0x3fb8aa3b, v10
	s_waitcnt lgkmcnt(15)
	v_lshlrev_b32_e32 v183, 16, v191
	v_mul_f32_e32 v189, v182, v183
	s_waitcnt lgkmcnt(14)
	v_lshlrev_b32_e32 v182, 16, v193
	v_mul_f32_e32 v4, v4, v182
	v_add_u32_e32 v182, s57, v93
	v_ashrrev_i32_e32 v183, 31, v182
	v_lshlrev_b64 v[182:183], 11, v[182:183]
	v_or_b32_e32 v182, v182, v171
	v_bfe_u32 v191, v189, 16, 1
	v_lshl_add_u64 v[184:185], s[44:45], 0, v[182:183]
	v_lshl_add_u64 v[182:183], s[52:53], 0, v[182:183]
	ds_read_u16 v193, v94 offset:8192
	ds_read_u16 v194, v94 offset:41984
	v_add3_u32 v182, v189, v191, s78
	ds_write_b16_d16_hi v85, v182 offset:8192
	v_bfe_u32 v182, v4, 16, 1
	v_mul_f32_e32 v190, v174, v4
	v_add3_u32 v4, v4, v182, s78
	ds_write_b16_d16_hi v85, v4 offset:41984
	v_mul_f32_e32 v4, v173, v189
	v_bfe_u32 v182, v4, 16, 1
	v_add3_u32 v4, v4, v182, s78
	v_add_u32_e32 v182, s57, v96
	v_ashrrev_i32_e32 v183, 31, v182
	v_lshlrev_b64 v[182:183], 11, v[182:183]
	v_or_b32_e32 v182, v182, v171
	v_lshl_add_u64 v[184:185], s[44:45], 0, v[182:183]
	v_lshl_add_u64 v[182:183], s[52:53], 0, v[182:183]
	ds_read_u16 v184, v97 offset:8192
	ds_write_b16_d16_hi v86, v4
	ds_read_u16 v185, v97 offset:41984
	v_rcp_f32_e32 v182, v181
	v_cvt_pk_bf16_f32 v4, v188, v190
	s_waitcnt lgkmcnt(15)
; DI unsigned cvt_pk_bf16(float lo, float hi) { unsigned r; asm("v_cvt_pk_bf16_f32 %0, %1, %2" : "=v"(r) : "v"(lo), "v"(hi)); return r; }
; DI bf16_t f2bf(float f) { unsigned u = __builtin_bit_cast(unsigned, f); return (bf16_t)((u + 0x7fffu + ((u >> 16) & 1u)) >> 16); }
; __device__ void phase_glaprep(const Params& p, unsigned char* shm) {
;     ...
;         for (int ii = 0; ii < 32; ii += 2) {
;             float kh[2];
; #pragma unroll
;             for (int e = 0; e < 2; ++e) { const int i = half * 32 + ii + e; const float E = __expf(g[ii + e] - Gmid), Ei = __builtin_amdgcn_rcpf(E);
;                 const size_t gi = (size_t)(r0 + i) * KD + h * 256 + d;
;                 const float qv = bf2f(Q[gi]) * E, kv = bf2f(Kx[gi]) * Ei; kh[e] = kv * e2d;
;                 Qs[i * 264 + d] = f2bf(qv); Ks[i * 264 + d] = f2bf(kv); Qh[i * 264 + d] = f2bf(qv * e1d); }
;             kt[ii >> 1] = cvt_pk_bf16(kh[0], kh[1]);
;         }
	v_lshlrev_b32_e32 v183, 16, v192
	v_mul_f32_e32 v181, v181, v183
	s_waitcnt lgkmcnt(15)
	v_lshlrev_b32_e32 v183, 16, v196
	v_mul_f32_e32 v182, v182, v183
	v_bfe_u32 v183, v181, 16, 1
	v_add3_u32 v183, v181, v183, s78
	ds_write_b16_d16_hi v88, v183 offset:8192
	v_bfe_u32 v183, v182, 16, 1
	v_mul_f32_e32 v188, v174, v182
	v_add3_u32 v182, v182, v183, s78
	v_mul_f32_e32 v181, v173, v181
	ds_write_b16_d16_hi v88, v182 offset:41984
	v_bfe_u32 v182, v181, 16, 1
	v_add3_u32 v181, v181, v182, s78
	ds_write_b16_d16_hi v89, v181
	v_rcp_f32_e32 v181, v180
	s_waitcnt lgkmcnt(15)
	v_lshlrev_b32_e32 v182, 16, v186
	v_mul_f32_e32 v186, v180, v182
	s_waitcnt lgkmcnt(15)
	v_lshlrev_b32_e32 v180, 16, v187
	v_mul_f32_e32 v187, v181, v180
	v_add_u32_e32 v180, s57, v99
	v_ashrrev_i32_e32 v181, 31, v180
	v_lshlrev_b64 v[180:181], 11, v[180:181]
	v_or_b32_e32 v180, v180, v171
	v_lshl_add_u64 v[182:183], s[44:45], 0, v[180:181]
	v_bfe_u32 v190, v186, 16, 1
	ds_read_u16 v191, v100 offset:8192
	v_lshl_add_u64 v[180:181], s[52:53], 0, v[180:181]
	ds_read_u16 v192, v100 offset:41984
	v_add3_u32 v180, v186, v190, s78
	ds_write_b16_d16_hi v91, v180 offset:8192
	v_bfe_u32 v180, v187, 16, 1
	v_add3_u32 v180, v187, v180, s78
	ds_write_b16_d16_hi v91, v180 offset:41984
	v_mul_f32_e32 v180, v173, v186
	v_bfe_u32 v181, v180, 16, 1
	v_add3_u32 v186, v180, v181, s78
	v_add_u32_e32 v180, s57, v102
	v_ashrrev_i32_e32 v181, 31, v180
	v_lshlrev_b64 v[180:181], 11, v[180:181]
	v_or_b32_e32 v180, v180, v171
	v_lshl_add_u64 v[182:183], s[44:45], 0, v[180:181]
	ds_read_u16 v190, v103 offset:8192
	v_lshl_add_u64 v[180:181], s[52:53], 0, v[180:181]
	ds_read_u16 v195, v103 offset:41984
	v_mul_f32_e32 v189, v174, v187
	v_exp_f32_e32 v187, v5
	ds_write_b16_d16_hi v92, v186
	v_cvt_pk_bf16_f32 v5, v188, v189
	v_sub_f32_e32 v172, v172, v41
	v_rcp_f32_e32 v180, v187
	v_mul_f32_e32 v172, 0x3fb8aa3b, v172
	v_exp_f32_e32 v172, v172
	v_sub_f32_e32 v11, v11, v41
	v_mul_f32_e32 v11, 0x3fb8aa3b, v11
	v_sub_f32_e32 v170, v170, v41
	v_mul_f32_e32 v170, 0x3fb8aa3b, v170
	v_exp_f32_e32 v170, v170
	s_waitcnt lgkmcnt(15)
	v_lshlrev_b32_e32 v181, 16, v193
	v_mul_f32_e32 v181, v187, v181
	s_waitcnt lgkmcnt(15)
	v_lshlrev_b32_e32 v182, 16, v194
	v_mul_f32_e32 v180, v180, v182
	v_bfe_u32 v182, v181, 16, 1
	v_add3_u32 v182, v181, v182, s78
	ds_write_b16_d16_hi v94, v182 offset:8192
	v_bfe_u32 v182, v180, 16, 1
	v_mul_f32_e32 v186, v174, v180
	v_add3_u32 v180, v180, v182, s78
	ds_write_b16_d16_hi v94, v180 offset:41984
	v_mul_f32_e32 v180, v173, v181
	v_bfe_u32 v181, v180, 16, 1
	v_add3_u32 v180, v180, v181, s78
	ds_write_b16_d16_hi v95, v180
	v_rcp_f32_e32 v180, v179
	v_sub_f32_e32 v169, v169, v41
	s_waitcnt lgkmcnt(15)
	v_lshlrev_b32_e32 v181, 16, v184
	v_mul_f32_e32 v179, v179, v181
	s_waitcnt lgkmcnt(13)
	v_lshlrev_b32_e32 v181, 16, v185
	v_mul_f32_e32 v184, v180, v181
	v_add_u32_e32 v180, s57, v105
	v_ashrrev_i32_e32 v181, 31, v180
	v_lshlrev_b64 v[180:181], 11, v[180:181]
	v_or_b32_e32 v180, v180, v171
	v_bfe_u32 v187, v179, 16, 1
	v_lshl_add_u64 v[182:183], s[44:45], 0, v[180:181]
	v_lshl_add_u64 v[180:181], s[52:53], 0, v[180:181]
	ds_read_u16 v188, v106 offset:8192
	ds_read_u16 v189, v106 offset:41984
	v_add3_u32 v180, v179, v187, s78
	ds_write_b16_d16_hi v97, v180 offset:8192
	v_bfe_u32 v180, v184, 16, 1
	v_add3_u32 v180, v184, v180, s78
	v_mul_f32_e32 v179, v173, v179
	v_mul_f32_e32 v185, v174, v184
	ds_write_b16_d16_hi v97, v180 offset:41984
	v_bfe_u32 v180, v179, 16, 1
	v_exp_f32_e32 v184, v6
	v_add3_u32 v179, v179, v180, s78
	v_add_u32_e32 v180, s57, v108
	v_ashrrev_i32_e32 v181, 31, v180
	v_lshlrev_b64 v[180:181], 11, v[180:181]
	v_or_b32_e32 v180, v180, v171
	ds_write_b16_d16_hi v98, v179
	v_rcp_f32_e32 v179, v184
	v_lshl_add_u64 v[182:183], s[44:45], 0, v[180:181]
	v_lshl_add_u64 v[180:181], s[52:53], 0, v[180:181]
	ds_read_u16 v182, v109 offset:8192
	v_cvt_pk_bf16_f32 v6, v186, v185
	ds_read_u16 v183, v109 offset:41984
	s_waitcnt lgkmcnt(15)
	v_lshlrev_b32_e32 v180, 16, v191
	v_mul_f32_e32 v180, v184, v180
	s_waitcnt lgkmcnt(15)
	v_lshlrev_b32_e32 v181, 16, v192
	v_mul_f32_e32 v179, v179, v181
	v_bfe_u32 v181, v180, 16, 1
	v_add3_u32 v181, v180, v181, s78
	ds_write_b16_d16_hi v100, v181 offset:8192
	v_bfe_u32 v181, v179, 16, 1
	v_mul_f32_e32 v184, v174, v179
	v_add3_u32 v179, v179, v181, s78
	ds_write_b16_d16_hi v100, v179 offset:41984
	v_mul_f32_e32 v179, v173, v180
	v_bfe_u32 v180, v179, 16, 1
	v_add3_u32 v179, v179, v180, s78
	ds_write_b16_d16_hi v101, v179
	v_rcp_f32_e32 v179, v178
	s_waitcnt lgkmcnt(15)
	v_lshlrev_b32_e32 v180, 16, v190
	v_mul_f32_e32 v185, v178, v180
	s_waitcnt lgkmcnt(14)
	v_lshlrev_b32_e32 v178, 16, v195
	v_mul_f32_e32 v186, v179, v178
	v_add_u32_e32 v178, s57, v111
	v_ashrrev_i32_e32 v179, 31, v178
	v_lshlrev_b64 v[178:179], 11, v[178:179]
	v_or_b32_e32 v178, v178, v171
	v_lshl_add_u64 v[180:181], s[44:45], 0, v[178:179]
	v_bfe_u32 v190, v185, 16, 1
	ds_read_u16 v191, v112 offset:8192
	v_lshl_add_u64 v[178:179], s[52:53], 0, v[178:179]
	ds_read_u16 v192, v112 offset:41984
	v_add3_u32 v178, v185, v190, s78
	ds_write_b16_d16_hi v103, v178 offset:8192
	v_bfe_u32 v178, v186, 16, 1
	v_add3_u32 v178, v186, v178, s78
	ds_write_b16_d16_hi v103, v178 offset:41984
	v_mul_f32_e32 v178, v173, v185
	v_bfe_u32 v179, v178, 16, 1
	v_add3_u32 v185, v178, v179, s78
	v_add_u32_e32 v178, s57, v114
	v_ashrrev_i32_e32 v179, 31, v178
	v_lshlrev_b64 v[178:179], 11, v[178:179]
	v_or_b32_e32 v178, v178, v171
	v_lshl_add_u64 v[180:181], s[44:45], 0, v[178:179]
	ds_read_u16 v190, v115 offset:8192
	v_lshl_add_u64 v[178:179], s[52:53], 0, v[178:179]
	ds_read_u16 v193, v115 offset:41984
	v_mul_f32_e32 v187, v174, v186
	v_exp_f32_e32 v186, v7
	ds_write_b16_d16_hi v104, v185
	v_cvt_pk_bf16_f32 v7, v184, v187
	v_mul_f32_e32 v169, 0x3fb8aa3b, v169
	v_rcp_f32_e32 v178, v186
	v_exp_f32_e32 v169, v169
	v_sub_f32_e32 v168, v168, v41
	v_mul_f32_e32 v168, 0x3fb8aa3b, v168
	v_sub_f32_e32 v167, v167, v41
	v_mul_f32_e32 v167, 0x3fb8aa3b, v167
	v_exp_f32_e32 v167, v167
	s_waitcnt lgkmcnt(15)
; DI unsigned cvt_pk_bf16(float lo, float hi) { unsigned r; asm("v_cvt_pk_bf16_f32 %0, %1, %2" : "=v"(r) : "v"(lo), "v"(hi)); return r; }
; DI bf16_t f2bf(float f) { unsigned u = __builtin_bit_cast(unsigned, f); return (bf16_t)((u + 0x7fffu + ((u >> 16) & 1u)) >> 16); }
; __device__ void phase_glaprep(const Params& p, unsigned char* shm) {
;     ...
;         for (int ii = 0; ii < 32; ii += 2) {
;             float kh[2];
; #pragma unroll
;             for (int e = 0; e < 2; ++e) { const int i = half * 32 + ii + e; const float E = __expf(g[ii + e] - Gmid), Ei = __builtin_amdgcn_rcpf(E);
;                 const size_t gi = (size_t)(r0 + i) * KD + h * 256 + d;
;                 const float qv = bf2f(Q[gi]) * E, kv = bf2f(Kx[gi]) * Ei; kh[e] = kv * e2d;
;                 Qs[i * 264 + d] = f2bf(qv); Ks[i * 264 + d] = f2bf(kv); Qh[i * 264 + d] = f2bf(qv * e1d); }
;             kt[ii >> 1] = cvt_pk_bf16(kh[0], kh[1]);
;         }
	v_lshlrev_b32_e32 v179, 16, v188
	v_mul_f32_e32 v179, v186, v179
	s_waitcnt lgkmcnt(15)
	v_lshlrev_b32_e32 v180, 16, v189
	v_mul_f32_e32 v178, v178, v180
	v_bfe_u32 v180, v179, 16, 1
	v_add3_u32 v180, v179, v180, s78
	ds_write_b16_d16_hi v106, v180 offset:8192
	v_bfe_u32 v180, v178, 16, 1
	v_mul_f32_e32 v184, v174, v178
	v_add3_u32 v178, v178, v180, s78
	ds_write_b16_d16_hi v106, v178 offset:41984
	v_mul_f32_e32 v178, v173, v179
	v_bfe_u32 v179, v178, 16, 1
	v_add3_u32 v178, v178, v179, s78
	ds_write_b16_d16_hi v107, v178
	v_rcp_f32_e32 v178, v177
	v_sub_f32_e32 v12, v12, v41
	v_mul_f32_e32 v12, 0x3fb8aa3b, v12
	v_exp_f32_e32 v12, v12
	v_sub_f32_e32 v38, v38, v41
	s_waitcnt lgkmcnt(14)
	v_lshlrev_b32_e32 v179, 16, v182
	v_mul_f32_e32 v177, v177, v179
	s_waitcnt lgkmcnt(13)
	v_lshlrev_b32_e32 v179, 16, v183
	v_mul_f32_e32 v182, v178, v179
	v_add_u32_e32 v178, s57, v117
	v_ashrrev_i32_e32 v179, 31, v178
	v_lshlrev_b64 v[178:179], 11, v[178:179]
	v_or_b32_e32 v178, v178, v171
	v_bfe_u32 v185, v177, 16, 1
	v_lshl_add_u64 v[180:181], s[44:45], 0, v[178:179]
	v_lshl_add_u64 v[178:179], s[52:53], 0, v[178:179]
	ds_read_u16 v186, v118 offset:8192
	ds_read_u16 v187, v118 offset:41984
	v_add3_u32 v178, v177, v185, s78
	ds_write_b16_d16_hi v109, v178 offset:8192
	v_bfe_u32 v178, v182, 16, 1
	v_add3_u32 v178, v182, v178, s78
	v_mul_f32_e32 v177, v173, v177
	v_mul_f32_e32 v183, v174, v182
	ds_write_b16_d16_hi v109, v178 offset:41984
	v_bfe_u32 v178, v177, 16, 1
	v_exp_f32_e32 v182, v8
	v_add3_u32 v177, v177, v178, s78
	v_add_u32_e32 v178, s57, v120
	v_ashrrev_i32_e32 v179, 31, v178
	v_lshlrev_b64 v[178:179], 11, v[178:179]
	v_or_b32_e32 v178, v178, v171
	ds_write_b16_d16_hi v110, v177
	v_rcp_f32_e32 v177, v182
	v_lshl_add_u64 v[180:181], s[44:45], 0, v[178:179]
	v_lshl_add_u64 v[178:179], s[52:53], 0, v[178:179]
	ds_read_u16 v180, v121 offset:8192
	v_cvt_pk_bf16_f32 v8, v184, v183
	ds_read_u16 v181, v121 offset:41984
	s_waitcnt lgkmcnt(15)
	v_lshlrev_b32_e32 v178, 16, v191
	v_mul_f32_e32 v178, v182, v178
	s_waitcnt lgkmcnt(15)
	v_lshlrev_b32_e32 v179, 16, v192
	v_mul_f32_e32 v177, v177, v179
	v_bfe_u32 v179, v178, 16, 1
	v_add3_u32 v179, v178, v179, s78
	ds_write_b16_d16_hi v112, v179 offset:8192
	v_bfe_u32 v179, v177, 16, 1
	v_mul_f32_e32 v182, v174, v177
	v_add3_u32 v177, v177, v179, s78
	ds_write_b16_d16_hi v112, v177 offset:41984
	v_mul_f32_e32 v177, v173, v178
	v_bfe_u32 v178, v177, 16, 1
	v_add3_u32 v177, v177, v178, s78
	ds_write_b16_d16_hi v113, v177
	v_rcp_f32_e32 v177, v176
	s_waitcnt lgkmcnt(15)
	v_lshlrev_b32_e32 v178, 16, v190
	v_mul_f32_e32 v183, v176, v178
	s_waitcnt lgkmcnt(14)
	v_lshlrev_b32_e32 v176, 16, v193
	v_mul_f32_e32 v184, v177, v176
	v_add_u32_e32 v176, s57, v123
	v_ashrrev_i32_e32 v177, 31, v176
	v_lshlrev_b64 v[176:177], 11, v[176:177]
	v_or_b32_e32 v176, v176, v171
	v_lshl_add_u64 v[178:179], s[44:45], 0, v[176:177]
	v_bfe_u32 v188, v183, 16, 1
	ds_read_u16 v189, v124 offset:8192
	v_lshl_add_u64 v[176:177], s[52:53], 0, v[176:177]
	ds_read_u16 v190, v124 offset:41984
	v_add3_u32 v176, v183, v188, s78
	ds_write_b16_d16_hi v115, v176 offset:8192
	v_bfe_u32 v176, v184, 16, 1
	v_add3_u32 v176, v184, v176, s78
	ds_write_b16_d16_hi v115, v176 offset:41984
	v_mul_f32_e32 v176, v173, v183
	v_bfe_u32 v177, v176, 16, 1
	v_add3_u32 v183, v176, v177, s78
	v_add_u32_e32 v176, s57, v126
	v_ashrrev_i32_e32 v177, 31, v176
	v_lshlrev_b64 v[176:177], 11, v[176:177]
	v_or_b32_e32 v176, v176, v171
	v_lshl_add_u64 v[178:179], s[44:45], 0, v[176:177]
	ds_read_u16 v188, v127 offset:8192
	v_lshl_add_u64 v[176:177], s[52:53], 0, v[176:177]
	ds_read_u16 v191, v127 offset:41984
	v_mul_f32_e32 v185, v174, v184
	v_exp_f32_e32 v184, v9
	ds_write_b16_d16_hi v116, v183
	v_cvt_pk_bf16_f32 v9, v182, v185
	v_mul_f32_e32 v38, 0x3fb8aa3b, v38
	v_rcp_f32_e32 v176, v184
	v_exp_f32_e32 v38, v38
	s_waitcnt lgkmcnt(15)
	v_lshlrev_b32_e32 v177, 16, v186
	v_mul_f32_e32 v177, v184, v177
	s_waitcnt lgkmcnt(15)
	v_lshlrev_b32_e32 v178, 16, v187
	v_mul_f32_e32 v176, v176, v178
	v_bfe_u32 v178, v177, 16, 1
	v_add3_u32 v178, v177, v178, s78
	ds_write_b16_d16_hi v118, v178 offset:8192
	v_bfe_u32 v178, v176, 16, 1
	v_mul_f32_e32 v182, v174, v176
	v_add3_u32 v176, v176, v178, s78
	ds_write_b16_d16_hi v118, v176 offset:41984
	v_mul_f32_e32 v176, v173, v177
	v_bfe_u32 v177, v176, 16, 1
	v_add3_u32 v176, v176, v177, s78
	ds_write_b16_d16_hi v119, v176
	v_rcp_f32_e32 v176, v175
	s_waitcnt lgkmcnt(14)
	v_lshlrev_b32_e32 v177, 16, v180
	v_mul_f32_e32 v175, v175, v177
	s_waitcnt lgkmcnt(13)
	v_lshlrev_b32_e32 v177, 16, v181
	v_mul_f32_e32 v180, v176, v177
	v_add_u32_e32 v176, s57, v129
	v_ashrrev_i32_e32 v177, 31, v176
	v_lshlrev_b64 v[176:177], 11, v[176:177]
	v_or_b32_e32 v176, v176, v171
	v_bfe_u32 v183, v175, 16, 1
	v_lshl_add_u64 v[178:179], s[44:45], 0, v[176:177]
	v_lshl_add_u64 v[176:177], s[52:53], 0, v[176:177]
	ds_read_u16 v184, v130 offset:8192
	ds_read_u16 v185, v130 offset:41984
	v_add3_u32 v176, v175, v183, s78
	ds_write_b16_d16_hi v121, v176 offset:8192
	v_bfe_u32 v176, v180, 16, 1
	v_add3_u32 v176, v180, v176, s78
	v_mul_f32_e32 v175, v173, v175
	v_mul_f32_e32 v181, v174, v180
	ds_write_b16_d16_hi v121, v176 offset:41984
	v_bfe_u32 v176, v175, 16, 1
	v_exp_f32_e32 v180, v10
	v_add3_u32 v175, v175, v176, s78
	v_add_u32_e32 v176, s57, v132
	v_ashrrev_i32_e32 v177, 31, v176
	v_lshlrev_b64 v[176:177], 11, v[176:177]
	v_or_b32_e32 v176, v176, v171
	ds_write_b16_d16_hi v122, v175
	v_rcp_f32_e32 v175, v180
	v_lshl_add_u64 v[178:179], s[44:45], 0, v[176:177]
	v_lshl_add_u64 v[176:177], s[52:53], 0, v[176:177]
	ds_read_u16 v183, v133 offset:8192
	ds_read_u16 v186, v133 offset:41984
	s_waitcnt lgkmcnt(15)
; DI unsigned cvt_pk_bf16(float lo, float hi) { unsigned r; asm("v_cvt_pk_bf16_f32 %0, %1, %2" : "=v"(r) : "v"(lo), "v"(hi)); return r; }
; DI bf16_t f2bf(float f) { unsigned u = __builtin_bit_cast(unsigned, f); return (bf16_t)((u + 0x7fffu + ((u >> 16) & 1u)) >> 16); }
; __device__ void phase_glaprep(const Params& p, unsigned char* shm) {
;     ...
;         for (int ii = 0; ii < 32; ii += 2) {
;             float kh[2];
; #pragma unroll
;             for (int e = 0; e < 2; ++e) { const int i = half * 32 + ii + e; const float E = __expf(g[ii + e] - Gmid), Ei = __builtin_amdgcn_rcpf(E);
;                 const size_t gi = (size_t)(r0 + i) * KD + h * 256 + d;
;                 const float qv = bf2f(Q[gi]) * E, kv = bf2f(Kx[gi]) * Ei; kh[e] = kv * e2d;
;                 Qs[i * 264 + d] = f2bf(qv); Ks[i * 264 + d] = f2bf(kv); Qh[i * 264 + d] = f2bf(qv * e1d); }
;             kt[ii >> 1] = cvt_pk_bf16(kh[0], kh[1]);
;         }
	v_lshlrev_b32_e32 v176, 16, v189
	v_mul_f32_e32 v176, v180, v176
	s_waitcnt lgkmcnt(15)
	v_lshlrev_b32_e32 v177, 16, v190
	v_mul_f32_e32 v175, v175, v177
	v_bfe_u32 v177, v176, 16, 1
	v_add3_u32 v177, v176, v177, s78
	ds_write_b16_d16_hi v124, v177 offset:8192
	v_bfe_u32 v177, v175, 16, 1
	v_mul_f32_e32 v180, v174, v175
	v_add3_u32 v175, v175, v177, s78
	ds_write_b16_d16_hi v124, v175 offset:41984
	v_mul_f32_e32 v175, v173, v176
	v_bfe_u32 v176, v175, 16, 1
	v_add3_u32 v175, v175, v176, s78
	ds_write_b16_d16_hi v125, v175
	v_rcp_f32_e32 v175, v172
	s_waitcnt lgkmcnt(15)
	v_lshlrev_b32_e32 v176, 16, v188
	v_mul_f32_e32 v172, v172, v176
	s_waitcnt lgkmcnt(14)
	v_lshlrev_b32_e32 v176, 16, v191
	v_mul_f32_e32 v175, v175, v176
	v_add_u32_e32 v176, s57, v135
	v_ashrrev_i32_e32 v177, 31, v176
	v_lshlrev_b64 v[176:177], 11, v[176:177]
	v_or_b32_e32 v176, v176, v171
	v_lshl_add_u64 v[178:179], s[44:45], 0, v[176:177]
	ds_read_u16 v187, v137 offset:8192
	v_lshl_add_u64 v[176:177], s[52:53], 0, v[176:177]
	ds_read_u16 v188, v137 offset:41984
	v_cvt_pk_bf16_f32 v10, v182, v181
	v_bfe_u32 v182, v172, 16, 1
	v_add3_u32 v176, v172, v182, s78
	ds_write_b16_d16_hi v127, v176 offset:8192
	v_bfe_u32 v176, v175, 16, 1
	v_exp_f32_e32 v182, v11
	v_mul_f32_e32 v181, v174, v175
	v_add3_u32 v175, v175, v176, s78
	v_add_u32_e32 v176, s57, v139
	v_mul_f32_e32 v172, v173, v172
	v_ashrrev_i32_e32 v177, 31, v176
	ds_write_b16_d16_hi v127, v175 offset:41984
	v_bfe_u32 v175, v172, 16, 1
	v_lshlrev_b64 v[176:177], 11, v[176:177]
	v_add3_u32 v11, v172, v175, s78
	v_rcp_f32_e32 v172, v182
	v_or_b32_e32 v176, v176, v171
	ds_write_b16_d16_hi v128, v11
	v_lshl_add_u64 v[178:179], s[44:45], 0, v[176:177]
	v_lshl_add_u64 v[176:177], s[52:53], 0, v[176:177]
	v_cvt_pk_bf16_f32 v11, v180, v181
	ds_read_u16 v175, v140 offset:8192
	ds_read_u16 v180, v140 offset:41984
	s_waitcnt lgkmcnt(15)
	v_lshlrev_b32_e32 v176, 16, v184
	v_mul_f32_e32 v176, v182, v176
	s_waitcnt lgkmcnt(15)
	v_lshlrev_b32_e32 v177, 16, v185
	v_mul_f32_e32 v172, v172, v177
	v_bfe_u32 v177, v176, 16, 1
	v_add3_u32 v177, v176, v177, s78
	ds_write_b16_d16_hi v130, v177 offset:8192
	v_bfe_u32 v177, v172, 16, 1
	v_mul_f32_e32 v181, v174, v172
	v_add3_u32 v172, v172, v177, s78
	ds_write_b16_d16_hi v130, v172 offset:41984
	v_mul_f32_e32 v172, v173, v176
	v_bfe_u32 v176, v172, 16, 1
	v_add3_u32 v172, v172, v176, s78
	ds_write_b16_d16_hi v131, v172
	v_rcp_f32_e32 v172, v170
	s_waitcnt lgkmcnt(14)
	v_lshlrev_b32_e32 v176, 16, v183
	v_mul_f32_e32 v170, v170, v176
	s_waitcnt lgkmcnt(13)
	v_lshlrev_b32_e32 v176, 16, v186
	v_mul_f32_e32 v172, v172, v176
	v_add_u32_e32 v176, s57, v142
	v_ashrrev_i32_e32 v177, 31, v176
	v_lshlrev_b64 v[176:177], 11, v[176:177]
	v_or_b32_e32 v176, v176, v171
	v_bfe_u32 v183, v170, 16, 1
	v_lshl_add_u64 v[178:179], s[44:45], 0, v[176:177]
	v_lshl_add_u64 v[176:177], s[52:53], 0, v[176:177]
	ds_read_u16 v184, v143 offset:8192
	ds_read_u16 v185, v143 offset:41984
	v_add3_u32 v176, v170, v183, s78
	ds_write_b16_d16_hi v133, v176 offset:8192
	v_bfe_u32 v176, v172, 16, 1
	v_mul_f32_e32 v182, v174, v172
	v_add3_u32 v172, v172, v176, s78
	v_add_u32_e32 v176, s57, v145
	v_ashrrev_i32_e32 v177, 31, v176
	v_lshlrev_b64 v[176:177], 11, v[176:177]
	v_mul_f32_e32 v170, v173, v170
	v_or_b32_e32 v176, v176, v171
	ds_write_b16_d16_hi v133, v172 offset:41984
	v_bfe_u32 v172, v170, 16, 1
	v_lshl_add_u64 v[178:179], s[44:45], 0, v[176:177]
	v_lshl_add_u64 v[176:177], s[52:53], 0, v[176:177]
	v_add3_u32 v170, v170, v172, s78
	ds_read_u16 v172, v146 offset:8192
	ds_read_u16 v183, v146 offset:41984
	v_rcp_f32_e32 v176, v169
	s_waitcnt lgkmcnt(15)
	v_lshlrev_b32_e32 v177, 16, v187
	v_mul_f32_e32 v169, v169, v177
	s_waitcnt lgkmcnt(14)
; DI unsigned cvt_pk_bf16(float lo, float hi) { unsigned r; asm("v_cvt_pk_bf16_f32 %0, %1, %2" : "=v"(r) : "v"(lo), "v"(hi)); return r; }
; DI bf16_t f2bf(float f) { unsigned u = __builtin_bit_cast(unsigned, f); return (bf16_t)((u + 0x7fffu + ((u >> 16) & 1u)) >> 16); }
; __device__ void phase_glaprep(const Params& p, unsigned char* shm) {
;     ...
;         for (int ii = 0; ii < 32; ii += 2) {
;             float kh[2];
; #pragma unroll
;             for (int e = 0; e < 2; ++e) { const int i = half * 32 + ii + e; const float E = __expf(g[ii + e] - Gmid), Ei = __builtin_amdgcn_rcpf(E);
;                 const size_t gi = (size_t)(r0 + i) * KD + h * 256 + d;
;                 const float qv = bf2f(Q[gi]) * E, kv = bf2f(Kx[gi]) * Ei; kh[e] = kv * e2d;
;                 Qs[i * 264 + d] = f2bf(qv); Ks[i * 264 + d] = f2bf(kv); Qh[i * 264 + d] = f2bf(qv * e1d); }
;             kt[ii >> 1] = cvt_pk_bf16(kh[0], kh[1]);
;         }
; #pragma unroll
;         for (int cc = 0; cc < 4; ++cc) { const int c = half * 4 + cc, cs = c ^ ((d >> 1) & 7);
;             u32x4 v; v.x = kt[cc * 4]; v.y = kt[cc * 4 + 1]; v.z = kt[cc * 4 + 2]; v.w = kt[cc * 4 + 3];
;             *(u32x4*)(kimg + (size_t)unit * 32768 + d * 128 + cs * 16) = v; }
;         if (half == 0) e12[(size_t)unit * 256 + d] = __expf(Glast);
	v_lshlrev_b32_e32 v177, 16, v188
	ds_write_b16_d16_hi v134, v170
	v_cvt_pk_bf16_f32 v170, v181, v182
	v_mul_f32_e32 v181, v176, v177
	v_bfe_u32 v176, v169, 16, 1
	v_add3_u32 v176, v169, v176, s78
	ds_write_b16_d16_hi v137, v176 offset:8192
	v_add_u32_e32 v176, s57, v148
	v_ashrrev_i32_e32 v177, 31, v176
	v_lshlrev_b64 v[176:177], 11, v[176:177]
	v_or_b32_e32 v176, v176, v171
	v_lshl_add_u64 v[178:179], s[44:45], 0, v[176:177]
	ds_read_u16 v178, v149 offset:8192
	v_lshl_add_u64 v[176:177], s[52:53], 0, v[176:177]
	ds_read_u16 v179, v149 offset:41984
	v_bfe_u32 v186, v181, 16, 1
	v_mul_f32_e32 v169, v173, v169
	v_mul_f32_e32 v182, v174, v181
	v_add3_u32 v176, v181, v186, s78
	v_exp_f32_e32 v181, v168
	v_bfe_u32 v168, v169, 16, 1
	v_add3_u32 v168, v169, v168, s78
	ds_write_b16_d16_hi v138, v168
	v_add_u32_e32 v168, s57, v151
	v_ashrrev_i32_e32 v169, 31, v168
	v_lshlrev_b64 v[168:169], 11, v[168:169]
	v_or_b32_e32 v168, v168, v171
	ds_write_b16_d16_hi v137, v176 offset:41984
	v_lshl_add_u64 v[176:177], s[44:45], 0, v[168:169]
	ds_read_u16 v176, v152 offset:8192
	v_lshl_add_u64 v[168:169], s[52:53], 0, v[168:169]
	ds_read_u16 v168, v152 offset:41984
	v_rcp_f32_e32 v186, v181
	s_waitcnt lgkmcnt(15)
	v_lshlrev_b32_e32 v175, 16, v175
	v_mul_f32_e32 v169, v181, v175
	s_waitcnt lgkmcnt(15)
	v_lshlrev_b32_e32 v171, 16, v180
	v_bfe_u32 v177, v169, 16, 1
	v_mul_f32_e32 v171, v186, v171
	v_add3_u32 v177, v169, v177, s78
	ds_write_b16_d16_hi v140, v177 offset:8192
	v_bfe_u32 v177, v171, 16, 1
	v_mul_f32_e32 v175, v174, v171
	v_add3_u32 v171, v171, v177, s78
	v_mul_f32_e32 v169, v173, v169
	ds_write_b16_d16_hi v140, v171 offset:41984
	v_bfe_u32 v171, v169, 16, 1
	v_add3_u32 v169, v169, v171, s78
	ds_write_b16_d16_hi v141, v169
	v_rcp_f32_e32 v169, v167
	v_cvt_pk_bf16_f32 v171, v182, v175
	s_ashr_i32 s57, s56, 31
	s_lshl_b64 s[58:59], s[56:57], 15
	s_waitcnt lgkmcnt(15)
	v_lshlrev_b32_e32 v175, 16, v184
	v_mul_f32_e32 v167, v167, v175
	s_waitcnt lgkmcnt(15)
	v_lshlrev_b32_e32 v175, 16, v185
	v_bfe_u32 v177, v167, 16, 1
	v_mul_f32_e32 v169, v169, v175
	v_add3_u32 v177, v167, v177, s78
	ds_write_b16_d16_hi v143, v177 offset:8192
	v_bfe_u32 v177, v169, 16, 1
	v_mul_f32_e32 v175, v174, v169
	v_add3_u32 v169, v169, v177, s78
	v_mul_f32_e32 v167, v173, v167
	ds_write_b16_d16_hi v143, v169 offset:41984
	v_bfe_u32 v169, v167, 16, 1
	v_add3_u32 v167, v167, v169, s78
	ds_write_b16_d16_hi v144, v167
	v_rcp_f32_e32 v167, v12
	s_waitcnt lgkmcnt(15)
	v_lshlrev_b32_e32 v169, 16, v172
	v_mul_f32_e32 v12, v12, v169
	s_waitcnt lgkmcnt(14)
	v_lshlrev_b32_e32 v169, 16, v183
	v_bfe_u32 v172, v12, 16, 1
	v_mul_f32_e32 v167, v167, v169
	v_add3_u32 v172, v12, v172, s78
	ds_write_b16_d16_hi v146, v172 offset:8192
	v_bfe_u32 v172, v167, 16, 1
	v_mul_f32_e32 v169, v174, v167
	v_add3_u32 v167, v167, v172, s78
	v_mul_f32_e32 v12, v173, v12
	ds_write_b16_d16_hi v146, v167 offset:41984
	v_bfe_u32 v167, v12, 16, 1
	v_add3_u32 v12, v12, v167, s78
	ds_write_b16_d16_hi v147, v12
	v_rcp_f32_e32 v12, v38
	v_cvt_pk_bf16_f32 v172, v175, v169
	s_waitcnt lgkmcnt(14)
	v_lshlrev_b32_e32 v167, 16, v178
	v_mul_f32_e32 v38, v38, v167
	s_waitcnt lgkmcnt(13)
	v_lshlrev_b32_e32 v167, 16, v179
	v_bfe_u32 v169, v38, 16, 1
	v_mul_f32_e32 v12, v12, v167
	v_add3_u32 v169, v38, v169, s78
	ds_write_b16_d16_hi v149, v169 offset:8192
	v_bfe_u32 v169, v12, 16, 1
	v_mul_f32_e32 v167, v174, v12
	v_add3_u32 v12, v12, v169, s78
	ds_write_b16_d16_hi v149, v12 offset:41984
	v_mul_f32_e32 v12, v173, v38
	v_sub_f32_e32 v38, v40, v41
	v_mul_f32_e32 v38, 0x3fb8aa3b, v38
	v_exp_f32_e32 v38, v38
	v_bfe_u32 v40, v12, 16, 1
	v_add3_u32 v12, v12, v40, s78
	ds_write_b16_d16_hi v150, v12
	v_rcp_f32_e32 v12, v38
	s_waitcnt lgkmcnt(13)
	v_lshlrev_b32_e32 v40, 16, v176
	v_mul_f32_e32 v38, v38, v40
	s_waitcnt lgkmcnt(12)
	v_lshlrev_b32_e32 v40, 16, v168
	v_bfe_u32 v41, v38, 16, 1
	v_mul_f32_e32 v12, v12, v40
	v_add3_u32 v41, v38, v41, s78
	ds_write_b16_d16_hi v152, v41 offset:8192
	v_bfe_u32 v41, v12, 16, 1
	v_mul_f32_e32 v40, v174, v12
	v_add3_u32 v12, v12, v41, s78
	ds_write_b16_d16_hi v152, v12 offset:41984
	v_mul_f32_e32 v12, v173, v38
	v_cvt_pk_bf16_f32 v173, v167, v40
	v_lshl_add_u64 v[40:41], v[16:17], 0, s[58:59]
	v_lshl_add_u64 v[168:169], v[40:41], 0, v[20:21]
	global_store_dwordx4 v[168:169], v[0:3], off
	v_bfe_u32 v38, v12, 16, 1
	v_add3_u32 v12, v12, v38, s78
	v_lshl_add_u64 v[0:1], v[40:41], 0, v[22:23]
	global_store_dwordx4 v[0:1], v[4:7], off
	v_lshl_add_u64 v[0:1], v[40:41], 0, v[24:25]
	global_store_dwordx4 v[0:1], v[8:11], off
	v_lshl_add_u64 v[0:1], v[40:41], 0, v[26:27]
	ds_write_b16_d16_hi v153, v12
	global_store_dwordx4 v[0:1], v[170:173], off
	s_and_saveexec_b64 s[60:61], s[4:5]
	s_cbranch_execz .LBB0_585
	v_mul_f32_e32 v0, 0x3fb8aa3b, v39
	v_exp_f32_e32 v2, v0
	s_lshl_b64 s[0:1], s[56:57], 10
	v_lshl_add_u64 v[0:1], v[18:19], 0, s[0:1]
	global_store_dword v[0:1], v2, off

; #define LAS __attribute__((address_space(3)))
; DI unsigned lds_addr_of(const void* p) { return (unsigned)(size_t)p; }
; __device__ void phase_scan(const Params& p, unsigned char* shm) {
;     const int tid = threadIdx.x, wid = __builtin_amdgcn_readfirstlane(tid >> 6), lane = tid & 63, fr = lane & 15, fq = lane >> 4;
;     const int dirw = wid >> 2, wq = wid & 3;
;     LAS unsigned char* lds = (LAS unsigned char*)shm;
;     const unsigned char* qimg = p.ws + OFF_QIMG; const unsigned char* kimg = p.ws + OFF_KIMG; const unsigned char* aimg = p.ws + OFF_AIMG;
;     const float* dg = (const float*)(p.ws + OFF_E12); const bf16_t* Vg = (const bf16_t*)(p.ws + OFF_VB); bf16_t* O = (bf16_t*)(p.ws + OFF_O);
;     const unsigned sbase = lds_addr_of(shm);
;     constexpr int L_QA = 0, L_QB = 32768, L_KA = 65536, L_KB = 98304, L_V = 131072, L_D = 147456, L_A = 149504;
;     ...
; #pragma unroll
;                     for (int k2 = 0; k2 < 2; ++k2) {
;                         u32x4 w = *(const LAS u32x4*)(lds + L_A + (16 * mt + fr) * 128 + (((4 * k2 + fq) ^ ((fr >> 1) & 7)) * 16));
;                         const int i = 16 * mt + fr;
; #pragma unroll
;                         for (int e = 0; e < 4; ++e) { const int d = i - (32 * k2 + 8 * fq + 2 * e);
;                             unsigned mk = d >= 1 ? 0xffffffffu : (d == 0 ? 0x0000ffffu : 0u); if (dirw) mk = ~mk; w[e] &= mk; }
.LBB0_677:
	s_cmpk_lg_i32 s30, 0x100
	s_cselect_b64 s[0:1], -1, 0
	s_cmpk_lt_u32 s2, 0xc0
	s_cselect_b64 s[4:5], -1, 0
	s_or_b64 s[0:1], s[4:5], s[0:1]
	v_and_b32_e32 v138, 15, v136
	v_lshlrev_b32_e32 v137, 2, v136
	v_lshrrev_b32_e32 v134, 1, v136
	s_mov_b64 s[4:5], -1
	s_and_b64 vcc, exec, s[0:1]
	s_cbranch_vccz .LBB0_702
	v_writelane_b32 v246, s94, 0
	s_cmpk_gt_i32 s2, 0xbf
	v_readfirstlane_b32 s0, v136
	v_writelane_b32 v246, s95, 1
	v_writelane_b32 v246, s92, 2
	v_writelane_b32 v246, s90, 3
	s_nop 1
	v_writelane_b32 v246, s91, 4
	s_cbranch_scc1 .LBB0_701
	s_lshr_b32 s98, s0, 6
	v_bfe_u32 v6, v136, 4, 2
	v_lshlrev_b32_e32 v2, 3, v6
	v_mov_b32_e32 v15, 0xffff
	v_cmp_eq_u32_e32 vcc, v138, v2
	v_or_b32_e32 v17, 2, v2
	v_or_b32_e32 v19, 4, v2
	v_cndmask_b32_e32 v16, 0, v15, vcc
	v_cmp_le_u32_e32 vcc, v138, v2
	v_or_b32_e32 v21, 6, v2
	v_xor_b32_e32 v10, v6, v138
	v_cndmask_b32_e32 v16, -1, v16, vcc
	v_cmp_eq_u32_e32 vcc, v138, v17
	v_lshrrev_b32_e32 v3, 2, v138
	v_lshlrev_b32_e32 v135, 4, v10
	v_cndmask_b32_e32 v18, 0, v15, vcc
	v_cmp_le_u32_e32 vcc, v138, v17
	v_or_b32_e32 v10, 16, v138
	v_mov_b32_e32 v89, 0
	v_cndmask_b32_e32 v18, -1, v18, vcc
	v_cmp_eq_u32_e32 vcc, v138, v19
	v_or_b32_e32 v3, v2, v3
	v_lshlrev_b32_e32 v8, 7, v3
	v_cndmask_b32_e32 v20, 0, v15, vcc
	v_cmp_le_u32_e32 vcc, v138, v19
	v_mov_b32_e32 v3, v89
	v_lshl_add_u64 v[4:5], s[26:27], 0, v[2:3]
	v_cndmask_b32_e32 v20, -1, v20, vcc
	v_cmp_eq_u32_e32 vcc, v138, v21
	v_or_b32_e32 v23, 32, v2
	v_or_b32_e32 v24, 34, v2
	v_cndmask_b32_e32 v22, 0, v15, vcc
	v_cmp_le_u32_e32 vcc, v138, v21
	v_or_b32_e32 v25, 36, v2
	v_or_b32_e32 v26, 38, v2
	v_cndmask_b32_e32 v22, -1, v22, vcc
	v_cmp_eq_u32_e32 vcc, v10, v2
	v_or_b32_e32 v11, 32, v138
	s_add_u32 s18, s26, 0x32000000
	v_cndmask_b32_e32 v27, 0, v15, vcc
	v_cmp_le_u32_e32 vcc, v10, v2
	v_or_b32_e32 v12, 48, v138
	s_addc_u32 s19, s27, 0
	v_cndmask_b32_e32 v2, -1, v27, vcc
	v_cmp_eq_u32_e32 vcc, v10, v17
	s_add_u32 s20, s26, 0x28000000
	s_addc_u32 s21, s27, 0
	v_cndmask_b32_e32 v27, 0, v15, vcc
	v_cmp_le_u32_e32 vcc, v10, v17
	v_lshlrev_b32_e32 v1, 4, v138
	s_cmp_lg_u32 0, -1
	v_cndmask_b32_e32 v17, -1, v27, vcc
	v_cmp_eq_u32_e32 vcc, v10, v19
	s_waitcnt lgkmcnt(0)
; #define LAS __attribute__((address_space(3)))
; DI unsigned lds_addr_of(const void* p) { return (unsigned)(size_t)p; }
; __device__ void phase_scan(const Params& p, unsigned char* shm) {
;     ...
;     const unsigned char* qimg = p.ws + OFF_QIMG; const unsigned char* kimg = p.ws + OFF_KIMG; const unsigned char* aimg = p.ws + OFF_AIMG;
;     const float* dg = (const float*)(p.ws + OFF_E12); const bf16_t* Vg = (const bf16_t*)(p.ws + OFF_VB); bf16_t* O = (bf16_t*)(p.ws + OFF_O);
;     const unsigned sbase = lds_addr_of(shm);
;     constexpr int L_QA = 0, L_QB = 32768, L_KA = 65536, L_KB = 98304, L_V = 131072, L_D = 147456, L_A = 149504;
;     ...
;     for (int item = blockIdx.x; item < 192; item += gridDim.x) {
;         const int xcd = item & 7, idx = item >> 3; int grp, slice;
;         if (idx < 16) { grp = xcd; slice = idx; } else { grp = 8 + (xcd >> 1); slice = (xcd & 1) * 8 + (idx - 16); }
;         int seq, h; if (grp < 8) { seq = 1 + (grp >> 2); h = grp & 3; } else { seq = 0; h = grp - 8; }
;         const int chunk0 = seq == 0 ? 0 : (seq == 1 ? 128 : 384), N = seq == 0 ? 128 : 256;
;         const int colbase = h * 1024 + slice * 64;
;         f32x4 S[16];
; #pragma unroll
;         for (int i = 0; i < 16; ++i) S[i] = (f32x4){0.f, 0.f, 0.f, 0.f};
;     ...
;                         u32x4 w = *(const LAS u32x4*)(lds + L_A + (16 * mt + fr) * 128 + (((4 * k2 + fq) ^ ((fr >> 1) & 7)) * 16));
;                         const int i = 16 * mt + fr;
; #pragma unroll
;                         for (int e = 0; e < 4; ++e) { const int d = i - (32 * k2 + 8 * fq + 2 * e);
;                             unsigned mk = d >= 1 ? 0xffffffffu : (d == 0 ? 0x0000ffffu : 0u); if (dirw) mk = ~mk; w[e] &= mk; }
	v_bitop3_b32 v13, v6, v138, 4 bitop3:0x36
	v_lshl_or_b32 v7, v6, 9, v1
	v_cndmask_b32_e32 v27, 0, v15, vcc
	v_cmp_le_u32_e32 vcc, v10, v19
	v_lshlrev_b32_e32 v1, 4, v136
	s_cselect_b32 s1, 0, 0
	v_cndmask_b32_e32 v19, -1, v27, vcc
	v_cmp_eq_u32_e32 vcc, v10, v21
	s_lshr_b32 s16, s0, 8
	v_and_b32_e32 v3, 7, v134
	v_cndmask_b32_e32 v27, 0, v15, vcc
	v_cmp_le_u32_e32 vcc, v10, v21
	v_lshlrev_b32_e32 v139, 4, v13
	v_bitop3_b32 v13, v6, v138, 8 bitop3:0x36
	v_cndmask_b32_e32 v21, -1, v27, vcc
	v_cmp_eq_u32_e32 vcc, v11, v24
	v_and_b32_e32 v0, 63, v136
	v_and_b32_e32 v88, 0x70, v1
	v_cndmask_b32_e32 v27, 0, v15, vcc
	v_cmp_le_u32_e32 vcc, v11, v24
	s_lshl_b32 s3, s16, 13
	v_lshlrev_b32_e32 v140, 4, v13
	v_cndmask_b32_e32 v27, -1, v27, vcc
	v_cmp_eq_u32_e32 vcc, v11, v25
	v_bitop3_b32 v13, v6, v138, 12 bitop3:0x36
	v_bitop3_b32 v14, v6, v134, 7 bitop3:0x78
	v_cndmask_b32_e32 v28, 0, v15, vcc
	v_cmp_le_u32_e32 vcc, v11, v25
	v_bitop3_b32 v3, v6, v3, 4 bitop3:0x36
	s_lshr_b32 s22, s0, 6
	v_cndmask_b32_e32 v28, -1, v28, vcc
	v_cmp_eq_u32_e32 vcc, v11, v26
	v_lshl_add_u64 v[90:91], s[26:27], 0, v[88:89]
	v_lshlrev_b32_e32 v88, 4, v0
	v_cndmask_b32_e32 v29, 0, v15, vcc
	v_cmp_le_u32_e32 vcc, v11, v26
	s_add_i32 s1, s1, s3
	v_lshlrev_b32_e32 v141, 4, v13
	v_cndmask_b32_e32 v29, -1, v29, vcc
	v_cmp_eq_u32_e32 vcc, v12, v23
	v_lshlrev_b32_e32 v13, 7, v138
	v_lshlrev_b32_e32 v142, 4, v14
	v_cndmask_b32_e32 v30, 0, v15, vcc
	v_cmp_le_u32_e32 vcc, v12, v23
	v_lshlrev_b32_e32 v143, 4, v3
	v_lshlrev_b32_e32 v3, 7, v10
	v_cndmask_b32_e32 v23, -1, v30, vcc
	v_cmp_eq_u32_e32 vcc, v12, v24
	v_lshlrev_b32_e32 v6, 7, v11
	v_lshlrev_b32_e32 v14, 7, v12
	v_cndmask_b32_e32 v30, 0, v15, vcc
	v_cmp_le_u32_e32 vcc, v12, v24
	s_add_i32 s3, 0, 0x24800
	s_lshl_b32 s10, s22, 10
	v_cndmask_b32_e32 v24, -1, v30, vcc
	v_cmp_eq_u32_e32 vcc, v12, v25
	v_lshl_add_u64 v[0:1], s[26:27], 0, v[88:89]
	s_mov_b64 s[4:5], 0x3e800000
	v_cndmask_b32_e32 v30, 0, v15, vcc
	v_cmp_le_u32_e32 vcc, v12, v25
	v_add_u32_e32 v144, s3, v13
	v_add_u32_e32 v145, s3, v3
	v_cndmask_b32_e32 v25, -1, v30, vcc
	v_cmp_eq_u32_e32 vcc, v12, v26
	v_add_u32_e32 v146, s3, v6
	v_add_u32_e32 v147, s3, v14
	v_cndmask_b32_e32 v15, 0, v15, vcc
	v_cmp_le_u32_e32 vcc, v12, v26
	s_movk_i32 s3, 0xffc0
	v_mov_b32_e32 v26, s0
	s_cmpk_gt_u32 s0, 0xff
	v_lshl_add_u64 v[92:93], v[0:1], 0, s[4:5]
	v_bfi_b32 v26, s3, v26, v136
	s_cselect_b64 s[4:5], -1, 0
	s_bfe_u32 s3, s0, 0x10006
	s_mov_b32 s9, 0
	s_cmp_eq_u32 s3, 0
	s_cselect_b64 s[12:13], -1, 0
	s_movk_i32 s100, 0x2000
	s_cselect_b32 s100, s100, 0xffffe000
	s_cselect_b32 s101, 0, -1
	s_mov_b32 s11, s9
	s_lshr_b32 s8, s0, 2
	v_lshl_add_u64 v[0:1], v[0:1], 0, s[10:11]
	s_mov_b64 s[14:15], 0x3c000000
	s_and_b32 s8, s8, 48
	v_lshl_add_u64 v[94:95], v[0:1], 0, s[14:15]
	v_and_or_b32 v0, v137, 12, s8
	v_lshlrev_b32_e32 v0, 1, v0
	s_add_i32 s1, s1, 0x20000
	s_lshl_b32 s8, s8, 1
	v_add3_u32 v149, s1, v8, v0
	v_lshl_add_u64 v[0:1], v[4:5], 0, s[8:9]
	s_lshl_b32 s8, s16, 10
	s_lshl_b32 s1, s16, 14
	s_add_i32 s8, s8, 0
	s_add_i32 s25, 0, 0x10000
	s_add_i32 s35, 0, 0x18000
	s_lshl_b32 s23, s3, 10
	s_add_i32 s24, s1, 0
	s_add_i32 s8, s8, 0x24000
	s_add_i32 s34, s25, s1
	s_add_i32 s1, s35, s1
	s_lshr_b32 s11, s0, 10
	s_bfe_u32 s16, s0, 0x40006
	s_mov_b64 s[14:15], 0x14000000
	s_cmpk_lt_u32 s0, 0x400
	v_lshl_add_u64 v[96:97], v[0:1], 0, s[14:15]
	s_cselect_b64 s[14:15], -1, 0
	s_lshl_b32 s36, s11, 14
	s_add_i32 s37, s22, 8
	s_add_i32 s73, s36, 0
	s_lshl_b32 s38, s16, 10
	s_lshr_b32 s62, s37, 4
	s_and_b32 s39, s37, 15
	s_cmpk_lt_u32 s0, 0x200
	v_lshl_or_b32 v0, s16, 11, v7
	v_mov_b32_e32 v1, v89
	s_cselect_b64 s[16:17], -1, 0
	s_add_i32 s40, s22, 16
	s_add_i32 s22, s22, 24
	v_lshl_add_u64 v[98:99], s[20:21], 0, v[0:1]
	v_lshl_or_b32 v0, s39, 11, v7
	s_and_b32 s41, s22, 15
	v_lshl_add_u64 v[100:101], s[20:21], 0, v[0:1]
	v_lshl_or_b32 v0, s41, 11, v7
	v_lshl_add_u64 v[102:103], s[20:21], 0, v[0:1]
	s_lshl_b32 s21, s37, 10
	s_lshr_b32 s63, s40, 4
	s_lshr_b32 s64, s22, 4
	s_and_b32 s44, s10, 0x3c00
	s_and_b32 s45, s21, 0x3c00
	s_lshl_b32 s21, s22, 10
	s_lshl_b32 s0, s62, 14
	s_lshl_b32 s40, s63, 14
	s_lshl_b32 s20, s64, 14
	v_or_b32_e32 v0, s44, v88
	s_and_b32 s52, s21, 0x3c00
	v_and_b32_e32 v9, 48, v136
	v_cndmask_b32_e32 v15, -1, v15, vcc
	v_cndmask_b32_e64 v4, 0, -1, s[4:5]
	s_add_i32 s74, s0, 0
	s_lshl_b32 s39, s39, 10
	s_add_i32 s75, s40, 0
	s_add_i32 s76, s20, 0
	s_lshl_b32 s41, s41, 10
	v_lshl_add_u64 v[104:105], s[18:19], 0, v[0:1]
	s_add_i32 s77, s25, s36
	v_or_b32_e32 v0, s45, v88
	s_add_i32 s78, s25, s0
	s_add_i32 s79, s25, s40
	v_or_b32_e32 v88, s52, v88
	s_add_i32 s80, s25, s20
	s_add_i32 s69, s35, s36
	s_add_i32 s70, s35, s0
	s_add_i32 s71, s35, s40
	s_add_i32 s72, s35, s20
	s_add_i32 s68, s23, 0
	v_ashrrev_i32_e32 v148, 3, v26
	v_lshl_add_u64 v[106:107], s[18:19], 0, v[0:1]
	v_lshl_add_u64 v[108:109], s[18:19], 0, v[88:89]
	v_lshl_add_u32 v88, v138, 8, s24
	v_lshl_add_u32 v150, v10, 8, s24
	v_lshl_add_u32 v151, v11, 8, s24
	v_lshl_add_u32 v152, v12, 8, s24
	v_add_u32_e32 v153, s34, v13
	v_add_u32_e32 v154, s34, v3
	v_add_u32_e32 v155, s34, v6
	v_add_u32_e32 v156, s34, v14
	v_xor_b32_e32 v157, v16, v4
	v_xor_b32_e32 v158, v18, v4
	v_xor_b32_e32 v159, v20, v4
	v_xor_b32_e32 v160, v22, v4
	v_xor_b32_e32 v161, v2, v4
	v_xor_b32_e32 v162, v17, v4
	v_xor_b32_e32 v163, v19, v4
	v_xor_b32_e32 v164, v21, v4
	v_xor_b32_e32 v165, v27, v4
	v_xor_b32_e32 v166, v28, v4
	v_xor_b32_e32 v167, v29, v4
	v_xor_b32_e32 v168, v23, v4
	v_xor_b32_e32 v169, v24, v4
	v_xor_b32_e32 v170, v25, v4
	v_xor_b32_e32 v171, v15, v4
	v_add_u32_e32 v172, s1, v13
	v_add_u32_e32 v173, s1, v3
	v_add_u32_e32 v174, s1, v6
	v_add_u32_e32 v175, s1, v14
	s_add_i32 s65, s64, -8
	s_add_i32 s66, s63, -8
	s_movk_i32 s67, 0x180
	s_mov_b64 s[18:19], 0x100
	s_add_i32 s68, s68, 0x24000
	s_add_i32 s69, s69, s44
	s_add_i32 s70, s70, s45
	s_add_i32 s71, s71, s44
	s_add_i32 s72, s72, s52
	s_mov_b64 s[20:21], 0x4000
	s_mov_b64 s[22:23], 0x60000
	s_mov_b64 s[24:25], 0x40000
	s_mov_b64 s[36:37], 0x20000
	s_add_i32 s73, s73, s38
	s_add_i32 s74, s74, s39
	s_add_i32 s75, s75, s38
	s_add_i32 s76, s76, s41
	s_add_i32 s77, s77, s44
	s_add_i32 s78, s78, s45
	s_add_i32 s79, s79, s44
	s_add_i32 s80, s80, s52
	v_add_u32_e32 v176, s8, v9
	s_mov_b32 s81, s2
	s_branch .LBB0_681

; #define SC_WV(n) asm volatile("s_waitcnt vmcnt(" #n ") lgkmcnt(0)" ::: "memory")
; #define SC_BAR __builtin_amdgcn_s_barrier()
; #define SC_LD_D(m_) do { const int _dir = wid & 1; \
;             __builtin_amdgcn_global_load_lds((const unsigned*)(dg + (size_t)SC_UNIT(_dir, m_) * 256 + lane * 4), (LAS unsigned*)(lds + L_D + _dir * 1024), 16, 0, 0); } while (0)
; #define SC_LD_A(m_) do { __builtin_amdgcn_global_load_lds((const unsigned*)(aimg + ((size_t)(chunk0 + (m_)) * 4 + h) * 8192 + wid * 1024 + lane * 16), (LAS unsigned*)(lds + L_A + wid * 1024), 16, 0, 0); } while (0)
; __device__ void phase_scan(const Params& p, unsigned char* shm) {
;     ...
;     for (int item = blockIdx.x; item < 192; item += gridDim.x) {
;         const int xcd = item & 7, idx = item >> 3; int grp, slice;
;         if (idx < 16) { grp = xcd; slice = idx; } else { grp = 8 + (xcd >> 1); slice = (xcd & 1) * 8 + (idx - 16); }
;         int seq, h; if (grp < 8) { seq = 1 + (grp >> 2); h = grp & 3; } else { seq = 0; h = grp - 8; }
;         const int chunk0 = seq == 0 ? 0 : (seq == 1 ? 128 : 384), N = seq == 0 ? 128 : 256;
;         const int colbase = h * 1024 + slice * 64;
;         f32x4 S[16];
; #pragma unroll
;         for (int i = 0; i < 16; ++i) S[i] = (f32x4){0.f, 0.f, 0.f, 0.f};
;     ...
;         SC_LD_QH(0, 0); SC_LD_V(0); SC_LD_QH(1, 0); SC_LD_KH(0, 0);
;         for (int n = 0; n < N; ++n) {
;             const int c = dirw ? (N - 1 - n) : n, row0 = (chunk0 + c) * 64, m = (n + 1 < N) ? n + 1 : n;
;             const bool first = n < (N >> 1);
;             if (n == (N >> 1)) SC_WV(0); else SC_WV(8);
;             SC_BAR;
;             SC_LD_D(n); SC_LD_KH(1, n); SC_LD_A(n);
.LBB0_681:
	s_ashr_i32 s0, s81, 3
	s_and_b32 s1, s81, 3
	s_cmp_lt_i32 s0, 16
	s_movk_i32 s8, 0x100
	s_cselect_b32 s82, s8, 0x80
	s_bfe_u32 s8, s81, 0x20001
	s_cmp_lt_i32 s0, 16
	s_cselect_b32 s34, s1, s8
	s_and_b32 s1, s81, 7
	s_cmp_lt_u32 s1, 4
	s_cselect_b32 s1, 0x80, s67
	s_cmp_lt_i32 s0, 16
	s_cselect_b32 s83, s1, 0
	s_lshl_b32 s1, s81, 3
	s_and_b32 s1, s1, 8
	s_add_i32 s1, s0, s1
	s_add_i32 s1, s1, -16
	s_cmp_lt_i32 s0, 16
	s_cselect_b32 s0, s0, s1
	s_lshl_b32 s35, s0, 6
	s_lshl_b32 s52, s34, 10
	s_add_i32 s8, s82, 0x1fffffff
	s_lshl_b32 s54, s34, 1
	s_and_b64 s[0:1], s[14:15], exec
	s_cselect_b32 s0, 0, s8
	s_add_i32 s0, s0, s83
	s_lshl_b32 s0, s0, 3
	s_add_i32 s84, s54, s11
	s_add_i32 s0, s0, s84
	s_ashr_i32 s1, s0, 31
	s_lshl_b64 s[0:1], s[0:1], 15
	s_and_b64 s[38:39], s[16:17], exec
	s_cselect_b32 s38, 0, s8
	s_add_i32 s38, s38, s83
	s_lshl_b32 s38, s38, 3
	s_add_i32 s85, s54, s62
	s_add_i32 s38, s38, s85
	s_add_i32 s8, s8, s83
	s_ashr_i32 s39, s38, 31
	s_lshl_b32 s44, s8, 3
	s_add_i32 s86, s54, s63
	s_add_i32 s99, s82, -1
	s_and_b64 vcc, s[12:13], exec
	s_cselect_b32 s99, 0, s99
	s_add_i32 s99, s99, s83
	s_lshl_b32 s99, s99, 3
	s_or_b32 s99, s99, s54
	s_or_b32 s99, s99, s3
	s_mov_b32 vcc_lo, s99
	s_mov_b32 vcc_hi, 0
	s_lshl_b64 vcc, vcc, 10
	v_lshl_add_u64 v[0:1], v[92:93], 0, vcc
	s_mov_b32 m0, s68
	s_cmp_gt_u32 s98, 1
	s_cbranch_scc1 .Lskip_d0
	global_load_lds_dwordx4 v[0:1], off
.Lskip_d0:
	s_xor_b32 s68, s68, 0x3000
	s_mov_b32 m0, s73
	v_lshl_add_u64 v[0:1], v[98:99], 0, s[0:1]
	s_lshl_b64 s[38:39], s[38:39], 15
	s_add_i32 s8, s44, s86
	s_add_i32 s87, s54, s64
	s_add_i32 s52, s35, s52
	global_load_lds_dwordx4 v[0:1], off
	v_lshl_add_u64 v[2:3], v[100:101], 0, s[38:39]
	s_mov_b32 m0, s74
	s_lshl_b64 s[40:41], s[8:9], 15
	s_add_i32 s8, s44, s87
	s_ashr_i32 s53, s52, 31
	v_lshl_add_u32 v8, s83, 6, v148
	global_load_lds_dwordx4 v[2:3], off
	v_lshl_add_u64 v[4:5], v[98:99], 0, s[40:41]
	s_mov_b32 m0, s75
	s_lshl_b64 s[44:45], s[8:9], 15
	s_lshl_b64 s[52:53], s[52:53], 1
	v_ashrrev_i32_e32 v9, 31, v8
	s_add_i32 s89, s10, 0
	global_load_lds_dwordx4 v[4:5], off
	v_lshl_add_u64 v[6:7], v[102:103], 0, s[44:45]
	s_mov_b32 m0, s76
	s_add_i32 s88, s82, -1
	v_lshl_add_u64 v[118:119], v[90:91], 0, s[52:53]
	v_lshlrev_b64 v[8:9], 13, v[8:9]
	s_add_i32 s91, s89, 0x20000
	global_load_lds_dwordx4 v[6:7], off
	v_lshl_add_u64 v[8:9], v[118:119], 0, v[8:9]
	s_mov_b32 m0, s91
	s_add_i32 s8, s88, s83
	global_load_lds_dwordx4 v[8:9], off
	v_lshl_add_u32 v8, s8, 6, v148
	v_ashrrev_i32_e32 v9, 31, v8
	v_lshlrev_b64 v[8:9], 13, v[8:9]
	s_add_i32 s92, s89, 0x22000
	v_lshl_add_u64 v[8:9], v[118:119], 0, v[8:9]
	s_mov_b32 m0, s92
	s_add_i32 s93, s73, 0x8000
	global_load_lds_dwordx4 v[8:9], off
	v_lshl_add_u64 v[0:1], v[0:1], 0, s[18:19]
	s_mov_b32 m0, s93
	s_add_i32 s94, s74, 0x8000
	global_load_lds_dwordx4 v[0:1], off
	v_lshl_add_u64 v[0:1], v[2:3], 0, s[18:19]
	s_mov_b32 m0, s94
	s_add_i32 s95, s75, 0x8000
	global_load_lds_dwordx4 v[0:1], off
	v_lshl_add_u64 v[0:1], v[4:5], 0, s[18:19]
	s_mov_b32 m0, s95
	s_add_i32 s96, s76, 0x8000
	global_load_lds_dwordx4 v[0:1], off
	v_lshl_add_u64 v[0:1], v[6:7], 0, s[18:19]
	s_mov_b32 m0, s96
	s_lshl_b32 s8, s34, 13
	global_load_lds_dwordx4 v[0:1], off
	v_lshl_add_u64 v[0:1], v[104:105], 0, s[0:1]
	s_mov_b32 m0, s77
	s_add_i32 s0, s83, s82
	global_load_lds_dwordx4 v[0:1], off
	v_lshl_add_u64 v[0:1], v[106:107], 0, s[38:39]
	s_mov_b32 m0, s78
	s_lshl_b32 s0, s0, 3
	global_load_lds_dwordx4 v[0:1], off
	v_lshl_add_u64 v[0:1], v[104:105], 0, s[40:41]
	s_mov_b32 m0, s79
	s_add_i32 s1, s65, s0
	global_load_lds_dwordx4 v[0:1], off
	v_lshl_add_u64 v[0:1], v[108:109], 0, s[44:45]
	s_mov_b32 m0, s80
	s_add_i32 s0, s66, s0
	global_load_lds_dwordx4 v[0:1], off
	s_lshr_b32 s97, s82, 1
	v_lshl_add_u64 v[120:121], v[94:95], 0, s[8:9]
	v_lshl_add_u64 v[122:123], v[96:97], 0, s[52:53]
	s_or_b32 s90, s54, s3
	s_add_i32 s38, s1, s54
	s_add_i32 s40, s0, s54
	s_mov_b32 s1, s9
	v_mov_b32_e32 v0, 0
	v_mov_b32_e32 v1, v89
	v_mov_b32_e32 v2, v89
	v_mov_b32_e32 v3, v89
	v_mov_b32_e32 v4, 0
	v_mov_b32_e32 v5, v89
	v_mov_b32_e32 v6, v89
	v_mov_b32_e32 v7, v89
	v_mov_b32_e32 v8, 0
	v_mov_b32_e32 v9, v89
	v_mov_b32_e32 v10, v89
	v_mov_b32_e32 v11, v89
	v_mov_b32_e32 v12, 0
	v_mov_b32_e32 v13, v89
	v_mov_b32_e32 v14, v89
	v_mov_b32_e32 v15, v89
	v_mov_b32_e32 v16, 0
	v_mov_b32_e32 v17, v89
	v_mov_b32_e32 v18, v89
	v_mov_b32_e32 v19, v89
	v_mov_b32_e32 v20, 0
	v_mov_b32_e32 v21, v89
	v_mov_b32_e32 v22, v89
	v_mov_b32_e32 v23, v89
	v_mov_b32_e32 v24, 0
	v_mov_b32_e32 v25, v89
	v_mov_b32_e32 v26, v89
	v_mov_b32_e32 v27, v89
	v_mov_b32_e32 v28, 0
	v_mov_b32_e32 v29, v89
	v_mov_b32_e32 v30, v89
	v_mov_b32_e32 v31, v89
	v_mov_b32_e32 v32, 0
	v_mov_b32_e32 v33, v89
	v_mov_b32_e32 v34, v89
	v_mov_b32_e32 v35, v89
	v_mov_b32_e32 v36, 0
	v_mov_b32_e32 v37, v89
	v_mov_b32_e32 v38, v89
	v_mov_b32_e32 v39, v89
	v_mov_b32_e32 v40, 0
	v_mov_b32_e32 v41, v89
	v_mov_b32_e32 v42, v89
	v_mov_b32_e32 v43, v89
	v_mov_b32_e32 v44, 0
	v_mov_b32_e32 v45, v89
	v_mov_b32_e32 v46, v89
	v_mov_b32_e32 v47, v89
	v_mov_b32_e32 v48, 0
	v_mov_b32_e32 v49, v89
	v_mov_b32_e32 v50, v89
	v_mov_b32_e32 v51, v89
	v_mov_b32_e32 v52, 0
	v_mov_b32_e32 v53, v89
	v_mov_b32_e32 v54, v89
	v_mov_b32_e32 v55, v89
	v_mov_b32_e32 v56, 0
	v_mov_b32_e32 v57, v89
	v_mov_b32_e32 v58, v89
	v_mov_b32_e32 v59, v89
	v_mov_b32_e32 v60, 0
	v_mov_b32_e32 v61, v89
	v_mov_b32_e32 v62, v89
	v_mov_b32_e32 v63, v89
	s_waitcnt vmcnt(4)
	s_cmp_lg_u32 s1, s97
	s_mov_b64 s[44:45], -1
	s_cbranch_scc0 .LBB0_683

; #define SC_WV(n) asm volatile("s_waitcnt vmcnt(" #n ") lgkmcnt(0)" ::: "memory")
; #define SC_BAR __builtin_amdgcn_s_barrier()
; #define SC_LD_D(m_) do { const int _dir = wid & 1; \
;             __builtin_amdgcn_global_load_lds((const unsigned*)(dg + (size_t)SC_UNIT(_dir, m_) * 256 + lane * 4), (LAS unsigned*)(lds + L_D + _dir * 1024), 16, 0, 0); } while (0)
; #define SC_LD_A(m_) do { __builtin_amdgcn_global_load_lds((const unsigned*)(aimg + ((size_t)(chunk0 + (m_)) * 4 + h) * 8192 + wid * 1024 + lane * 16), (LAS unsigned*)(lds + L_A + wid * 1024), 16, 0, 0); } while (0)
; __device__ void phase_scan(const Params& p, unsigned char* shm) {
;     ...
;         for (int n = 0; n < N; ++n) {
;             const int c = dirw ? (N - 1 - n) : n, row0 = (chunk0 + c) * 64, m = (n + 1 < N) ? n + 1 : n;
;             const bool first = n < (N >> 1);
;             if (n == (N >> 1)) SC_WV(0); else SC_WV(8);
;             SC_BAR;
;             SC_LD_D(n); SC_LD_KH(1, n); SC_LD_A(n);
;             bf16x8 vb[2];
;             { const unsigned ad = sbase + (unsigned)L_V + (unsigned)(dirw * 8192 + (8 * fq + (fr >> 2)) * 128 + (wq * 16 + (fr & 3) * 4) * 2);
;               s16x4 r0, r1, r2, r3;
;               asm volatile("ds_read_b64_tr_b16 %0, %4\n\tds_read_b64_tr_b16 %1, %4 offset:512\n\tds_read_b64_tr_b16 %2, %4 offset:4096\n\tds_read_b64_tr_b16 %3, %4 offset:4608\n\ts_waitcnt lgkmcnt(0)"
;                            : "=&v"(r0), "=&v"(r1), "=&v"(r2), "=&v"(r3) : "v"(ad) : "memory");
;               vb[0] = __builtin_shufflevector(r0, r1, 0, 1, 2, 3, 4, 5, 6, 7); vb[1] = __builtin_shufflevector(r2, r3, 0, 1, 2, 3, 4, 5, 6, 7); }
;             f32x4 o[4];
; #pragma unroll
;             for (int mt = 0; mt < 4; ++mt) o[mt] = (f32x4){0.f, 0.f, 0.f, 0.f};
;             SC_OINTER(L_QA, 0);
;             SC_WV(10); SC_BAR;
;             SC_LD_QH(0, m); SC_LD_V(m);
;             bf16_t* op = O + (size_t)(row0 + fr) * EI + colbase + wq * 16 + 4 * fq;
;             u32x2 opv[4];
;             asm volatile("" ::: "memory");
;             if (!first) {
; #pragma unroll
;                 for (int mt = 0; mt < 4; ++mt) asm volatile("global_load_dwordx2 %0, %1, off" : "=&v"(opv[mt]) : "v"(op + (size_t)(16 * mt) * EI) : "memory");
;             }
.LBB0_685:
	s_and_b64 s[44:45], s[4:5], exec
	s_cselect_b32 s60, s88, s1
	s_add_i32 s60, s60, s83
	s_add_i32 s0, s1, 1
	s_cmp_lt_u32 s0, s82
	s_cselect_b32 s61, s0, s1
	s_cmp_ge_u32 s1, s97
	s_cselect_b64 s[58:59], -1, 0
	s_and_b64 s[44:45], s[12:13], exec
	s_cselect_b32 s8, s1, s88
	s_add_i32 s8, s8, s83
	s_lshl_b32 s8, s8, 3
	s_or_b32 s44, s8, s90
	s_ashr_i32 s45, s44, 31
	s_lshl_b64 s[44:45], s[44:45], 10
	s_and_b64 s[52:53], s[14:15], exec
	s_cselect_b32 s8, s1, s88
	s_add_i32 s8, s8, s83
	s_lshl_b32 s8, s8, 3
	s_add_i32 s52, s8, s84
	s_ashr_i32 s53, s52, 31
	s_lshl_b64 s[52:53], s[52:53], 15
	s_and_b64 s[54:55], s[16:17], exec
	s_cselect_b32 s8, s1, s88
	s_add_i32 s8, s8, s83
	s_lshl_b32 s8, s8, 3
	s_mov_b32 m0, s68
	s_add_i32 s54, s8, s85
	v_lshl_add_u64 v[64:65], v[92:93], 0, s[44:45]
	v_lshl_add_u64 v[64:65], v[64:65], 0, s[100:101]
	s_ashr_i32 s55, s54, 31
	s_barrier
	s_cmp_gt_u32 s98, 1
	s_cbranch_scc1 .Lskip_dload
	global_load_lds_dwordx4 v[64:65], off
.Lskip_dload:
	s_xor_b32 s68, s68, 0x3000
	v_lshl_add_u64 v[64:65], v[104:105], 0, s[52:53]
	s_lshl_b64 s[54:55], s[54:55], 15
	v_lshl_add_u64 v[64:65], v[64:65], 0, s[20:21]
	s_mov_b32 m0, s69
	s_ashr_i32 s41, s40, 31
	global_load_lds_dwordx4 v[64:65], off
	v_lshl_add_u64 v[64:65], v[106:107], 0, s[54:55]
	s_lshl_b64 s[56:57], s[40:41], 15
	v_lshl_add_u64 v[64:65], v[64:65], 0, s[20:21]
	s_mov_b32 m0, s70
	s_ashr_i32 s39, s38, 31
	global_load_lds_dwordx4 v[64:65], off
	v_lshl_add_u64 v[64:65], v[104:105], 0, s[56:57]
	s_lshl_b64 vcc, s[38:39], 15
	v_lshl_add_u64 v[64:65], v[64:65], 0, s[20:21]
	s_mov_b32 m0, s71
	s_add_i32 s8, s83, s1
	global_load_lds_dwordx4 v[64:65], off
	v_lshl_add_u64 v[64:65], v[108:109], 0, vcc
	s_lshl_b64 s[34:35], s[8:9], 15
	s_add_i32 s8, s89, 0x24800
	v_lshl_add_u64 v[64:65], v[64:65], 0, s[20:21]
	s_mov_b32 m0, s72
	v_add_u32_e32 v177, v88, v135
	global_load_lds_dwordx4 v[64:65], off
	v_lshl_add_u64 v[64:65], v[120:121], 0, s[34:35]
	s_mov_b32 m0, s8
	s_not_b32 s8, s61
	global_load_lds_dwordx4 v[64:65], off
	s_add_i32 s8, s82, s8
	s_and_b64 s[34:35], s[14:15], exec
	s_cselect_b32 s34, s61, s8
	s_add_i32 s34, s34, s83
	s_lshl_b32 s34, s34, 3
	s_add_i32 s34, s34, s84
	s_ashr_i32 s35, s34, 31
	s_lshl_b64 s[44:45], s[34:35], 15
	s_and_b64 s[34:35], s[16:17], exec
	s_cselect_b32 s34, s61, s8
	s_add_i32 s34, s34, s83
	s_lshl_b32 s34, s34, 3
	s_add_i32 s34, s34, s85
	s_add_i32 s8, s8, s83
	s_ashr_i32 s35, s34, 31
	s_lshl_b32 s39, s8, 3
	ds_read_b64_tr_b16 v[68:69], v149
	ds_read_b64_tr_b16 v[70:71], v149 offset:512
	ds_read_b64_tr_b16 v[64:65], v149 offset:4096
	ds_read_b64_tr_b16 v[66:67], v149 offset:4608
	s_waitcnt lgkmcnt(0)
	v_add_u32_e32 v179, v151, v135
	v_add_u32_e32 v181, v88, v139
	v_add_u32_e32 v183, v151, v139
	v_add_u32_e32 v185, v88, v140
	v_add_u32_e32 v187, v151, v140
	v_add_u32_e32 v189, v88, v141
	v_add_u32_e32 v191, v151, v141
	s_lshl_b64 s[52:53], s[34:35], 15
	s_add_i32 s34, s39, s86
	v_add_u32_e32 v178, v150, v135
	ds_read_b128 v[72:75], v177
	ds_read_b128 v[76:79], v178
	v_add_u32_e32 v180, v152, v135
	ds_read_b128 v[80:83], v179
	ds_read_b128 v[84:87], v180
	v_add_u32_e32 v182, v150, v139
	ds_read_b128 v[124:127], v181
	ds_read_b128 v[128:131], v182
	v_add_u32_e32 v184, v152, v139
	ds_read_b128 v[194:197], v183
	ds_read_b128 v[198:201], v184
	v_add_u32_e32 v186, v150, v140
	ds_read_b128 v[202:205], v185
	ds_read_b128 v[206:209], v186
	v_add_u32_e32 v188, v152, v140
	ds_read_b128 v[210:213], v187
	ds_read_b128 v[214:217], v188
	v_add_u32_e32 v190, v150, v141
	ds_read_b128 v[218:221], v189
	ds_read_b128 v[222:225], v190
	v_add_u32_e32 v192, v152, v141
	ds_read_b128 v[226:229], v191
	ds_read_b128 v[230:233], v192
	s_ashr_i32 s35, s34, 31
	s_lshl_b64 s[54:55], s[34:35], 15
	s_add_i32 s34, s39, s87
	s_ashr_i32 s35, s34, 31
	s_lshl_b64 s[56:57], s[34:35], 15
	s_add_i32 s61, s61, s83
	s_cmp_lt_u32 s1, s97
	v_cvt_pk_bf16_f32 v234, v0, v1
	v_cvt_pk_bf16_f32 v235, v2, v3
	v_cvt_pk_bf16_f32 v236, v4, v5
	v_cvt_pk_bf16_f32 v237, v6, v7
	s_waitcnt lgkmcnt(0)
	v_mfma_f32_16x16x32_bf16 v[72:75], v[234:237], v[72:75], 0
	v_mfma_f32_16x16x32_bf16 v[76:79], v[234:237], v[76:79], 0
	v_mfma_f32_16x16x32_bf16 v[80:83], v[234:237], v[80:83], 0
	v_mfma_f32_16x16x32_bf16 v[84:87], v[234:237], v[84:87], 0
	v_cvt_pk_bf16_f32 v234, v8, v9
	v_cvt_pk_bf16_f32 v235, v10, v11
	v_cvt_pk_bf16_f32 v236, v12, v13
	v_cvt_pk_bf16_f32 v237, v14, v15
	s_nop 0
	v_mfma_f32_16x16x32_bf16 v[72:75], v[234:237], v[124:127], v[72:75]
	v_cvt_pk_bf16_f32 v124, v16, v17
	v_cvt_pk_bf16_f32 v125, v18, v19
	v_cvt_pk_bf16_f32 v126, v20, v21
	v_mfma_f32_16x16x32_bf16 v[76:79], v[234:237], v[128:131], v[76:79]
	v_cvt_pk_bf16_f32 v127, v22, v23
	v_mfma_f32_16x16x32_bf16 v[80:83], v[234:237], v[194:197], v[80:83]
	v_mfma_f32_16x16x32_bf16 v[84:87], v[234:237], v[198:201], v[84:87]
	v_mfma_f32_16x16x32_bf16 v[72:75], v[124:127], v[202:205], v[72:75]
	v_mfma_f32_16x16x32_bf16 v[76:79], v[124:127], v[206:209], v[76:79]
	v_mfma_f32_16x16x32_bf16 v[80:83], v[124:127], v[210:213], v[80:83]
	v_mfma_f32_16x16x32_bf16 v[84:87], v[124:127], v[214:217], v[84:87]
	v_cvt_pk_bf16_f32 v124, v24, v25
	v_cvt_pk_bf16_f32 v125, v26, v27
	v_cvt_pk_bf16_f32 v126, v28, v29
	v_cvt_pk_bf16_f32 v127, v30, v31
	s_nop 0
	v_mfma_f32_16x16x32_bf16 v[72:75], v[124:127], v[218:221], v[72:75]
	v_mfma_f32_16x16x32_bf16 v[76:79], v[124:127], v[222:225], v[76:79]
	v_mfma_f32_16x16x32_bf16 v[80:83], v[124:127], v[226:229], v[80:83]
	v_mfma_f32_16x16x32_bf16 v[84:87], v[124:127], v[230:233], v[84:87]
	s_mov_b32 m0, s73
	v_lshl_add_u64 v[126:127], v[98:99], 0, s[44:45]
	s_waitcnt vmcnt(13) lgkmcnt(0)
	s_barrier
	global_load_lds_dwordx4 v[126:127], off
	v_lshl_add_u64 v[128:129], v[100:101], 0, s[52:53]
	s_mov_b32 m0, s74
	v_lshl_add_u32 v124, s61, 6, v148
	global_load_lds_dwordx4 v[128:129], off
	v_lshl_add_u64 v[130:131], v[98:99], 0, s[54:55]
	s_mov_b32 m0, s75
	v_ashrrev_i32_e32 v125, 31, v124
	global_load_lds_dwordx4 v[130:131], off
	v_lshl_add_u64 v[132:133], v[102:103], 0, s[56:57]
	s_mov_b32 m0, s76
	v_lshlrev_b64 v[124:125], 13, v[124:125]
	global_load_lds_dwordx4 v[132:133], off
	v_lshl_add_u64 v[124:125], v[118:119], 0, v[124:125]
	s_mov_b32 m0, s91
	s_nop 0
	global_load_lds_dwordx4 v[124:125], off
	v_lshl_add_u32 v124, s8, 6, v148
	v_ashrrev_i32_e32 v125, 31, v124
	v_lshlrev_b64 v[124:125], 13, v[124:125]
	v_lshl_add_u64 v[124:125], v[118:119], 0, v[124:125]
	s_mov_b32 m0, s92
	s_nop 0
	global_load_lds_dwordx4 v[124:125], off
	v_lshl_or_b32 v124, s60, 6, v138
	v_ashrrev_i32_e32 v125, 31, v124
	v_lshlrev_b64 v[124:125], 13, v[124:125]
	v_lshl_add_u64 v[124:125], v[122:123], 0, v[124:125]
	s_cbranch_scc1 .LBB0_687
	global_load_dwordx2 v[110:111], v[124:125], off
	v_lshl_add_u64 v[114:115], v[124:125], 0, s[36:37]
	global_load_dwordx2 v[112:113], v[114:115], off
	v_lshl_add_u64 v[116:117], v[124:125], 0, s[24:25]
	global_load_dwordx2 v[114:115], v[116:117], off
	v_lshl_add_u64 v[194:195], v[124:125], 0, s[22:23]
	global_load_dwordx2 v[116:117], v[194:195], off
; #define SC_WV(n) asm volatile("s_waitcnt vmcnt(" #n ") lgkmcnt(0)" ::: "memory")
; __device__ void phase_scan(const Params& p, unsigned char* shm) {
;     ...
;             SC_OINTER(L_QB, 1);
;             if (first) SC_WV(11); else SC_WV(15);
.LBB0_687:
	ds_read_b128 v[194:197], v177 offset:32768
	ds_read_b128 v[198:201], v178 offset:32768
	ds_read_b128 v[202:205], v179 offset:32768
	ds_read_b128 v[206:209], v180 offset:32768
	ds_read_b128 v[178:181], v181 offset:32768
	ds_read_b128 v[210:213], v182 offset:32768
	ds_read_b128 v[214:217], v183 offset:32768
	ds_read_b128 v[218:221], v184 offset:32768
	ds_read_b128 v[182:185], v185 offset:32768
	ds_read_b128 v[222:225], v186 offset:32768
	ds_read_b128 v[226:229], v187 offset:32768
	ds_read_b128 v[230:233], v188 offset:32768
	ds_read_b128 v[186:189], v189 offset:32768
	ds_read_b128 v[234:237], v190 offset:32768
	ds_read_b128 v[238:241], v191 offset:32768
	ds_read_b128 v[190:193], v192 offset:32768
	v_cvt_pk_bf16_f32 v242, v32, v33
	v_cvt_pk_bf16_f32 v243, v34, v35
	v_cvt_pk_bf16_f32 v244, v36, v37
	v_cvt_pk_bf16_f32 v245, v38, v39
	s_waitcnt lgkmcnt(0)
	v_mfma_f32_16x16x32_bf16 v[72:75], v[242:245], v[194:197], v[72:75]
	v_cvt_pk_bf16_f32 v194, v40, v41
	v_cvt_pk_bf16_f32 v195, v42, v43
	v_cvt_pk_bf16_f32 v196, v44, v45
	v_mfma_f32_16x16x32_bf16 v[76:79], v[242:245], v[198:201], v[76:79]
	v_cvt_pk_bf16_f32 v197, v46, v47
	v_mfma_f32_16x16x32_bf16 v[80:83], v[242:245], v[202:205], v[80:83]
	v_mfma_f32_16x16x32_bf16 v[84:87], v[242:245], v[206:209], v[84:87]
	v_mfma_f32_16x16x32_bf16 v[72:75], v[194:197], v[178:181], v[72:75]
	v_cvt_pk_bf16_f32 v178, v48, v49
	v_cvt_pk_bf16_f32 v179, v50, v51
	v_cvt_pk_bf16_f32 v180, v52, v53
	v_mfma_f32_16x16x32_bf16 v[76:79], v[194:197], v[210:213], v[76:79]
	v_cvt_pk_bf16_f32 v181, v54, v55
	v_mfma_f32_16x16x32_bf16 v[80:83], v[194:197], v[214:217], v[80:83]
	v_mfma_f32_16x16x32_bf16 v[84:87], v[194:197], v[218:221], v[84:87]
	v_cvt_pk_bf16_f32 v194, v56, v57
	v_cvt_pk_bf16_f32 v195, v58, v59
	v_cvt_pk_bf16_f32 v196, v60, v61
	v_mfma_f32_16x16x32_bf16 v[72:75], v[178:181], v[182:185], v[72:75]
	v_cvt_pk_bf16_f32 v197, v62, v63
	v_mfma_f32_16x16x32_bf16 v[76:79], v[178:181], v[222:225], v[76:79]
	v_mfma_f32_16x16x32_bf16 v[182:185], v[178:181], v[226:229], v[80:83]
	v_mfma_f32_16x16x32_bf16 v[178:181], v[178:181], v[230:233], v[84:87]
	v_mfma_f32_16x16x32_bf16 v[84:87], v[194:197], v[186:189], v[72:75]
	v_mfma_f32_16x16x32_bf16 v[80:83], v[194:197], v[234:237], v[76:79]
	v_mfma_f32_16x16x32_bf16 v[76:79], v[194:197], v[238:241], v[182:185]
	v_mfma_f32_16x16x32_bf16 v[72:75], v[194:197], v[190:193], v[178:181]
	s_mov_b64 s[60:61], -1
	s_and_b64 vcc, exec, s[58:59]
	s_cbranch_vccz .LBB0_689
	s_waitcnt vmcnt(19) lgkmcnt(0)
	s_mov_b64 s[60:61], 0
.LBB0_689:
	s_andn2_b64 vcc, exec, s[60:61]
	s_cbranch_vccnz .LBB0_691
	s_waitcnt vmcnt(15) lgkmcnt(0)

; DI unsigned cvt_pk_bf16(float lo, float hi) { unsigned r; asm("v_cvt_pk_bf16_f32 %0, %1, %2" : "=v"(r) : "v"(lo), "v"(hi)); return r; }
; __device__ void phase_scan(const Params& p, unsigned char* shm) {
;     ...
;                     for (int mt = 0; mt < 4; ++mt) { u32x2 w; w.x = cvt_pk_bf16(o[mt][0], o[mt][1]); w.y = cvt_pk_bf16(o[mt][2], o[mt][3]); *(u32x2*)(op + (size_t)(16 * mt) * EI) = w; }
;                 } else {
;                     u32x2 pv[4];
;                     asm volatile("s_waitcnt vmcnt(0)\n\tv_mov_b64 %0, %4\n\tv_mov_b64 %1, %5\n\tv_mov_b64 %2, %6\n\tv_mov_b64 %3, %7"
;                                  : "=&v"(pv[0]), "=&v"(pv[1]), "=&v"(pv[2]), "=&v"(pv[3]) : "v"(opv[0]), "v"(opv[1]), "v"(opv[2]), "v"(opv[3]) : "memory");
; #pragma unroll
;                     for (int mt = 0; mt < 4; ++mt) { f32x4 v = o[mt];
;                         v[0] += bflo(pv[mt].x); v[1] += bfhi(pv[mt].x); v[2] += bflo(pv[mt].y); v[3] += bfhi(pv[mt].y);
;                         u32x2 w; w.x = cvt_pk_bf16(v[0], v[1]); w.y = cvt_pk_bf16(v[2], v[3]); *(u32x2*)(op + (size_t)(16 * mt) * EI) = w; }
;                 }
;             }
;             asm volatile("" ::: "memory");
;             SC_LD_KH(0, m);
;             SC_SUPD(L_KB, 8);
.LBB0_699:
	s_nop 4
	v_add_co_u32_e32 v72, vcc, 0x20000, v124
	s_nop 1
	v_addc_co_u32_e32 v73, vcc, 0, v125, vcc
	global_store_dwordx2 v[72:73], v[126:127], off
	v_add_co_u32_e32 v72, vcc, 0x40000, v124
	v_add_u32_e32 v132, v172, v142
	s_nop 0
	v_addc_co_u32_e32 v73, vcc, 0, v125, vcc
	global_store_dwordx2 v[72:73], v[128:129], off
	v_add_co_u32_e32 v72, vcc, 0x60000, v124
	v_add_u32_e32 v124, v173, v142
	s_nop 0
	v_addc_co_u32_e32 v73, vcc, 0, v125, vcc
	global_store_dwordx2 v[72:73], v[130:131], off
	v_add_u32_e32 v128, v173, v143
	v_add_u32_e32 v133, v172, v143
	ds_read_b128 v[72:75], v176 offset:512
	ds_read_b128 v[76:79], v176 offset:576
	ds_read_b128 v[80:83], v132
	ds_read_b128 v[84:87], v133
	ds_read_b128 v[124:127], v124
	ds_read_b128 v[128:131], v128
	v_add_u32_e32 v177, v174, v142
	v_add_u32_e32 v190, v174, v143
	ds_read_b128 v[178:181], v176 offset:640
	ds_read_b128 v[182:185], v176 offset:704
	ds_read_b128 v[186:189], v177
	ds_read_b128 v[190:193], v190
	v_add_u32_e32 v177, v175, v142
	v_add_u32_e32 v198, v175, v143
	ds_read_b128 v[194:197], v177
	ds_read_b128 v[198:201], v198
	s_waitcnt lgkmcnt(0)
	v_pk_mul_f32 v[32:33], v[32:33], v[72:73]
	v_pk_mul_f32 v[34:35], v[34:35], v[74:75]
	v_pk_mul_f32 v[36:37], v[36:37], v[76:77]
	v_pk_mul_f32 v[38:39], v[38:39], v[78:79]
	v_mfma_f32_16x16x32_bf16 v[32:35], v[80:83], v[68:71], v[32:35]
	s_nop 0
	v_mfma_f32_16x16x32_bf16 v[36:39], v[124:127], v[68:71], v[36:39]
	v_mfma_f32_16x16x32_bf16 v[32:35], v[84:87], v[64:67], v[32:35]
	v_mfma_f32_16x16x32_bf16 v[36:39], v[128:131], v[64:67], v[36:39]
	ds_read_b128 v[72:75], v176 offset:768
	ds_read_b128 v[76:79], v176 offset:832
	ds_read_b128 v[80:83], v132 offset:8192
	ds_read_b128 v[84:87], v132 offset:10240
	ds_read_b128 v[124:127], v133 offset:8192
	ds_read_b128 v[128:131], v133 offset:10240
	v_pk_mul_f32 v[40:41], v[40:41], v[178:179]
	v_pk_mul_f32 v[42:43], v[42:43], v[180:181]
	v_pk_mul_f32 v[44:45], v[44:45], v[182:183]
	v_pk_mul_f32 v[46:47], v[46:47], v[184:185]
	v_mfma_f32_16x16x32_bf16 v[40:43], v[186:189], v[68:71], v[40:43]
	s_nop 0
	v_mfma_f32_16x16x32_bf16 v[44:47], v[194:197], v[68:71], v[44:47]
	v_mfma_f32_16x16x32_bf16 v[40:43], v[190:193], v[64:67], v[40:43]
	v_mfma_f32_16x16x32_bf16 v[44:47], v[198:201], v[64:67], v[44:47]
	ds_read_b128 v[178:181], v176 offset:896
	ds_read_b128 v[182:185], v176 offset:960
	ds_read_b128 v[186:189], v132 offset:12288
	ds_read_b128 v[190:193], v132 offset:14336
	ds_read_b128 v[194:197], v133 offset:12288
	ds_read_b128 v[198:201], v133 offset:14336
	s_waitcnt lgkmcnt(0)
	v_pk_mul_f32 v[48:49], v[48:49], v[72:73]
	v_pk_mul_f32 v[50:51], v[50:51], v[74:75]
	v_pk_mul_f32 v[52:53], v[52:53], v[76:77]
	v_pk_mul_f32 v[54:55], v[54:55], v[78:79]
	v_mfma_f32_16x16x32_bf16 v[48:51], v[80:83], v[68:71], v[48:51]
	s_nop 0
	v_mfma_f32_16x16x32_bf16 v[52:55], v[84:87], v[68:71], v[52:55]
	v_mfma_f32_16x16x32_bf16 v[48:51], v[124:127], v[64:67], v[48:51]
	v_mfma_f32_16x16x32_bf16 v[52:55], v[128:131], v[64:67], v[52:55]
	v_mul_f32_e64 v56, v56, v178
	v_mul_f32_e64 v57, v57, v179
	v_pk_mul_f32 v[58:59], v[58:59], v[180:181]
	v_pk_mul_f32 v[60:61], v[60:61], v[182:183]
	v_pk_mul_f32 v[62:63], v[62:63], v[184:185]
	v_mfma_f32_16x16x32_bf16 v[56:59], v[186:189], v[68:71], v[56:59]
	s_nop 0
	v_mfma_f32_16x16x32_bf16 v[60:63], v[190:193], v[68:71], v[60:63]
	v_mfma_f32_16x16x32_bf16 v[56:59], v[194:197], v[64:67], v[56:59]
	v_mfma_f32_16x16x32_bf16 v[60:63], v[198:201], v[64:67], v[60:63]
	v_xor_b32_e32 v176, 0x3000, v176
	s_add_i32 s38, s38, -8
	s_add_i32 s40, s40, -8
	s_add_i32 s88, s88, -1
	s_cmp_eq_u32 s0, s82
	s_cbranch_scc1 .LBB0_680
	s_mov_b32 s1, s0
	s_cmp_lg_u32 s1, s97
	s_mov_b64 s[44:45], -1
	s_cbranch_scc1 .LBB0_682
	s_branch .LBB0_683

; #define LAS __attribute__((address_space(3)))
; __global__ void __launch_bounds__(512) fwd_megakernel(Params p) {
;     extern __shared__ __attribute__((aligned(16))) unsigned char shm[];
;     cg::grid_group grid = cg::this_grid();
;     LAS unsigned char* lds = (LAS unsigned char*)shm;
	.amdhsa_kernel _Z14fwd_megakernel6Params
		.amdhsa_group_segment_fixed_size 4096
		.amdhsa_private_segment_fixed_size 0
		.amdhsa_kernarg_size 400
		.amdhsa_user_sgpr_count 2
		.amdhsa_user_sgpr_dispatch_ptr 0
		.amdhsa_user_sgpr_queue_ptr 0
		.amdhsa_user_sgpr_kernarg_segment_ptr 1
		.amdhsa_user_sgpr_dispatch_id 0
		.amdhsa_user_sgpr_kernarg_preload_length 0
		.amdhsa_user_sgpr_kernarg_preload_offset 0
		.amdhsa_user_sgpr_private_segment_size 0
		.amdhsa_uses_dynamic_stack 0
		.amdhsa_enable_private_segment 0
		.amdhsa_system_sgpr_workgroup_id_x 1
		.amdhsa_system_sgpr_workgroup_id_y 0
		.amdhsa_system_sgpr_workgroup_id_z 0
		.amdhsa_system_sgpr_workgroup_info 0
		.amdhsa_system_vgpr_workitem_id 2
		.amdhsa_next_free_vgpr 256
		.amdhsa_next_free_sgpr 102
		.amdhsa_accum_offset 256
		.amdhsa_reserve_vcc 1
		.amdhsa_float_round_mode_32 0
		.amdhsa_float_round_mode_16_64 0
		.amdhsa_float_denorm_mode_32 3
		.amdhsa_float_denorm_mode_16_64 3
		.amdhsa_dx10_clamp 1
		.amdhsa_ieee_mode 1
		.amdhsa_fp16_overflow 0
		.amdhsa_tg_split 0
		.amdhsa_exception_fp_ieee_invalid_op 0
		.amdhsa_exception_fp_denorm_src 0
		.amdhsa_exception_fp_ieee_div_zero 0
		.amdhsa_exception_fp_ieee_overflow 0
		.amdhsa_exception_fp_ieee_underflow 0
		.amdhsa_exception_fp_ieee_inexact 0
		.amdhsa_exception_int_div_zero 0
	.end_amdhsa_kernel

; #define LAS __attribute__((address_space(3)))
; __global__ void __launch_bounds__(512) fwd_megakernel(Params p) {
;     extern __shared__ __attribute__((aligned(16))) unsigned char shm[];
;     cg::grid_group grid = cg::this_grid();
;     LAS unsigned char* lds = (LAS unsigned char*)shm;
amdhsa.kernels:
  - .agpr_count:     0
    .args:
      - .offset:         0
        .size:           144
        .value_kind:     by_value
      - .offset:         144
        .size:           4
        .value_kind:     hidden_block_count_x
      - .offset:         148
        .size:           4
        .value_kind:     hidden_block_count_y
      - .offset:         152
        .size:           4
        .value_kind:     hidden_block_count_z
      - .offset:         156
        .size:           2
        .value_kind:     hidden_group_size_x
      - .offset:         158
        .size:           2
        .value_kind:     hidden_group_size_y
      - .offset:         160
        .size:           2
        .value_kind:     hidden_group_size_z
      - .offset:         162
        .size:           2
        .value_kind:     hidden_remainder_x
      - .offset:         164
        .size:           2
        .value_kind:     hidden_remainder_y
      - .offset:         166
        .size:           2
        .value_kind:     hidden_remainder_z
      - .offset:         184
        .size:           8
        .value_kind:     hidden_global_offset_x
      - .offset:         192
        .size:           8
        .value_kind:     hidden_global_offset_y
      - .offset:         200
        .size:           8
        .value_kind:     hidden_global_offset_z
      - .offset:         208
        .size:           2
        .value_kind:     hidden_grid_dims
      - .offset:         232
        .size:           8
        .value_kind:     hidden_multigrid_sync_arg
      - .offset:         264
        .size:           4
        .value_kind:     hidden_dynamic_lds_size
    .group_segment_fixed_size: 4096
    .kernarg_segment_align: 8
    .kernarg_segment_size: 400
    .language:       OpenCL C
    .language_version:
      - 2
      - 0
    .max_flat_workgroup_size: 512
    .name:           _Z14fwd_megakernel6Params
    .private_segment_fixed_size: 0
    .sgpr_count:     108
    .sgpr_spill_count: 10
    .symbol:         _Z14fwd_megakernel6Params.kd
    .uniform_work_group_size: 1
    .uses_dynamic_stack: false
    .vgpr_count:     256
    .vgpr_spill_count: 0
    .wavefront_size: 64
